# snake+noscale, plus s_setprio 1 hoisted above the pre-MFMA s_barrier and the redundant post-barrier lgkmcnt(0) removed
# baseline (speedup 1.0000x reference)
.LBB0_197:
	s_ashr_i32 s47, s46, 31
	ds_read_b128 v[18:21], v190
	ds_read_b128 v[22:25], v190 offset:1024
	ds_read_b128 v[26:29], v190 offset:2048
	ds_read_b128 v[30:33], v190 offset:3072
	ds_read_b128 v[2:5], v190 offset:16384
	ds_read_b128 v[6:9], v190 offset:17408
	ds_read_b128 v[10:13], v190 offset:18432
	ds_read_b128 v[14:17], v190 offset:19456
	s_lshl_b64 s[8:9], s[46:47], 20
	s_add_u32 s48, s22, s8
	s_addc_u32 s49, s23, s9
	s_and_b64 s[8:9], s[2:3], exec
	s_cselect_b32 s47, s49, s73
	s_cselect_b32 s70, s48, s72
	s_ashr_i32 s45, s44, 31
	s_lshl_b64 s[8:9], s[44:45], 20
	s_add_u32 s50, s27, s8
	s_addc_u32 s51, s68, s9
	s_and_b64 s[8:9], s[2:3], exec
	s_cselect_b32 s45, s51, s55
	s_cselect_b32 s71, s50, s54
	s_add_u32 s8, s72, 0x80080
	s_addc_u32 s9, s73, 0
	s_mov_b32 m0, s92
	v_lshl_add_u64 v[216:217], s[8:9], 0, v[164:165]
	ds_read_b128 v[180:183], v191
	ds_read_b128 v[184:187], v191 offset:1024
	ds_read_b128 v[192:195], v191 offset:2048
	ds_read_b128 v[196:199], v191 offset:3072
	ds_read_b128 v[200:203], v191 offset:4096
	ds_read_b128 v[204:207], v191 offset:5120
	ds_read_b128 v[208:211], v191 offset:6144
	ds_read_b128 v[212:215], v191 offset:7168
	global_load_lds_dwordx4 v[216:217], off
	v_lshl_add_u64 v[216:217], s[8:9], 0, v[168:169]
	s_mov_b32 m0, s93
	s_nop 0
	global_load_lds_dwordx4 v[216:217], off
	s_waitcnt vmcnt(8)
	s_waitcnt lgkmcnt(0)
	s_setprio 1
	s_barrier
	v_mfma_f32_16x16x128_f8f6f4 v[158:161], v[18:25], v[180:187], 0
	v_mfma_f32_16x16x128_f8f6f4 v[154:157], v[26:33], v[180:187], 0
	v_mfma_f32_16x16x128_f8f6f4 v[146:149], v[26:33], v[192:199], 0
	v_mfma_f32_16x16x128_f8f6f4 v[150:153], v[18:25], v[192:199], 0
	v_mfma_f32_16x16x128_f8f6f4 v[142:145], v[18:25], v[200:207], 0
	v_mfma_f32_16x16x128_f8f6f4 v[138:141], v[26:33], v[200:207], 0
	v_mfma_f32_16x16x128_f8f6f4 v[130:133], v[26:33], v[208:215], 0
	v_mfma_f32_16x16x128_f8f6f4 v[134:137], v[18:25], v[208:215], 0
	s_setprio 0
	s_setprio 1
	v_mfma_f32_16x16x128_f8f6f4 v[102:105], v[2:9], v[208:215], 0
	v_mfma_f32_16x16x128_f8f6f4 v[98:101], v[10:17], v[208:215], 0
	v_mfma_f32_16x16x128_f8f6f4 v[106:109], v[10:17], v[200:207], 0
	v_mfma_f32_16x16x128_f8f6f4 v[110:113], v[2:9], v[200:207], 0
	v_mfma_f32_16x16x128_f8f6f4 v[118:121], v[2:9], v[192:199], 0
	v_mfma_f32_16x16x128_f8f6f4 v[114:117], v[10:17], v[192:199], 0
	v_mfma_f32_16x16x128_f8f6f4 v[122:125], v[10:17], v[180:187], 0
	v_mfma_f32_16x16x128_f8f6f4 v[126:129], v[2:9], v[180:187], 0
	s_setprio 0
	s_barrier
	v_lshl_add_u64 v[180:181], s[54:55], 0, v[166:167]
	s_mov_b32 m0, s77
	v_lshl_add_u64 v[182:183], v[180:181], 0, s[16:17]
	ds_read_b128 v[192:195], v191 offset:16384
	ds_read_b128 v[196:199], v191 offset:17408
	ds_read_b128 v[200:203], v191 offset:18432
	ds_read_b128 v[204:207], v191 offset:19456
	ds_read_b128 v[208:211], v191 offset:20480
	ds_read_b128 v[212:215], v191 offset:21504
	ds_read_b128 v[216:219], v191 offset:22528
	ds_read_b128 v[220:223], v191 offset:23552
	global_load_lds_dwordx4 v[182:183], off
	v_lshl_add_u64 v[182:183], s[54:55], 0, v[170:171]
	s_add_u32 s8, s54, 0x80100
	v_lshl_add_u64 v[184:185], v[182:183], 0, s[16:17]
	s_mov_b32 m0, s78
	s_addc_u32 s9, s55, 0
	global_load_lds_dwordx4 v[184:185], off
	v_lshl_add_u64 v[184:185], s[8:9], 0, v[166:167]
	s_mov_b32 m0, s79
	s_nop 0
	global_load_lds_dwordx4 v[184:185], off
	v_lshl_add_u64 v[184:185], s[8:9], 0, v[170:171]
	s_mov_b32 m0, s80
	s_nop 0
	global_load_lds_dwordx4 v[184:185], off
	v_lshl_add_u64 v[184:185], s[72:73], 0, v[164:165]
	v_lshl_add_u64 v[186:187], v[184:185], 0, s[16:17]
	s_mov_b32 m0, s53
	s_nop 0
	global_load_lds_dwordx4 v[186:187], off
	v_lshl_add_u64 v[186:187], s[72:73], 0, v[168:169]
	v_lshl_add_u64 v[224:225], v[186:187], 0, s[16:17]
	s_mov_b32 m0, s81
	s_nop 0
	global_load_lds_dwordx4 v[224:225], off
	s_waitcnt vmcnt(8)
	s_waitcnt lgkmcnt(0)
	s_setprio 1
	s_barrier
	v_mfma_f32_16x16x128_f8f6f4 v[94:97], v[18:25], v[192:199], 0
	v_mfma_f32_16x16x128_f8f6f4 v[90:93], v[26:33], v[192:199], 0
	v_mfma_f32_16x16x128_f8f6f4 v[82:85], v[26:33], v[200:207], 0
	v_mfma_f32_16x16x128_f8f6f4 v[86:89], v[18:25], v[200:207], 0
	v_mfma_f32_16x16x128_f8f6f4 v[78:81], v[18:25], v[208:215], 0
	v_mfma_f32_16x16x128_f8f6f4 v[74:77], v[26:33], v[208:215], 0
	v_mfma_f32_16x16x128_f8f6f4 v[66:69], v[26:33], v[216:223], 0
	v_mfma_f32_16x16x128_f8f6f4 v[70:73], v[18:25], v[216:223], 0
	s_setprio 0
	s_setprio 1
	v_mfma_f32_16x16x128_f8f6f4 v[38:41], v[2:9], v[216:223], 0
	v_mfma_f32_16x16x128_f8f6f4 v[34:37], v[10:17], v[216:223], 0
	v_mfma_f32_16x16x128_f8f6f4 v[42:45], v[10:17], v[208:215], 0
	v_mfma_f32_16x16x128_f8f6f4 v[46:49], v[2:9], v[208:215], 0
	v_mfma_f32_16x16x128_f8f6f4 v[54:57], v[2:9], v[200:207], 0
	v_mfma_f32_16x16x128_f8f6f4 v[50:53], v[10:17], v[200:207], 0
	v_mfma_f32_16x16x128_f8f6f4 v[58:61], v[10:17], v[192:199], 0
	v_mfma_f32_16x16x128_f8f6f4 v[62:65], v[2:9], v[192:199], 0
	s_setprio 0
	s_barrier
	ds_read_b128 v[18:21], v190 offset:32768
	ds_read_b128 v[22:25], v190 offset:33792
	ds_read_b128 v[26:29], v190 offset:34816
	ds_read_b128 v[30:33], v190 offset:35840
	ds_read_b128 v[2:5], v190 offset:49152
	ds_read_b128 v[6:9], v190 offset:50176
	ds_read_b128 v[10:13], v190 offset:51200
	ds_read_b128 v[14:17], v190 offset:52224
	s_add_u32 s8, s72, 0x80100
	s_addc_u32 s9, s73, 0
	s_mov_b32 m0, s82
	v_lshl_add_u64 v[224:225], s[8:9], 0, v[164:165]
	ds_read_b128 v[192:195], v191 offset:32768
	ds_read_b128 v[196:199], v191 offset:33792
	ds_read_b128 v[200:203], v191 offset:34816
	ds_read_b128 v[204:207], v191 offset:35840
	ds_read_b128 v[208:211], v191 offset:36864
	ds_read_b128 v[212:215], v191 offset:37888
	ds_read_b128 v[216:219], v191 offset:38912
	ds_read_b128 v[220:223], v191 offset:39936
	global_load_lds_dwordx4 v[224:225], off
	v_lshl_add_u64 v[224:225], s[8:9], 0, v[168:169]
	s_mov_b32 m0, s83
	s_nop 0
	global_load_lds_dwordx4 v[224:225], off
	s_waitcnt vmcnt(8)
	s_waitcnt lgkmcnt(0)
	s_setprio 1
	s_barrier
	v_mfma_f32_16x16x128_f8f6f4 v[158:161], v[18:25], v[192:199], v[158:161]
	v_mfma_f32_16x16x128_f8f6f4 v[154:157], v[26:33], v[192:199], v[154:157]
	v_mfma_f32_16x16x128_f8f6f4 v[146:149], v[26:33], v[200:207], v[146:149]
	v_mfma_f32_16x16x128_f8f6f4 v[150:153], v[18:25], v[200:207], v[150:153]
	v_mfma_f32_16x16x128_f8f6f4 v[142:145], v[18:25], v[208:215], v[142:145]
	v_mfma_f32_16x16x128_f8f6f4 v[138:141], v[26:33], v[208:215], v[138:141]
	v_mfma_f32_16x16x128_f8f6f4 v[130:133], v[26:33], v[216:223], v[130:133]
	v_mfma_f32_16x16x128_f8f6f4 v[134:137], v[18:25], v[216:223], v[134:137]
	s_setprio 0
	s_setprio 1
	v_mfma_f32_16x16x128_f8f6f4 v[102:105], v[2:9], v[216:223], v[102:105]
	v_mfma_f32_16x16x128_f8f6f4 v[98:101], v[10:17], v[216:223], v[98:101]
	v_mfma_f32_16x16x128_f8f6f4 v[106:109], v[10:17], v[208:215], v[106:109]
	v_mfma_f32_16x16x128_f8f6f4 v[110:113], v[2:9], v[208:215], v[110:113]
	v_mfma_f32_16x16x128_f8f6f4 v[118:121], v[2:9], v[200:207], v[118:121]
	v_mfma_f32_16x16x128_f8f6f4 v[114:117], v[10:17], v[200:207], v[114:117]
	v_mfma_f32_16x16x128_f8f6f4 v[122:125], v[10:17], v[192:199], v[122:125]
	v_mfma_f32_16x16x128_f8f6f4 v[126:129], v[2:9], v[192:199], v[126:129]
	s_setprio 0
	s_barrier
	s_mov_b32 m0, s86
	v_lshl_add_u64 v[180:181], v[180:181], 0, s[20:21]
	s_add_u32 s8, s54, 0x80180
	ds_read_b128 v[192:195], v191 offset:49152
	ds_read_b128 v[196:199], v191 offset:50176
	ds_read_b128 v[200:203], v191 offset:51200
	ds_read_b128 v[204:207], v191 offset:52224
	ds_read_b128 v[208:211], v191 offset:53248
	ds_read_b128 v[212:215], v191 offset:54272
	ds_read_b128 v[216:219], v191 offset:55296
	ds_read_b128 v[220:223], v191 offset:56320
	global_load_lds_dwordx4 v[180:181], off
	v_lshl_add_u64 v[180:181], v[182:183], 0, s[20:21]
	s_mov_b32 m0, s87
	s_addc_u32 s9, s55, 0
	global_load_lds_dwordx4 v[180:181], off
	v_lshl_add_u64 v[180:181], s[8:9], 0, v[166:167]
	s_mov_b32 m0, s90
	s_nop 0
	global_load_lds_dwordx4 v[180:181], off
	v_lshl_add_u64 v[180:181], s[8:9], 0, v[170:171]
	s_mov_b32 m0, s91
	s_nop 0
	global_load_lds_dwordx4 v[180:181], off
	v_lshl_add_u64 v[180:181], v[184:185], 0, s[20:21]
	s_mov_b32 m0, s88
	s_nop 0
	global_load_lds_dwordx4 v[180:181], off
	v_lshl_add_u64 v[180:181], v[186:187], 0, s[20:21]
	s_mov_b32 m0, s89
	s_nop 0
	global_load_lds_dwordx4 v[180:181], off
	s_waitcnt vmcnt(8)
	s_waitcnt lgkmcnt(0)
	s_setprio 1
	s_barrier
	v_mfma_f32_16x16x128_f8f6f4 v[94:97], v[18:25], v[192:199], v[94:97]
	v_mfma_f32_16x16x128_f8f6f4 v[90:93], v[26:33], v[192:199], v[90:93]
	v_mfma_f32_16x16x128_f8f6f4 v[82:85], v[26:33], v[200:207], v[82:85]
	v_mfma_f32_16x16x128_f8f6f4 v[86:89], v[18:25], v[200:207], v[86:89]
	v_mfma_f32_16x16x128_f8f6f4 v[78:81], v[18:25], v[208:215], v[78:81]
	v_mfma_f32_16x16x128_f8f6f4 v[74:77], v[26:33], v[208:215], v[74:77]
	v_mfma_f32_16x16x128_f8f6f4 v[66:69], v[26:33], v[216:223], v[66:69]
	v_mfma_f32_16x16x128_f8f6f4 v[70:73], v[18:25], v[216:223], v[70:73]
	s_setprio 0
	s_setprio 1
	v_mfma_f32_16x16x128_f8f6f4 v[38:41], v[2:9], v[216:223], v[38:41]
	v_mfma_f32_16x16x128_f8f6f4 v[34:37], v[10:17], v[216:223], v[34:37]
	v_mfma_f32_16x16x128_f8f6f4 v[42:45], v[10:17], v[208:215], v[42:45]
	v_mfma_f32_16x16x128_f8f6f4 v[46:49], v[2:9], v[208:215], v[46:49]
	v_mfma_f32_16x16x128_f8f6f4 v[54:57], v[2:9], v[200:207], v[54:57]
	v_mfma_f32_16x16x128_f8f6f4 v[50:53], v[10:17], v[200:207], v[50:53]
	v_mfma_f32_16x16x128_f8f6f4 v[58:61], v[10:17], v[192:199], v[58:61]
	v_mfma_f32_16x16x128_f8f6f4 v[62:65], v[2:9], v[192:199], v[62:65]
	s_setprio 0
	s_barrier
	s_add_u32 s72, s72, 0x80180
	s_addc_u32 s73, s73, 0
	s_add_u32 s8, s54, 0x200
	s_addc_u32 s9, s55, 0
	s_mov_b32 s62, 0
.LBB0_198:
	ds_read_b128 v[2:5], v190
	ds_read_b128 v[6:9], v190 offset:1024
	ds_read_b128 v[18:21], v190 offset:2048
	ds_read_b128 v[22:25], v190 offset:3072
	ds_read_b128 v[26:29], v190 offset:16384
	ds_read_b128 v[30:33], v190 offset:17408
	ds_read_b128 v[180:183], v190 offset:18432
	ds_read_b128 v[184:187], v190 offset:19456
	s_add_u32 s54, s72, 0xfff80080
	s_addc_u32 s55, s73, -1
	s_cmp_eq_u32 s62, 28
	s_cselect_b32 s75, s47, s55
	s_cselect_b32 s74, s70, s54
	s_cselect_b32 s55, s45, s9
	s_cselect_b32 s54, s71, s8
	s_mov_b32 m0, s92
	v_lshl_add_u64 v[216:217], s[72:73], 0, v[172:173]
	ds_read_b128 v[10:13], v191
	ds_read_b128 v[14:17], v191 offset:1024
	ds_read_b128 v[192:195], v191 offset:2048
	ds_read_b128 v[196:199], v191 offset:3072
	ds_read_b128 v[200:203], v191 offset:4096
	ds_read_b128 v[204:207], v191 offset:5120
	ds_read_b128 v[208:211], v191 offset:6144
	ds_read_b128 v[212:215], v191 offset:7168
	global_load_lds_dwordx4 v[216:217], off
	v_lshl_add_u64 v[216:217], s[72:73], 0, v[174:175]
	s_mov_b32 m0, s93
	s_nop 0
	global_load_lds_dwordx4 v[216:217], off
	s_waitcnt vmcnt(8)
	s_waitcnt lgkmcnt(0)
	s_setprio 1
	s_barrier
	v_mfma_f32_16x16x128_f8f6f4 v[158:161], v[2:9], v[10:17], v[158:161]
	v_mfma_f32_16x16x128_f8f6f4 v[154:157], v[18:25], v[10:17], v[154:157]
	v_mfma_f32_16x16x128_f8f6f4 v[146:149], v[18:25], v[192:199], v[146:149]
	v_mfma_f32_16x16x128_f8f6f4 v[150:153], v[2:9], v[192:199], v[150:153]
	v_mfma_f32_16x16x128_f8f6f4 v[142:145], v[2:9], v[200:207], v[142:145]
	v_mfma_f32_16x16x128_f8f6f4 v[138:141], v[18:25], v[200:207], v[138:141]
	v_mfma_f32_16x16x128_f8f6f4 v[130:133], v[18:25], v[208:215], v[130:133]
	v_mfma_f32_16x16x128_f8f6f4 v[134:137], v[2:9], v[208:215], v[134:137]
	s_setprio 0
	s_setprio 1
	v_mfma_f32_16x16x128_f8f6f4 v[102:105], v[26:33], v[208:215], v[102:105]
	v_mfma_f32_16x16x128_f8f6f4 v[98:101], v[180:187], v[208:215], v[98:101]
	v_mfma_f32_16x16x128_f8f6f4 v[106:109], v[180:187], v[200:207], v[106:109]
	v_mfma_f32_16x16x128_f8f6f4 v[110:113], v[26:33], v[200:207], v[110:113]
	v_mfma_f32_16x16x128_f8f6f4 v[118:121], v[26:33], v[192:199], v[118:121]
	v_mfma_f32_16x16x128_f8f6f4 v[114:117], v[180:187], v[192:199], v[114:117]
	v_mfma_f32_16x16x128_f8f6f4 v[122:125], v[180:187], v[10:17], v[122:125]
	v_mfma_f32_16x16x128_f8f6f4 v[126:129], v[26:33], v[10:17], v[126:129]
	s_setprio 0
	s_barrier
	s_mov_b32 m0, s77
	v_lshl_add_u64 v[10:11], s[54:55], 0, v[166:167]
	s_add_u32 vcc_lo, s54, 0x80000
	ds_read_b128 v[192:195], v191 offset:16384
	ds_read_b128 v[196:199], v191 offset:17408
	ds_read_b128 v[200:203], v191 offset:18432
	ds_read_b128 v[204:207], v191 offset:19456
	ds_read_b128 v[208:211], v191 offset:20480
	ds_read_b128 v[212:215], v191 offset:21504
	ds_read_b128 v[216:219], v191 offset:22528
	ds_read_b128 v[220:223], v191 offset:23552
	global_load_lds_dwordx4 v[10:11], off
	v_lshl_add_u64 v[12:13], s[54:55], 0, v[170:171]
	s_mov_b32 m0, s78
	s_addc_u32 vcc_hi, s55, 0
	global_load_lds_dwordx4 v[12:13], off
	v_lshl_add_u64 v[14:15], vcc, 0, v[166:167]
	s_mov_b32 m0, s79
	v_lshl_add_u64 v[16:17], s[74:75], 0, v[168:169]
	global_load_lds_dwordx4 v[14:15], off
	v_lshl_add_u64 v[14:15], vcc, 0, v[170:171]
	s_mov_b32 m0, s80
	s_nop 0
	global_load_lds_dwordx4 v[14:15], off
	v_lshl_add_u64 v[14:15], s[74:75], 0, v[164:165]
	s_mov_b32 m0, s53
	s_nop 0
	global_load_lds_dwordx4 v[14:15], off
	s_mov_b32 m0, s81
	s_nop 0
	global_load_lds_dwordx4 v[16:17], off
	s_waitcnt vmcnt(8)
	s_waitcnt lgkmcnt(0)
	s_setprio 1
	s_barrier
	v_mfma_f32_16x16x128_f8f6f4 v[94:97], v[2:9], v[192:199], v[94:97]
	v_mfma_f32_16x16x128_f8f6f4 v[90:93], v[18:25], v[192:199], v[90:93]
	v_mfma_f32_16x16x128_f8f6f4 v[82:85], v[18:25], v[200:207], v[82:85]
	v_mfma_f32_16x16x128_f8f6f4 v[86:89], v[2:9], v[200:207], v[86:89]
	v_mfma_f32_16x16x128_f8f6f4 v[78:81], v[2:9], v[208:215], v[78:81]
	v_mfma_f32_16x16x128_f8f6f4 v[74:77], v[18:25], v[208:215], v[74:77]
	v_mfma_f32_16x16x128_f8f6f4 v[66:69], v[18:25], v[216:223], v[66:69]
	v_mfma_f32_16x16x128_f8f6f4 v[70:73], v[2:9], v[216:223], v[70:73]
	s_setprio 0
	s_setprio 1
	v_mfma_f32_16x16x128_f8f6f4 v[38:41], v[26:33], v[216:223], v[38:41]
	v_mfma_f32_16x16x128_f8f6f4 v[34:37], v[180:187], v[216:223], v[34:37]
	v_mfma_f32_16x16x128_f8f6f4 v[42:45], v[180:187], v[208:215], v[42:45]
	v_mfma_f32_16x16x128_f8f6f4 v[46:49], v[26:33], v[208:215], v[46:49]
	v_mfma_f32_16x16x128_f8f6f4 v[54:57], v[26:33], v[200:207], v[54:57]
	v_mfma_f32_16x16x128_f8f6f4 v[50:53], v[180:187], v[200:207], v[50:53]
	v_mfma_f32_16x16x128_f8f6f4 v[58:61], v[180:187], v[192:199], v[58:61]
	v_mfma_f32_16x16x128_f8f6f4 v[62:65], v[26:33], v[192:199], v[62:65]
	s_setprio 0
	s_barrier
	ds_read_b128 v[18:21], v190 offset:32768
	ds_read_b128 v[22:25], v190 offset:33792
	ds_read_b128 v[26:29], v190 offset:34816
	ds_read_b128 v[30:33], v190 offset:35840
	ds_read_b128 v[2:5], v190 offset:49152
	ds_read_b128 v[6:9], v190 offset:50176
	ds_read_b128 v[180:183], v190 offset:51200
	ds_read_b128 v[184:187], v190 offset:52224
	s_add_u32 s74, s74, 0x80000
	s_addc_u32 s75, s75, 0
	s_mov_b32 m0, s82
	v_lshl_add_u64 v[224:225], s[74:75], 0, v[164:165]
	ds_read_b128 v[192:195], v191 offset:32768
	ds_read_b128 v[196:199], v191 offset:33792
	ds_read_b128 v[200:203], v191 offset:34816
	ds_read_b128 v[204:207], v191 offset:35840
	ds_read_b128 v[208:211], v191 offset:36864
	ds_read_b128 v[212:215], v191 offset:37888
	ds_read_b128 v[216:219], v191 offset:38912
	ds_read_b128 v[220:223], v191 offset:39936
	global_load_lds_dwordx4 v[224:225], off
	v_lshl_add_u64 v[224:225], s[74:75], 0, v[168:169]
	s_mov_b32 m0, s83
	s_nop 0
	global_load_lds_dwordx4 v[224:225], off
	s_waitcnt vmcnt(8)
	s_waitcnt lgkmcnt(0)
	s_setprio 1
	s_barrier
	v_mfma_f32_16x16x128_f8f6f4 v[158:161], v[18:25], v[192:199], v[158:161]
	v_mfma_f32_16x16x128_f8f6f4 v[154:157], v[26:33], v[192:199], v[154:157]
	v_mfma_f32_16x16x128_f8f6f4 v[146:149], v[26:33], v[200:207], v[146:149]
	v_mfma_f32_16x16x128_f8f6f4 v[150:153], v[18:25], v[200:207], v[150:153]
	v_mfma_f32_16x16x128_f8f6f4 v[142:145], v[18:25], v[208:215], v[142:145]
	v_mfma_f32_16x16x128_f8f6f4 v[138:141], v[26:33], v[208:215], v[138:141]
	v_mfma_f32_16x16x128_f8f6f4 v[130:133], v[26:33], v[216:223], v[130:133]
	v_mfma_f32_16x16x128_f8f6f4 v[134:137], v[18:25], v[216:223], v[134:137]
	s_setprio 0
	s_setprio 1
	v_mfma_f32_16x16x128_f8f6f4 v[102:105], v[2:9], v[216:223], v[102:105]
	v_mfma_f32_16x16x128_f8f6f4 v[98:101], v[180:187], v[216:223], v[98:101]
	v_mfma_f32_16x16x128_f8f6f4 v[106:109], v[180:187], v[208:215], v[106:109]
	v_mfma_f32_16x16x128_f8f6f4 v[110:113], v[2:9], v[208:215], v[110:113]
	v_mfma_f32_16x16x128_f8f6f4 v[118:121], v[2:9], v[200:207], v[118:121]
	v_mfma_f32_16x16x128_f8f6f4 v[114:117], v[180:187], v[200:207], v[114:117]
	v_mfma_f32_16x16x128_f8f6f4 v[122:125], v[180:187], v[192:199], v[122:125]
	v_mfma_f32_16x16x128_f8f6f4 v[126:129], v[2:9], v[192:199], v[126:129]
	s_setprio 0
	s_barrier
	s_mov_b32 m0, s86
	v_lshl_add_u64 v[10:11], v[10:11], 0, s[4:5]
	s_add_u32 s54, s54, 0x80080
	ds_read_b128 v[192:195], v191 offset:49152
	ds_read_b128 v[196:199], v191 offset:50176
	ds_read_b128 v[200:203], v191 offset:51200
	ds_read_b128 v[204:207], v191 offset:52224
	ds_read_b128 v[208:211], v191 offset:53248
	ds_read_b128 v[212:215], v191 offset:54272
	ds_read_b128 v[216:219], v191 offset:55296
	ds_read_b128 v[220:223], v191 offset:56320
	global_load_lds_dwordx4 v[10:11], off
	v_lshl_add_u64 v[10:11], v[12:13], 0, s[4:5]
	s_mov_b32 m0, s87
	s_addc_u32 s55, s55, 0
	global_load_lds_dwordx4 v[10:11], off
	v_lshl_add_u64 v[10:11], s[54:55], 0, v[166:167]
	s_mov_b32 m0, s90
	s_nop 0
	global_load_lds_dwordx4 v[10:11], off
	v_lshl_add_u64 v[10:11], s[54:55], 0, v[170:171]
	s_mov_b32 m0, s91
	s_nop 0
	global_load_lds_dwordx4 v[10:11], off
	v_lshl_add_u64 v[10:11], v[14:15], 0, s[4:5]
	s_mov_b32 m0, s88
	s_nop 0
	global_load_lds_dwordx4 v[10:11], off
	v_lshl_add_u64 v[10:11], v[16:17], 0, s[4:5]
	s_mov_b32 m0, s89
	s_nop 0
	global_load_lds_dwordx4 v[10:11], off
	s_waitcnt vmcnt(8)
	s_waitcnt lgkmcnt(0)
	s_setprio 1
	s_barrier
	v_mfma_f32_16x16x128_f8f6f4 v[94:97], v[18:25], v[192:199], v[94:97]
	v_mfma_f32_16x16x128_f8f6f4 v[90:93], v[26:33], v[192:199], v[90:93]
	v_mfma_f32_16x16x128_f8f6f4 v[82:85], v[26:33], v[200:207], v[82:85]
	v_mfma_f32_16x16x128_f8f6f4 v[86:89], v[18:25], v[200:207], v[86:89]
	v_mfma_f32_16x16x128_f8f6f4 v[78:81], v[18:25], v[208:215], v[78:81]
	v_mfma_f32_16x16x128_f8f6f4 v[74:77], v[26:33], v[208:215], v[74:77]
	v_mfma_f32_16x16x128_f8f6f4 v[66:69], v[26:33], v[216:223], v[66:69]
	v_mfma_f32_16x16x128_f8f6f4 v[70:73], v[18:25], v[216:223], v[70:73]
	s_setprio 0
	s_setprio 1
	v_mfma_f32_16x16x128_f8f6f4 v[38:41], v[2:9], v[216:223], v[38:41]
	v_mfma_f32_16x16x128_f8f6f4 v[34:37], v[180:187], v[216:223], v[34:37]
	v_mfma_f32_16x16x128_f8f6f4 v[42:45], v[180:187], v[208:215], v[42:45]
	v_mfma_f32_16x16x128_f8f6f4 v[46:49], v[2:9], v[208:215], v[46:49]
	v_mfma_f32_16x16x128_f8f6f4 v[54:57], v[2:9], v[200:207], v[54:57]
	v_mfma_f32_16x16x128_f8f6f4 v[50:53], v[180:187], v[200:207], v[50:53]
	v_mfma_f32_16x16x128_f8f6f4 v[58:61], v[180:187], v[192:199], v[58:61]
	v_mfma_f32_16x16x128_f8f6f4 v[62:65], v[2:9], v[192:199], v[62:65]
	s_setprio 0
	s_barrier
	s_add_i32 s62, s62, 2
	s_add_u32 s72, s72, 0x100
	s_addc_u32 s73, s73, 0
	s_add_u32 s8, s8, 0x100
	s_addc_u32 s9, s9, 0
	s_cmp_gt_u32 s62, 29
	s_cbranch_scc0 .LBB0_198
	s_and_b64 vcc, exec, s[6:7]
	s_cbranch_vccz .LBB0_201
	s_barrier

.LBB0_282:
	ds_read_b128 v[2:5], v187
	ds_read_b128 v[6:9], v187 offset:1024
	ds_read_b128 v[174:177], v187 offset:2048
	ds_read_b128 v[178:181], v187 offset:3072
	ds_read_b128 v[190:193], v187 offset:16384
	ds_read_b128 v[194:197], v187 offset:17408
	ds_read_b128 v[198:201], v187 offset:18432
	ds_read_b128 v[202:205], v187 offset:19456
	s_add_u32 s49, s52, 0x100
	s_addc_u32 s71, s53, 0
	s_and_b64 s[62:63], s[54:55], exec
	s_cselect_b32 s73, s1, s71
	s_cselect_b32 s72, s0, s49
	s_add_u32 s49, s50, 0x100
	s_addc_u32 s62, s51, 0
	s_and_b64 s[54:55], s[54:55], exec
	s_cselect_b32 s55, s5, s62
	s_cselect_b32 s54, s4, s49
	s_add_u32 s62, s52, 0x158080
	s_addc_u32 s63, s53, 0
	s_add_i32 s49, s33, 0xc000
	v_lshl_add_u64 v[182:183], s[62:63], 0, v[154:155]
	s_mov_b32 m0, s49
	s_add_i32 s71, s33, 0xe000
	ds_read_b128 v[206:209], v188
	ds_read_b128 v[210:213], v188 offset:1024
	ds_read_b128 v[214:217], v188 offset:2048
	ds_read_b128 v[218:221], v188 offset:3072
	ds_read_b128 v[222:225], v188 offset:4096
	ds_read_b128 v[226:229], v188 offset:5120
	ds_read_b128 v[230:233], v188 offset:6144
	ds_read_b128 v[234:237], v188 offset:7168
	global_load_lds_dwordx4 v[182:183], off
	v_lshl_add_u64 v[182:183], s[62:63], 0, v[158:159]
	s_mov_b32 m0, s71
	s_nop 0
	global_load_lds_dwordx4 v[182:183], off
	s_waitcnt vmcnt(8)
	s_waitcnt lgkmcnt(0)
	s_setprio 1
	s_barrier
	v_mfma_f32_16x16x128_f8f6f4 v[134:137], v[2:9], v[206:213], 0
	v_mfma_f32_16x16x128_f8f6f4 v[130:133], v[174:181], v[206:213], 0
	v_mfma_f32_16x16x128_f8f6f4 v[122:125], v[174:181], v[214:221], 0
	v_mfma_f32_16x16x128_f8f6f4 v[126:129], v[2:9], v[214:221], 0
	v_mfma_f32_16x16x128_f8f6f4 v[118:121], v[2:9], v[222:229], 0
	v_mfma_f32_16x16x128_f8f6f4 v[114:117], v[174:181], v[222:229], 0
	v_mfma_f32_16x16x128_f8f6f4 v[106:109], v[174:181], v[230:237], 0
	v_mfma_f32_16x16x128_f8f6f4 v[110:113], v[2:9], v[230:237], 0
	s_setprio 0
	s_setprio 1
	v_mfma_f32_16x16x128_f8f6f4 v[78:81], v[190:197], v[230:237], 0
	v_mfma_f32_16x16x128_f8f6f4 v[74:77], v[198:205], v[230:237], 0
	v_mfma_f32_16x16x128_f8f6f4 v[82:85], v[198:205], v[222:229], 0
	v_mfma_f32_16x16x128_f8f6f4 v[86:89], v[190:197], v[222:229], 0
	v_mfma_f32_16x16x128_f8f6f4 v[94:97], v[190:197], v[214:221], 0
	v_mfma_f32_16x16x128_f8f6f4 v[90:93], v[198:205], v[214:221], 0
	v_mfma_f32_16x16x128_f8f6f4 v[98:101], v[198:205], v[206:213], 0
	v_mfma_f32_16x16x128_f8f6f4 v[102:105], v[190:197], v[206:213], 0
	s_setprio 0
	s_barrier
	s_mov_b32 m0, s47
	v_lshl_add_u64 v[182:183], s[54:55], 0, v[156:157]
	s_add_u32 s62, s54, 0x158000
	ds_read_b128 v[206:209], v188 offset:16384
	ds_read_b128 v[210:213], v188 offset:17408
	ds_read_b128 v[214:217], v188 offset:18432
	ds_read_b128 v[218:221], v188 offset:19456
	ds_read_b128 v[222:225], v188 offset:20480
	ds_read_b128 v[226:229], v188 offset:21504
	ds_read_b128 v[230:233], v188 offset:22528
	ds_read_b128 v[234:237], v188 offset:23552
	global_load_lds_dwordx4 v[182:183], off
	v_lshl_add_u64 v[238:239], s[54:55], 0, v[160:161]
	s_mov_b32 m0, s68
	s_addc_u32 s63, s55, 0
	global_load_lds_dwordx4 v[238:239], off
	v_lshl_add_u64 v[242:243], s[62:63], 0, v[156:157]
	s_mov_b32 m0, s69
	v_lshl_add_u64 v[244:245], s[72:73], 0, v[158:159]
	global_load_lds_dwordx4 v[242:243], off
	v_lshl_add_u64 v[242:243], s[62:63], 0, v[160:161]
	s_mov_b32 m0, s74
	s_nop 0
	global_load_lds_dwordx4 v[242:243], off
	v_lshl_add_u64 v[242:243], s[72:73], 0, v[154:155]
	s_mov_b32 m0, s33
	s_nop 0
	global_load_lds_dwordx4 v[242:243], off
	s_mov_b32 m0, s75
	s_nop 0
	global_load_lds_dwordx4 v[244:245], off
	s_waitcnt vmcnt(8)
	s_waitcnt lgkmcnt(0)
	s_setprio 1
	s_barrier
	v_mfma_f32_16x16x128_f8f6f4 v[70:73], v[2:9], v[206:213], 0
	v_mfma_f32_16x16x128_f8f6f4 v[66:69], v[174:181], v[206:213], 0
	v_mfma_f32_16x16x128_f8f6f4 v[58:61], v[174:181], v[214:221], 0
	v_mfma_f32_16x16x128_f8f6f4 v[62:65], v[2:9], v[214:221], 0
	v_mfma_f32_16x16x128_f8f6f4 v[54:57], v[2:9], v[222:229], 0
	v_mfma_f32_16x16x128_f8f6f4 v[50:53], v[174:181], v[222:229], 0
	v_mfma_f32_16x16x128_f8f6f4 v[42:45], v[174:181], v[230:237], 0
	v_mfma_f32_16x16x128_f8f6f4 v[46:49], v[2:9], v[230:237], 0
	s_setprio 0
	s_setprio 1
	v_mfma_f32_16x16x128_f8f6f4 v[14:17], v[190:197], v[230:237], 0
	v_mfma_f32_16x16x128_f8f6f4 v[10:13], v[198:205], v[230:237], 0
	v_mfma_f32_16x16x128_f8f6f4 v[18:21], v[198:205], v[222:229], 0
	v_mfma_f32_16x16x128_f8f6f4 v[22:25], v[190:197], v[222:229], 0
	v_mfma_f32_16x16x128_f8f6f4 v[30:33], v[190:197], v[214:221], 0
	v_mfma_f32_16x16x128_f8f6f4 v[26:29], v[198:205], v[214:221], 0
	v_mfma_f32_16x16x128_f8f6f4 v[34:37], v[198:205], v[206:213], 0
	v_mfma_f32_16x16x128_f8f6f4 v[38:41], v[190:197], v[206:213], 0
	s_setprio 0
	s_barrier
	ds_read_b128 v[2:5], v187 offset:32768
	ds_read_b128 v[6:9], v187 offset:33792
	ds_read_b128 v[174:177], v187 offset:34816
	ds_read_b128 v[178:181], v187 offset:35840
	ds_read_b128 v[190:193], v187 offset:49152
	ds_read_b128 v[194:197], v187 offset:50176
	ds_read_b128 v[198:201], v187 offset:51200
	ds_read_b128 v[202:205], v187 offset:52224
	s_add_u32 s62, s72, 0x158000
	s_addc_u32 s63, s73, 0
	s_mov_b32 m0, s76
	v_lshl_add_u64 v[246:247], s[62:63], 0, v[154:155]
	ds_read_b128 v[206:209], v188 offset:32768
	ds_read_b128 v[210:213], v188 offset:33792
	ds_read_b128 v[214:217], v188 offset:34816
	ds_read_b128 v[218:221], v188 offset:35840
	ds_read_b128 v[222:225], v188 offset:36864
	ds_read_b128 v[226:229], v188 offset:37888
	ds_read_b128 v[230:233], v188 offset:38912
	ds_read_b128 v[234:237], v188 offset:39936
	global_load_lds_dwordx4 v[246:247], off
	v_lshl_add_u64 v[246:247], s[62:63], 0, v[158:159]
	s_mov_b32 m0, s77
	s_nop 0
	global_load_lds_dwordx4 v[246:247], off
	s_waitcnt vmcnt(8)
	s_waitcnt lgkmcnt(0)
	s_setprio 1
	s_barrier
	v_mfma_f32_16x16x128_f8f6f4 v[134:137], v[2:9], v[206:213], v[134:137]
	v_mfma_f32_16x16x128_f8f6f4 v[130:133], v[174:181], v[206:213], v[130:133]
	v_mfma_f32_16x16x128_f8f6f4 v[122:125], v[174:181], v[214:221], v[122:125]
	v_mfma_f32_16x16x128_f8f6f4 v[126:129], v[2:9], v[214:221], v[126:129]
	v_mfma_f32_16x16x128_f8f6f4 v[118:121], v[2:9], v[222:229], v[118:121]
	v_mfma_f32_16x16x128_f8f6f4 v[114:117], v[174:181], v[222:229], v[114:117]
	v_mfma_f32_16x16x128_f8f6f4 v[106:109], v[174:181], v[230:237], v[106:109]
	v_mfma_f32_16x16x128_f8f6f4 v[110:113], v[2:9], v[230:237], v[110:113]
	s_setprio 0
	s_setprio 1
	v_mfma_f32_16x16x128_f8f6f4 v[78:81], v[190:197], v[230:237], v[78:81]
	v_mfma_f32_16x16x128_f8f6f4 v[74:77], v[198:205], v[230:237], v[74:77]
	v_mfma_f32_16x16x128_f8f6f4 v[82:85], v[198:205], v[222:229], v[82:85]
	v_mfma_f32_16x16x128_f8f6f4 v[86:89], v[190:197], v[222:229], v[86:89]
	v_mfma_f32_16x16x128_f8f6f4 v[94:97], v[190:197], v[214:221], v[94:97]
	v_mfma_f32_16x16x128_f8f6f4 v[90:93], v[198:205], v[214:221], v[90:93]
	v_mfma_f32_16x16x128_f8f6f4 v[98:101], v[198:205], v[206:213], v[98:101]
	v_mfma_f32_16x16x128_f8f6f4 v[102:105], v[190:197], v[206:213], v[102:105]
	s_setprio 0
	s_barrier
	s_mov_b32 m0, s83
	v_lshl_add_u64 v[182:183], v[182:183], 0, s[26:27]
	s_add_u32 s54, s54, 0x158080
	ds_read_b128 v[206:209], v188 offset:49152
	ds_read_b128 v[210:213], v188 offset:50176
	ds_read_b128 v[214:217], v188 offset:51200
	ds_read_b128 v[218:221], v188 offset:52224
	ds_read_b128 v[222:225], v188 offset:53248
	ds_read_b128 v[226:229], v188 offset:54272
	ds_read_b128 v[230:233], v188 offset:55296
	ds_read_b128 v[234:237], v188 offset:56320
	global_load_lds_dwordx4 v[182:183], off
	v_lshl_add_u64 v[182:183], v[238:239], 0, s[26:27]
	s_mov_b32 m0, s84
	s_addc_u32 s55, s55, 0
	global_load_lds_dwordx4 v[182:183], off
	v_lshl_add_u64 v[182:183], s[54:55], 0, v[156:157]
	s_mov_b32 m0, s87
	s_nop 0
	global_load_lds_dwordx4 v[182:183], off
	v_lshl_add_u64 v[182:183], s[54:55], 0, v[160:161]
	s_mov_b32 m0, s88
	s_nop 0
	global_load_lds_dwordx4 v[182:183], off
	v_lshl_add_u64 v[182:183], v[242:243], 0, s[26:27]
	s_mov_b32 m0, s85
	s_nop 0
	global_load_lds_dwordx4 v[182:183], off
	v_lshl_add_u64 v[182:183], v[244:245], 0, s[26:27]
	s_mov_b32 m0, s86
	s_nop 0
	global_load_lds_dwordx4 v[182:183], off
	s_waitcnt vmcnt(8)
	s_waitcnt lgkmcnt(0)
	s_setprio 1
	s_barrier
	v_mfma_f32_16x16x128_f8f6f4 v[70:73], v[2:9], v[206:213], v[70:73]
	v_mfma_f32_16x16x128_f8f6f4 v[66:69], v[174:181], v[206:213], v[66:69]
	v_mfma_f32_16x16x128_f8f6f4 v[58:61], v[174:181], v[214:221], v[58:61]
	v_mfma_f32_16x16x128_f8f6f4 v[62:65], v[2:9], v[214:221], v[62:65]
	v_mfma_f32_16x16x128_f8f6f4 v[54:57], v[2:9], v[222:229], v[54:57]
	v_mfma_f32_16x16x128_f8f6f4 v[50:53], v[174:181], v[222:229], v[50:53]
	v_mfma_f32_16x16x128_f8f6f4 v[42:45], v[174:181], v[230:237], v[42:45]
	v_mfma_f32_16x16x128_f8f6f4 v[46:49], v[2:9], v[230:237], v[46:49]
	s_setprio 0
	s_setprio 1
	v_mfma_f32_16x16x128_f8f6f4 v[14:17], v[190:197], v[230:237], v[14:17]
	v_mfma_f32_16x16x128_f8f6f4 v[10:13], v[198:205], v[230:237], v[10:13]
	v_mfma_f32_16x16x128_f8f6f4 v[18:21], v[198:205], v[222:229], v[18:21]
	v_mfma_f32_16x16x128_f8f6f4 v[22:25], v[190:197], v[222:229], v[22:25]
	v_mfma_f32_16x16x128_f8f6f4 v[30:33], v[190:197], v[214:221], v[30:33]
	v_mfma_f32_16x16x128_f8f6f4 v[26:29], v[198:205], v[214:221], v[26:29]
	v_mfma_f32_16x16x128_f8f6f4 v[34:37], v[198:205], v[206:213], v[34:37]
	v_mfma_f32_16x16x128_f8f6f4 v[38:41], v[190:197], v[206:213], v[38:41]
	s_setprio 0
	s_barrier
	s_cmp_lt_u32 s95, 3
	s_cbranch_scc1 .LBB0_287
	s_add_u32 s54, s79, s9
	s_addc_u32 s55, s80, s8
	s_add_u32 s52, s52, 0x158180
	s_addc_u32 s53, s53, 0
	s_add_u32 s8, s50, 0x200
	v_lshl_add_u64 v[174:175], v[172:173], 2, s[54:55]
	s_addc_u32 s9, s51, 0
	s_mov_b32 s72, 4
	s_cmp_eq_u32 s95, s72
	s_cselect_b64 s[50:51], -1, 0
	s_cmp_lg_u32 s95, s72
	s_cbranch_scc1 .LBB0_285

.LBB0_285:
	ds_read_b128 v[2:5], v187
	ds_read_b128 v[6:9], v187 offset:1024
	ds_read_b128 v[190:193], v187 offset:2048
	ds_read_b128 v[194:197], v187 offset:3072
	ds_read_b128 v[198:201], v187 offset:16384
	ds_read_b128 v[202:205], v187 offset:17408
	ds_read_b128 v[206:209], v187 offset:18432
	ds_read_b128 v[210:213], v187 offset:19456
	s_add_u32 s54, s52, 0xffea8080
	s_addc_u32 s55, s53, -1
	s_and_b64 s[50:51], s[50:51], exec
	s_cselect_b32 s50, s4, s8
	s_cselect_b32 s55, s1, s55
	s_cselect_b32 s54, s0, s54
	s_cselect_b32 s51, s5, s9
	s_mov_b32 m0, s49
	v_lshl_add_u64 v[238:239], s[52:53], 0, v[162:163]
	ds_read_b128 v[176:179], v188
	ds_read_b128 v[180:183], v188 offset:1024
	ds_read_b128 v[214:217], v188 offset:2048
	ds_read_b128 v[218:221], v188 offset:3072
	ds_read_b128 v[222:225], v188 offset:4096
	ds_read_b128 v[226:229], v188 offset:5120
	ds_read_b128 v[230:233], v188 offset:6144
	ds_read_b128 v[234:237], v188 offset:7168
	global_load_lds_dwordx4 v[238:239], off
	v_lshl_add_u64 v[238:239], s[52:53], 0, v[164:165]
	s_mov_b32 m0, s71
	s_nop 0
	global_load_lds_dwordx4 v[238:239], off
	s_waitcnt vmcnt(8)
	s_waitcnt lgkmcnt(0)
	s_setprio 1
	s_barrier
	v_mfma_f32_16x16x128_f8f6f4 v[134:137], v[2:9], v[176:183], v[134:137]
	v_mfma_f32_16x16x128_f8f6f4 v[130:133], v[190:197], v[176:183], v[130:133]
	v_mfma_f32_16x16x128_f8f6f4 v[122:125], v[190:197], v[214:221], v[122:125]
	v_mfma_f32_16x16x128_f8f6f4 v[126:129], v[2:9], v[214:221], v[126:129]
	v_mfma_f32_16x16x128_f8f6f4 v[118:121], v[2:9], v[222:229], v[118:121]
	v_mfma_f32_16x16x128_f8f6f4 v[114:117], v[190:197], v[222:229], v[114:117]
	v_mfma_f32_16x16x128_f8f6f4 v[106:109], v[190:197], v[230:237], v[106:109]
	v_mfma_f32_16x16x128_f8f6f4 v[110:113], v[2:9], v[230:237], v[110:113]
	s_setprio 0
	s_setprio 1
	v_mfma_f32_16x16x128_f8f6f4 v[78:81], v[198:205], v[230:237], v[78:81]
	v_mfma_f32_16x16x128_f8f6f4 v[74:77], v[206:213], v[230:237], v[74:77]
	v_mfma_f32_16x16x128_f8f6f4 v[82:85], v[206:213], v[222:229], v[82:85]
	v_mfma_f32_16x16x128_f8f6f4 v[86:89], v[198:205], v[222:229], v[86:89]
	v_mfma_f32_16x16x128_f8f6f4 v[94:97], v[198:205], v[214:221], v[94:97]
	v_mfma_f32_16x16x128_f8f6f4 v[90:93], v[206:213], v[214:221], v[90:93]
	v_mfma_f32_16x16x128_f8f6f4 v[98:101], v[206:213], v[176:183], v[98:101]
	v_mfma_f32_16x16x128_f8f6f4 v[102:105], v[198:205], v[176:183], v[102:105]
	s_setprio 0
	s_barrier
	s_mov_b32 m0, s47
	v_lshl_add_u64 v[176:177], s[50:51], 0, v[156:157]
	s_add_u32 s62, s50, 0x158000
	ds_read_b128 v[214:217], v188 offset:16384
	ds_read_b128 v[218:221], v188 offset:17408
	ds_read_b128 v[222:225], v188 offset:18432
	ds_read_b128 v[226:229], v188 offset:19456
	ds_read_b128 v[230:233], v188 offset:20480
	ds_read_b128 v[234:237], v188 offset:21504
	ds_read_b128 v[242:245], v188 offset:22528
	ds_read_b128 v[246:249], v188 offset:23552
	global_load_lds_dwordx4 v[176:177], off
	v_lshl_add_u64 v[178:179], s[50:51], 0, v[160:161]
	s_mov_b32 m0, s68
	s_addc_u32 s63, s51, 0
	global_load_lds_dwordx4 v[178:179], off
	v_lshl_add_u64 v[180:181], s[62:63], 0, v[156:157]
	s_mov_b32 m0, s69
	v_lshl_add_u64 v[182:183], s[54:55], 0, v[158:159]
	global_load_lds_dwordx4 v[180:181], off
	v_lshl_add_u64 v[180:181], s[62:63], 0, v[160:161]
	s_mov_b32 m0, s74
	s_nop 0
	global_load_lds_dwordx4 v[180:181], off
	v_lshl_add_u64 v[180:181], s[54:55], 0, v[154:155]
	s_mov_b32 m0, s33
	s_nop 0
	global_load_lds_dwordx4 v[180:181], off
	s_mov_b32 m0, s75
	s_nop 0
	global_load_lds_dwordx4 v[182:183], off
	s_waitcnt vmcnt(8)
	s_waitcnt lgkmcnt(0)
	s_setprio 1
	s_barrier
	v_mfma_f32_16x16x128_f8f6f4 v[70:73], v[2:9], v[214:221], v[70:73]
	v_mfma_f32_16x16x128_f8f6f4 v[66:69], v[190:197], v[214:221], v[66:69]
	v_mfma_f32_16x16x128_f8f6f4 v[58:61], v[190:197], v[222:229], v[58:61]
	v_mfma_f32_16x16x128_f8f6f4 v[62:65], v[2:9], v[222:229], v[62:65]
	v_mfma_f32_16x16x128_f8f6f4 v[54:57], v[2:9], v[230:237], v[54:57]
	v_mfma_f32_16x16x128_f8f6f4 v[50:53], v[190:197], v[230:237], v[50:53]
	v_mfma_f32_16x16x128_f8f6f4 v[42:45], v[190:197], v[242:249], v[42:45]
	v_mfma_f32_16x16x128_f8f6f4 v[46:49], v[2:9], v[242:249], v[46:49]
	s_setprio 0
	s_setprio 1
	v_mfma_f32_16x16x128_f8f6f4 v[14:17], v[198:205], v[242:249], v[14:17]
	v_mfma_f32_16x16x128_f8f6f4 v[10:13], v[206:213], v[242:249], v[10:13]
	v_mfma_f32_16x16x128_f8f6f4 v[18:21], v[206:213], v[230:237], v[18:21]
	v_mfma_f32_16x16x128_f8f6f4 v[22:25], v[198:205], v[230:237], v[22:25]
	v_mfma_f32_16x16x128_f8f6f4 v[30:33], v[198:205], v[222:229], v[30:33]
	v_mfma_f32_16x16x128_f8f6f4 v[26:29], v[206:213], v[222:229], v[26:29]
	v_mfma_f32_16x16x128_f8f6f4 v[34:37], v[206:213], v[214:221], v[34:37]
	v_mfma_f32_16x16x128_f8f6f4 v[38:41], v[198:205], v[214:221], v[38:41]
	s_setprio 0
	s_barrier
	ds_read_b128 v[190:193], v187 offset:32768
	ds_read_b128 v[194:197], v187 offset:33792
	ds_read_b128 v[198:201], v187 offset:34816
	ds_read_b128 v[202:205], v187 offset:35840
	ds_read_b128 v[2:5], v187 offset:49152
	ds_read_b128 v[6:9], v187 offset:50176
	ds_read_b128 v[206:209], v187 offset:51200
	ds_read_b128 v[210:213], v187 offset:52224
	s_add_u32 s54, s54, 0x158000
	s_addc_u32 s55, s55, 0
	s_mov_b32 m0, s76
	v_lshl_add_u64 v[238:239], s[54:55], 0, v[154:155]
	ds_read_b128 v[214:217], v188 offset:32768
	ds_read_b128 v[218:221], v188 offset:33792
	ds_read_b128 v[222:225], v188 offset:34816
	ds_read_b128 v[226:229], v188 offset:35840
	ds_read_b128 v[230:233], v188 offset:36864
	ds_read_b128 v[234:237], v188 offset:37888
	ds_read_b128 v[242:245], v188 offset:38912
	ds_read_b128 v[246:249], v188 offset:39936
	global_load_lds_dwordx4 v[238:239], off
	v_lshl_add_u64 v[238:239], s[54:55], 0, v[158:159]
	s_mov_b32 m0, s77
	s_nop 0
	global_load_lds_dwordx4 v[238:239], off
	s_waitcnt vmcnt(8)
	s_waitcnt lgkmcnt(0)
	s_setprio 1
	s_barrier
	v_mfma_f32_16x16x128_f8f6f4 v[134:137], v[190:197], v[214:221], v[134:137]
	v_mfma_f32_16x16x128_f8f6f4 v[130:133], v[198:205], v[214:221], v[130:133]
	v_mfma_f32_16x16x128_f8f6f4 v[122:125], v[198:205], v[222:229], v[122:125]
	v_mfma_f32_16x16x128_f8f6f4 v[126:129], v[190:197], v[222:229], v[126:129]
	v_mfma_f32_16x16x128_f8f6f4 v[118:121], v[190:197], v[230:237], v[118:121]
	v_mfma_f32_16x16x128_f8f6f4 v[114:117], v[198:205], v[230:237], v[114:117]
	v_mfma_f32_16x16x128_f8f6f4 v[106:109], v[198:205], v[242:249], v[106:109]
	v_mfma_f32_16x16x128_f8f6f4 v[110:113], v[190:197], v[242:249], v[110:113]
	s_setprio 0
	s_setprio 1
	v_mfma_f32_16x16x128_f8f6f4 v[78:81], v[2:9], v[242:249], v[78:81]
	v_mfma_f32_16x16x128_f8f6f4 v[74:77], v[206:213], v[242:249], v[74:77]
	v_mfma_f32_16x16x128_f8f6f4 v[82:85], v[206:213], v[230:237], v[82:85]
	v_mfma_f32_16x16x128_f8f6f4 v[86:89], v[2:9], v[230:237], v[86:89]
	v_mfma_f32_16x16x128_f8f6f4 v[94:97], v[2:9], v[222:229], v[94:97]
	v_mfma_f32_16x16x128_f8f6f4 v[90:93], v[206:213], v[222:229], v[90:93]
	v_mfma_f32_16x16x128_f8f6f4 v[98:101], v[206:213], v[214:221], v[98:101]
	v_mfma_f32_16x16x128_f8f6f4 v[102:105], v[2:9], v[214:221], v[102:105]
	s_setprio 0
	s_barrier
	s_mov_b32 m0, s83
	v_lshl_add_u64 v[176:177], v[176:177], 0, s[26:27]
	s_add_u32 s50, s50, 0x158080
	ds_read_b128 v[214:217], v188 offset:49152
	ds_read_b128 v[218:221], v188 offset:50176
	ds_read_b128 v[222:225], v188 offset:51200
	ds_read_b128 v[226:229], v188 offset:52224
	ds_read_b128 v[230:233], v188 offset:53248
	ds_read_b128 v[234:237], v188 offset:54272
	ds_read_b128 v[242:245], v188 offset:55296
	ds_read_b128 v[246:249], v188 offset:56320
	global_load_lds_dwordx4 v[176:177], off
	v_lshl_add_u64 v[176:177], v[178:179], 0, s[26:27]
	s_mov_b32 m0, s84
	s_addc_u32 s51, s51, 0
	global_load_lds_dwordx4 v[176:177], off
	v_lshl_add_u64 v[176:177], s[50:51], 0, v[156:157]
	s_mov_b32 m0, s87
	s_nop 0
	global_load_lds_dwordx4 v[176:177], off
	v_lshl_add_u64 v[176:177], s[50:51], 0, v[160:161]
	s_mov_b32 m0, s88
	s_nop 0
	global_load_lds_dwordx4 v[176:177], off
	v_lshl_add_u64 v[176:177], v[180:181], 0, s[26:27]
	s_mov_b32 m0, s85
	s_nop 0
	global_load_lds_dwordx4 v[176:177], off
	v_lshl_add_u64 v[176:177], v[182:183], 0, s[26:27]
	s_mov_b32 m0, s86
	s_nop 0
	global_load_lds_dwordx4 v[176:177], off
	s_waitcnt vmcnt(8)
	s_waitcnt lgkmcnt(0)
	s_setprio 1
	s_barrier
	v_mfma_f32_16x16x128_f8f6f4 v[70:73], v[190:197], v[214:221], v[70:73]
	v_mfma_f32_16x16x128_f8f6f4 v[66:69], v[198:205], v[214:221], v[66:69]
	v_mfma_f32_16x16x128_f8f6f4 v[58:61], v[198:205], v[222:229], v[58:61]
	v_mfma_f32_16x16x128_f8f6f4 v[62:65], v[190:197], v[222:229], v[62:65]
	v_mfma_f32_16x16x128_f8f6f4 v[54:57], v[190:197], v[230:237], v[54:57]
	v_mfma_f32_16x16x128_f8f6f4 v[50:53], v[198:205], v[230:237], v[50:53]
	v_mfma_f32_16x16x128_f8f6f4 v[42:45], v[198:205], v[242:249], v[42:45]
	v_mfma_f32_16x16x128_f8f6f4 v[46:49], v[190:197], v[242:249], v[46:49]
	s_setprio 0
	s_setprio 1
	v_mfma_f32_16x16x128_f8f6f4 v[14:17], v[2:9], v[242:249], v[14:17]
	v_mfma_f32_16x16x128_f8f6f4 v[10:13], v[206:213], v[242:249], v[10:13]
	v_mfma_f32_16x16x128_f8f6f4 v[18:21], v[206:213], v[230:237], v[18:21]
	v_mfma_f32_16x16x128_f8f6f4 v[22:25], v[2:9], v[230:237], v[22:25]
	v_mfma_f32_16x16x128_f8f6f4 v[30:33], v[2:9], v[222:229], v[30:33]
	v_mfma_f32_16x16x128_f8f6f4 v[26:29], v[206:213], v[222:229], v[26:29]
	v_mfma_f32_16x16x128_f8f6f4 v[34:37], v[206:213], v[214:221], v[34:37]
	v_mfma_f32_16x16x128_f8f6f4 v[38:41], v[2:9], v[214:221], v[38:41]
	s_setprio 0
	s_barrier
	s_add_i32 s50, s72, 2
	s_add_u32 s52, s52, 0x100
	s_addc_u32 s53, s53, 0
	s_add_u32 s8, s8, 0x100
	s_addc_u32 s9, s9, 0
	s_cmp_ge_i32 s72, s95
	s_cbranch_scc1 .LBB0_287
	s_mov_b32 s72, s50
	s_cmp_eq_u32 s95, s72
	s_cselect_b64 s[50:51], -1, 0
	s_cmp_lg_u32 s95, s72
	s_cbranch_scc0 .LBB0_284
	s_branch .LBB0_285

.LBB0_437:
	s_ashr_i32 s47, s46, 31
	ds_read_b128 v[18:21], v200
	ds_read_b128 v[22:25], v200 offset:1024
	ds_read_b128 v[26:29], v200 offset:2048
	ds_read_b128 v[30:33], v200 offset:3072
	ds_read_b128 v[2:5], v200 offset:16384
	ds_read_b128 v[6:9], v200 offset:17408
	ds_read_b128 v[10:13], v200 offset:18432
	ds_read_b128 v[14:17], v200 offset:19456
	s_lshl_b64 s[8:9], s[46:47], 20
	s_add_u32 s48, s12, s8
	s_addc_u32 s49, s13, s9
	s_and_b64 s[8:9], s[2:3], exec
	s_cselect_b32 s47, s49, s73
	s_cselect_b32 s71, s48, s72
	s_ashr_i32 s45, s44, 31
	s_lshl_b64 s[8:9], s[44:45], 20
	s_add_u32 s50, s39, s8
	s_addc_u32 s51, s76, s9
	s_and_b64 s[8:9], s[2:3], exec
	s_cselect_b32 s45, s51, s55
	s_cselect_b32 s94, s50, s54
	s_add_u32 s8, s72, 0x80080
	s_addc_u32 s9, s73, 0
	s_mov_b32 m0, s33
	v_lshl_add_u64 v[226:227], s[8:9], 0, v[162:163]
	ds_read_b128 v[180:183], v201
	ds_read_b128 v[184:187], v201 offset:1024
	ds_read_b128 v[202:205], v201 offset:2048
	ds_read_b128 v[206:209], v201 offset:3072
	ds_read_b128 v[210:213], v201 offset:4096
	ds_read_b128 v[214:217], v201 offset:5120
	ds_read_b128 v[218:221], v201 offset:6144
	ds_read_b128 v[222:225], v201 offset:7168
	global_load_lds_dwordx4 v[226:227], off
	v_lshl_add_u64 v[226:227], s[8:9], 0, v[166:167]
	s_mov_b32 m0, s93
	s_nop 0
	global_load_lds_dwordx4 v[226:227], off
	s_waitcnt vmcnt(8)
	s_waitcnt lgkmcnt(0)
	s_setprio 1
	s_barrier
	v_mfma_f32_16x16x128_f8f6f4 v[158:161], v[18:25], v[180:187], 0
	v_mfma_f32_16x16x128_f8f6f4 v[154:157], v[26:33], v[180:187], 0
	v_mfma_f32_16x16x128_f8f6f4 v[146:149], v[26:33], v[202:209], 0
	v_mfma_f32_16x16x128_f8f6f4 v[150:153], v[18:25], v[202:209], 0
	v_mfma_f32_16x16x128_f8f6f4 v[142:145], v[18:25], v[210:217], 0
	v_mfma_f32_16x16x128_f8f6f4 v[138:141], v[26:33], v[210:217], 0
	v_mfma_f32_16x16x128_f8f6f4 v[130:133], v[26:33], v[218:225], 0
	v_mfma_f32_16x16x128_f8f6f4 v[134:137], v[18:25], v[218:225], 0
	s_setprio 0
	s_setprio 1
	v_mfma_f32_16x16x128_f8f6f4 v[102:105], v[2:9], v[218:225], 0
	v_mfma_f32_16x16x128_f8f6f4 v[98:101], v[10:17], v[218:225], 0
	v_mfma_f32_16x16x128_f8f6f4 v[106:109], v[10:17], v[210:217], 0
	v_mfma_f32_16x16x128_f8f6f4 v[110:113], v[2:9], v[210:217], 0
	v_mfma_f32_16x16x128_f8f6f4 v[118:121], v[2:9], v[202:209], 0
	v_mfma_f32_16x16x128_f8f6f4 v[114:117], v[10:17], v[202:209], 0
	v_mfma_f32_16x16x128_f8f6f4 v[122:125], v[10:17], v[180:187], 0
	v_mfma_f32_16x16x128_f8f6f4 v[126:129], v[2:9], v[180:187], 0
	s_setprio 0
	s_barrier
	v_lshl_add_u64 v[180:181], s[54:55], 0, v[164:165]
	s_mov_b32 m0, s78
	v_lshl_add_u64 v[182:183], v[180:181], 0, s[26:27]
	ds_read_b128 v[202:205], v201 offset:16384
	ds_read_b128 v[206:209], v201 offset:17408
	ds_read_b128 v[210:213], v201 offset:18432
	ds_read_b128 v[214:217], v201 offset:19456
	ds_read_b128 v[218:221], v201 offset:20480
	ds_read_b128 v[222:225], v201 offset:21504
	ds_read_b128 v[226:229], v201 offset:22528
	ds_read_b128 v[230:233], v201 offset:23552
	global_load_lds_dwordx4 v[182:183], off
	v_lshl_add_u64 v[182:183], s[54:55], 0, v[168:169]
	s_add_u32 s8, s54, 0x80100
	v_lshl_add_u64 v[184:185], v[182:183], 0, s[26:27]
	s_mov_b32 m0, s79
	s_addc_u32 s9, s55, 0
	global_load_lds_dwordx4 v[184:185], off
	v_lshl_add_u64 v[184:185], s[8:9], 0, v[164:165]
	s_mov_b32 m0, s80
	s_nop 0
	global_load_lds_dwordx4 v[184:185], off
	v_lshl_add_u64 v[184:185], s[8:9], 0, v[168:169]
	s_mov_b32 m0, s81
	s_nop 0
	global_load_lds_dwordx4 v[184:185], off
	v_lshl_add_u64 v[184:185], s[72:73], 0, v[162:163]
	v_lshl_add_u64 v[186:187], v[184:185], 0, s[26:27]
	s_mov_b32 m0, s53
	s_nop 0
	global_load_lds_dwordx4 v[186:187], off
	v_lshl_add_u64 v[186:187], s[72:73], 0, v[166:167]
	v_lshl_add_u64 v[234:235], v[186:187], 0, s[26:27]
	s_mov_b32 m0, s82
	s_nop 0
	global_load_lds_dwordx4 v[234:235], off
	s_waitcnt vmcnt(8)
	s_waitcnt lgkmcnt(0)
	s_setprio 1
	s_barrier
	v_mfma_f32_16x16x128_f8f6f4 v[94:97], v[18:25], v[202:209], 0
	v_mfma_f32_16x16x128_f8f6f4 v[90:93], v[26:33], v[202:209], 0
	v_mfma_f32_16x16x128_f8f6f4 v[82:85], v[26:33], v[210:217], 0
	v_mfma_f32_16x16x128_f8f6f4 v[86:89], v[18:25], v[210:217], 0
	v_mfma_f32_16x16x128_f8f6f4 v[78:81], v[18:25], v[218:225], 0
	v_mfma_f32_16x16x128_f8f6f4 v[74:77], v[26:33], v[218:225], 0
	v_mfma_f32_16x16x128_f8f6f4 v[66:69], v[26:33], v[226:233], 0
	v_mfma_f32_16x16x128_f8f6f4 v[70:73], v[18:25], v[226:233], 0
	s_setprio 0
	s_setprio 1
	v_mfma_f32_16x16x128_f8f6f4 v[38:41], v[2:9], v[226:233], 0
	v_mfma_f32_16x16x128_f8f6f4 v[34:37], v[10:17], v[226:233], 0
	v_mfma_f32_16x16x128_f8f6f4 v[42:45], v[10:17], v[218:225], 0
	v_mfma_f32_16x16x128_f8f6f4 v[46:49], v[2:9], v[218:225], 0
	v_mfma_f32_16x16x128_f8f6f4 v[54:57], v[2:9], v[210:217], 0
	v_mfma_f32_16x16x128_f8f6f4 v[50:53], v[10:17], v[210:217], 0
	v_mfma_f32_16x16x128_f8f6f4 v[58:61], v[10:17], v[202:209], 0
	v_mfma_f32_16x16x128_f8f6f4 v[62:65], v[2:9], v[202:209], 0
	s_setprio 0
	s_barrier
	ds_read_b128 v[18:21], v200 offset:32768
	ds_read_b128 v[22:25], v200 offset:33792
	ds_read_b128 v[26:29], v200 offset:34816
	ds_read_b128 v[30:33], v200 offset:35840
	ds_read_b128 v[2:5], v200 offset:49152
	ds_read_b128 v[6:9], v200 offset:50176
	ds_read_b128 v[10:13], v200 offset:51200
	ds_read_b128 v[14:17], v200 offset:52224
	s_add_u32 s8, s72, 0x80100
	s_addc_u32 s9, s73, 0
	s_mov_b32 m0, s83
	v_lshl_add_u64 v[234:235], s[8:9], 0, v[162:163]
	ds_read_b128 v[202:205], v201 offset:32768
	ds_read_b128 v[206:209], v201 offset:33792
	ds_read_b128 v[210:213], v201 offset:34816
	ds_read_b128 v[214:217], v201 offset:35840
	ds_read_b128 v[218:221], v201 offset:36864
	ds_read_b128 v[222:225], v201 offset:37888
	ds_read_b128 v[226:229], v201 offset:38912
	ds_read_b128 v[230:233], v201 offset:39936
	global_load_lds_dwordx4 v[234:235], off
	v_lshl_add_u64 v[234:235], s[8:9], 0, v[166:167]
	s_mov_b32 m0, s84
	s_nop 0
	global_load_lds_dwordx4 v[234:235], off
	s_waitcnt vmcnt(8)
	s_waitcnt lgkmcnt(0)
	s_setprio 1
	s_barrier
	v_mfma_f32_16x16x128_f8f6f4 v[158:161], v[18:25], v[202:209], v[158:161]
	v_mfma_f32_16x16x128_f8f6f4 v[154:157], v[26:33], v[202:209], v[154:157]
	v_mfma_f32_16x16x128_f8f6f4 v[146:149], v[26:33], v[210:217], v[146:149]
	v_mfma_f32_16x16x128_f8f6f4 v[150:153], v[18:25], v[210:217], v[150:153]
	v_mfma_f32_16x16x128_f8f6f4 v[142:145], v[18:25], v[218:225], v[142:145]
	v_mfma_f32_16x16x128_f8f6f4 v[138:141], v[26:33], v[218:225], v[138:141]
	v_mfma_f32_16x16x128_f8f6f4 v[130:133], v[26:33], v[226:233], v[130:133]
	v_mfma_f32_16x16x128_f8f6f4 v[134:137], v[18:25], v[226:233], v[134:137]
	s_setprio 0
	s_setprio 1
	v_mfma_f32_16x16x128_f8f6f4 v[102:105], v[2:9], v[226:233], v[102:105]
	v_mfma_f32_16x16x128_f8f6f4 v[98:101], v[10:17], v[226:233], v[98:101]
	v_mfma_f32_16x16x128_f8f6f4 v[106:109], v[10:17], v[218:225], v[106:109]
	v_mfma_f32_16x16x128_f8f6f4 v[110:113], v[2:9], v[218:225], v[110:113]
	v_mfma_f32_16x16x128_f8f6f4 v[118:121], v[2:9], v[210:217], v[118:121]
	v_mfma_f32_16x16x128_f8f6f4 v[114:117], v[10:17], v[210:217], v[114:117]
	v_mfma_f32_16x16x128_f8f6f4 v[122:125], v[10:17], v[202:209], v[122:125]
	v_mfma_f32_16x16x128_f8f6f4 v[126:129], v[2:9], v[202:209], v[126:129]
	s_setprio 0
	s_barrier
	s_mov_b32 m0, s87
	v_lshl_add_u64 v[180:181], v[180:181], 0, s[36:37]
	s_add_u32 s8, s54, 0x80180
	ds_read_b128 v[202:205], v201 offset:49152
	ds_read_b128 v[206:209], v201 offset:50176
	ds_read_b128 v[210:213], v201 offset:51200
	ds_read_b128 v[214:217], v201 offset:52224
	ds_read_b128 v[218:221], v201 offset:53248
	ds_read_b128 v[222:225], v201 offset:54272
	ds_read_b128 v[226:229], v201 offset:55296
	ds_read_b128 v[230:233], v201 offset:56320
	global_load_lds_dwordx4 v[180:181], off
	v_lshl_add_u64 v[180:181], v[182:183], 0, s[36:37]
	s_mov_b32 m0, s88
	s_addc_u32 s9, s55, 0
	global_load_lds_dwordx4 v[180:181], off
	v_lshl_add_u64 v[180:181], s[8:9], 0, v[164:165]
	s_mov_b32 m0, s91
	s_nop 0
	global_load_lds_dwordx4 v[180:181], off
	v_lshl_add_u64 v[180:181], s[8:9], 0, v[168:169]
	s_mov_b32 m0, s92
	s_nop 0
	global_load_lds_dwordx4 v[180:181], off
	v_lshl_add_u64 v[180:181], v[184:185], 0, s[36:37]
	s_mov_b32 m0, s89
	s_nop 0
	global_load_lds_dwordx4 v[180:181], off
	v_lshl_add_u64 v[180:181], v[186:187], 0, s[36:37]
	s_mov_b32 m0, s90
	s_nop 0
	global_load_lds_dwordx4 v[180:181], off
	s_waitcnt vmcnt(8)
	s_waitcnt lgkmcnt(0)
	s_setprio 1
	s_barrier
	v_mfma_f32_16x16x128_f8f6f4 v[94:97], v[18:25], v[202:209], v[94:97]
	v_mfma_f32_16x16x128_f8f6f4 v[90:93], v[26:33], v[202:209], v[90:93]
	v_mfma_f32_16x16x128_f8f6f4 v[82:85], v[26:33], v[210:217], v[82:85]
	v_mfma_f32_16x16x128_f8f6f4 v[86:89], v[18:25], v[210:217], v[86:89]
	v_mfma_f32_16x16x128_f8f6f4 v[78:81], v[18:25], v[218:225], v[78:81]
	v_mfma_f32_16x16x128_f8f6f4 v[74:77], v[26:33], v[218:225], v[74:77]
	v_mfma_f32_16x16x128_f8f6f4 v[66:69], v[26:33], v[226:233], v[66:69]
	v_mfma_f32_16x16x128_f8f6f4 v[70:73], v[18:25], v[226:233], v[70:73]
	s_setprio 0
	s_setprio 1
	v_mfma_f32_16x16x128_f8f6f4 v[38:41], v[2:9], v[226:233], v[38:41]
	v_mfma_f32_16x16x128_f8f6f4 v[34:37], v[10:17], v[226:233], v[34:37]
	v_mfma_f32_16x16x128_f8f6f4 v[42:45], v[10:17], v[218:225], v[42:45]
	v_mfma_f32_16x16x128_f8f6f4 v[46:49], v[2:9], v[218:225], v[46:49]
	v_mfma_f32_16x16x128_f8f6f4 v[54:57], v[2:9], v[210:217], v[54:57]
	v_mfma_f32_16x16x128_f8f6f4 v[50:53], v[10:17], v[210:217], v[50:53]
	v_mfma_f32_16x16x128_f8f6f4 v[58:61], v[10:17], v[202:209], v[58:61]
	v_mfma_f32_16x16x128_f8f6f4 v[62:65], v[2:9], v[202:209], v[62:65]
	s_setprio 0
	s_barrier
	s_add_u32 s72, s72, 0x80180
	s_addc_u32 s73, s73, 0
	s_add_u32 s8, s54, 0x200
	s_addc_u32 s9, s55, 0
	s_mov_b32 s62, 0
.LBB0_438:
	ds_read_b128 v[2:5], v200
	ds_read_b128 v[6:9], v200 offset:1024
	ds_read_b128 v[18:21], v200 offset:2048
	ds_read_b128 v[22:25], v200 offset:3072
	ds_read_b128 v[26:29], v200 offset:16384
	ds_read_b128 v[30:33], v200 offset:17408
	ds_read_b128 v[180:183], v200 offset:18432
	ds_read_b128 v[184:187], v200 offset:19456
	s_add_u32 s54, s72, 0xfff80080
	s_addc_u32 s55, s73, -1
	s_cmp_eq_u32 s62, 28
	s_cselect_b32 s75, s47, s55
	s_cselect_b32 s74, s71, s54
	s_cselect_b32 s55, s45, s9
	s_cselect_b32 s54, s94, s8
	s_mov_b32 m0, s33
	v_lshl_add_u64 v[226:227], s[72:73], 0, v[170:171]
	ds_read_b128 v[10:13], v201
	ds_read_b128 v[14:17], v201 offset:1024
	ds_read_b128 v[202:205], v201 offset:2048
	ds_read_b128 v[206:209], v201 offset:3072
	ds_read_b128 v[210:213], v201 offset:4096
	ds_read_b128 v[214:217], v201 offset:5120
	ds_read_b128 v[218:221], v201 offset:6144
	ds_read_b128 v[222:225], v201 offset:7168
	global_load_lds_dwordx4 v[226:227], off
	v_lshl_add_u64 v[226:227], s[72:73], 0, v[172:173]
	s_mov_b32 m0, s93
	s_nop 0
	global_load_lds_dwordx4 v[226:227], off
	s_waitcnt vmcnt(8)
	s_waitcnt lgkmcnt(0)
	s_setprio 1
	s_barrier
	v_mfma_f32_16x16x128_f8f6f4 v[158:161], v[2:9], v[10:17], v[158:161]
	v_mfma_f32_16x16x128_f8f6f4 v[154:157], v[18:25], v[10:17], v[154:157]
	v_mfma_f32_16x16x128_f8f6f4 v[146:149], v[18:25], v[202:209], v[146:149]
	v_mfma_f32_16x16x128_f8f6f4 v[150:153], v[2:9], v[202:209], v[150:153]
	v_mfma_f32_16x16x128_f8f6f4 v[142:145], v[2:9], v[210:217], v[142:145]
	v_mfma_f32_16x16x128_f8f6f4 v[138:141], v[18:25], v[210:217], v[138:141]
	v_mfma_f32_16x16x128_f8f6f4 v[130:133], v[18:25], v[218:225], v[130:133]
	v_mfma_f32_16x16x128_f8f6f4 v[134:137], v[2:9], v[218:225], v[134:137]
	s_setprio 0
	s_setprio 1
	v_mfma_f32_16x16x128_f8f6f4 v[102:105], v[26:33], v[218:225], v[102:105]
	v_mfma_f32_16x16x128_f8f6f4 v[98:101], v[180:187], v[218:225], v[98:101]
	v_mfma_f32_16x16x128_f8f6f4 v[106:109], v[180:187], v[210:217], v[106:109]
	v_mfma_f32_16x16x128_f8f6f4 v[110:113], v[26:33], v[210:217], v[110:113]
	v_mfma_f32_16x16x128_f8f6f4 v[118:121], v[26:33], v[202:209], v[118:121]
	v_mfma_f32_16x16x128_f8f6f4 v[114:117], v[180:187], v[202:209], v[114:117]
	v_mfma_f32_16x16x128_f8f6f4 v[122:125], v[180:187], v[10:17], v[122:125]
	v_mfma_f32_16x16x128_f8f6f4 v[126:129], v[26:33], v[10:17], v[126:129]
	s_setprio 0
	s_barrier
	s_mov_b32 m0, s78
	v_lshl_add_u64 v[10:11], s[54:55], 0, v[164:165]
	s_add_u32 s96, s54, 0x80000
	ds_read_b128 v[202:205], v201 offset:16384
	ds_read_b128 v[206:209], v201 offset:17408
	ds_read_b128 v[210:213], v201 offset:18432
	ds_read_b128 v[214:217], v201 offset:19456
	ds_read_b128 v[218:221], v201 offset:20480
	ds_read_b128 v[222:225], v201 offset:21504
	ds_read_b128 v[226:229], v201 offset:22528
	ds_read_b128 v[230:233], v201 offset:23552
	global_load_lds_dwordx4 v[10:11], off
	v_lshl_add_u64 v[12:13], s[54:55], 0, v[168:169]
	s_mov_b32 m0, s79
	s_addc_u32 s97, s55, 0
	global_load_lds_dwordx4 v[12:13], off
	v_lshl_add_u64 v[14:15], s[96:97], 0, v[164:165]
	s_mov_b32 m0, s80
	v_lshl_add_u64 v[16:17], s[74:75], 0, v[166:167]
	global_load_lds_dwordx4 v[14:15], off
	v_lshl_add_u64 v[14:15], s[96:97], 0, v[168:169]
	s_mov_b32 m0, s81
	s_nop 0
	global_load_lds_dwordx4 v[14:15], off
	v_lshl_add_u64 v[14:15], s[74:75], 0, v[162:163]
	s_mov_b32 m0, s53
	s_nop 0
	global_load_lds_dwordx4 v[14:15], off
	s_mov_b32 m0, s82
	s_nop 0
	global_load_lds_dwordx4 v[16:17], off
	s_waitcnt vmcnt(8)
	s_waitcnt lgkmcnt(0)
	s_setprio 1
	s_barrier
	v_mfma_f32_16x16x128_f8f6f4 v[94:97], v[2:9], v[202:209], v[94:97]
	v_mfma_f32_16x16x128_f8f6f4 v[90:93], v[18:25], v[202:209], v[90:93]
	v_mfma_f32_16x16x128_f8f6f4 v[82:85], v[18:25], v[210:217], v[82:85]
	v_mfma_f32_16x16x128_f8f6f4 v[86:89], v[2:9], v[210:217], v[86:89]
	v_mfma_f32_16x16x128_f8f6f4 v[78:81], v[2:9], v[218:225], v[78:81]
	v_mfma_f32_16x16x128_f8f6f4 v[74:77], v[18:25], v[218:225], v[74:77]
	v_mfma_f32_16x16x128_f8f6f4 v[66:69], v[18:25], v[226:233], v[66:69]
	v_mfma_f32_16x16x128_f8f6f4 v[70:73], v[2:9], v[226:233], v[70:73]
	s_setprio 0
	s_setprio 1
	v_mfma_f32_16x16x128_f8f6f4 v[38:41], v[26:33], v[226:233], v[38:41]
	v_mfma_f32_16x16x128_f8f6f4 v[34:37], v[180:187], v[226:233], v[34:37]
	v_mfma_f32_16x16x128_f8f6f4 v[42:45], v[180:187], v[218:225], v[42:45]
	v_mfma_f32_16x16x128_f8f6f4 v[46:49], v[26:33], v[218:225], v[46:49]
	v_mfma_f32_16x16x128_f8f6f4 v[54:57], v[26:33], v[210:217], v[54:57]
	v_mfma_f32_16x16x128_f8f6f4 v[50:53], v[180:187], v[210:217], v[50:53]
	v_mfma_f32_16x16x128_f8f6f4 v[58:61], v[180:187], v[202:209], v[58:61]
	v_mfma_f32_16x16x128_f8f6f4 v[62:65], v[26:33], v[202:209], v[62:65]
	s_setprio 0
	s_barrier
	ds_read_b128 v[18:21], v200 offset:32768
	ds_read_b128 v[22:25], v200 offset:33792
	ds_read_b128 v[26:29], v200 offset:34816
	ds_read_b128 v[30:33], v200 offset:35840
	ds_read_b128 v[2:5], v200 offset:49152
	ds_read_b128 v[6:9], v200 offset:50176
	ds_read_b128 v[180:183], v200 offset:51200
	ds_read_b128 v[184:187], v200 offset:52224
	s_add_u32 s74, s74, 0x80000
	s_addc_u32 s75, s75, 0
	s_mov_b32 m0, s83
	v_lshl_add_u64 v[234:235], s[74:75], 0, v[162:163]
	ds_read_b128 v[202:205], v201 offset:32768
	ds_read_b128 v[206:209], v201 offset:33792
	ds_read_b128 v[210:213], v201 offset:34816
	ds_read_b128 v[214:217], v201 offset:35840
	ds_read_b128 v[218:221], v201 offset:36864
	ds_read_b128 v[222:225], v201 offset:37888
	ds_read_b128 v[226:229], v201 offset:38912
	ds_read_b128 v[230:233], v201 offset:39936
	global_load_lds_dwordx4 v[234:235], off
	v_lshl_add_u64 v[234:235], s[74:75], 0, v[166:167]
	s_mov_b32 m0, s84
	s_nop 0
	global_load_lds_dwordx4 v[234:235], off
	s_waitcnt vmcnt(8)
	s_waitcnt lgkmcnt(0)
	s_setprio 1
	s_barrier
	v_mfma_f32_16x16x128_f8f6f4 v[158:161], v[18:25], v[202:209], v[158:161]
	v_mfma_f32_16x16x128_f8f6f4 v[154:157], v[26:33], v[202:209], v[154:157]
	v_mfma_f32_16x16x128_f8f6f4 v[146:149], v[26:33], v[210:217], v[146:149]
	v_mfma_f32_16x16x128_f8f6f4 v[150:153], v[18:25], v[210:217], v[150:153]
	v_mfma_f32_16x16x128_f8f6f4 v[142:145], v[18:25], v[218:225], v[142:145]
	v_mfma_f32_16x16x128_f8f6f4 v[138:141], v[26:33], v[218:225], v[138:141]
	v_mfma_f32_16x16x128_f8f6f4 v[130:133], v[26:33], v[226:233], v[130:133]
	v_mfma_f32_16x16x128_f8f6f4 v[134:137], v[18:25], v[226:233], v[134:137]
	s_setprio 0
	s_setprio 1
	v_mfma_f32_16x16x128_f8f6f4 v[102:105], v[2:9], v[226:233], v[102:105]
	v_mfma_f32_16x16x128_f8f6f4 v[98:101], v[180:187], v[226:233], v[98:101]
	v_mfma_f32_16x16x128_f8f6f4 v[106:109], v[180:187], v[218:225], v[106:109]
	v_mfma_f32_16x16x128_f8f6f4 v[110:113], v[2:9], v[218:225], v[110:113]
	v_mfma_f32_16x16x128_f8f6f4 v[118:121], v[2:9], v[210:217], v[118:121]
	v_mfma_f32_16x16x128_f8f6f4 v[114:117], v[180:187], v[210:217], v[114:117]
	v_mfma_f32_16x16x128_f8f6f4 v[122:125], v[180:187], v[202:209], v[122:125]
	v_mfma_f32_16x16x128_f8f6f4 v[126:129], v[2:9], v[202:209], v[126:129]
	s_setprio 0
	s_barrier
	s_mov_b32 m0, s87
	v_lshl_add_u64 v[10:11], v[10:11], 0, s[4:5]
	s_add_u32 s54, s54, 0x80080
	ds_read_b128 v[202:205], v201 offset:49152
	ds_read_b128 v[206:209], v201 offset:50176
	ds_read_b128 v[210:213], v201 offset:51200
	ds_read_b128 v[214:217], v201 offset:52224
	ds_read_b128 v[218:221], v201 offset:53248
	ds_read_b128 v[222:225], v201 offset:54272
	ds_read_b128 v[226:229], v201 offset:55296
	ds_read_b128 v[230:233], v201 offset:56320
	global_load_lds_dwordx4 v[10:11], off
	v_lshl_add_u64 v[10:11], v[12:13], 0, s[4:5]
	s_mov_b32 m0, s88
	s_addc_u32 s55, s55, 0
	global_load_lds_dwordx4 v[10:11], off
	v_lshl_add_u64 v[10:11], s[54:55], 0, v[164:165]
	s_mov_b32 m0, s91
	s_nop 0
	global_load_lds_dwordx4 v[10:11], off
	v_lshl_add_u64 v[10:11], s[54:55], 0, v[168:169]
	s_mov_b32 m0, s92
	s_nop 0
	global_load_lds_dwordx4 v[10:11], off
	v_lshl_add_u64 v[10:11], v[14:15], 0, s[4:5]
	s_mov_b32 m0, s89
	s_nop 0
	global_load_lds_dwordx4 v[10:11], off
	v_lshl_add_u64 v[10:11], v[16:17], 0, s[4:5]
	s_mov_b32 m0, s90
	s_nop 0
	global_load_lds_dwordx4 v[10:11], off
	s_waitcnt vmcnt(8)
	s_waitcnt lgkmcnt(0)
	s_setprio 1
	s_barrier
	v_mfma_f32_16x16x128_f8f6f4 v[94:97], v[18:25], v[202:209], v[94:97]
	v_mfma_f32_16x16x128_f8f6f4 v[90:93], v[26:33], v[202:209], v[90:93]
	v_mfma_f32_16x16x128_f8f6f4 v[82:85], v[26:33], v[210:217], v[82:85]
	v_mfma_f32_16x16x128_f8f6f4 v[86:89], v[18:25], v[210:217], v[86:89]
	v_mfma_f32_16x16x128_f8f6f4 v[78:81], v[18:25], v[218:225], v[78:81]
	v_mfma_f32_16x16x128_f8f6f4 v[74:77], v[26:33], v[218:225], v[74:77]
	v_mfma_f32_16x16x128_f8f6f4 v[66:69], v[26:33], v[226:233], v[66:69]
	v_mfma_f32_16x16x128_f8f6f4 v[70:73], v[18:25], v[226:233], v[70:73]
	s_setprio 0
	s_setprio 1
	v_mfma_f32_16x16x128_f8f6f4 v[38:41], v[2:9], v[226:233], v[38:41]
	v_mfma_f32_16x16x128_f8f6f4 v[34:37], v[180:187], v[226:233], v[34:37]
	v_mfma_f32_16x16x128_f8f6f4 v[42:45], v[180:187], v[218:225], v[42:45]
	v_mfma_f32_16x16x128_f8f6f4 v[46:49], v[2:9], v[218:225], v[46:49]
	v_mfma_f32_16x16x128_f8f6f4 v[54:57], v[2:9], v[210:217], v[54:57]
	v_mfma_f32_16x16x128_f8f6f4 v[50:53], v[180:187], v[210:217], v[50:53]
	v_mfma_f32_16x16x128_f8f6f4 v[58:61], v[180:187], v[202:209], v[58:61]
	v_mfma_f32_16x16x128_f8f6f4 v[62:65], v[2:9], v[202:209], v[62:65]
	s_setprio 0
	s_barrier
	s_add_i32 s62, s62, 2
	s_add_u32 s72, s72, 0x100
	s_addc_u32 s73, s73, 0
	s_add_u32 s8, s8, 0x100
	s_addc_u32 s9, s9, 0
	s_cmp_gt_u32 s62, 29
	s_cbranch_scc0 .LBB0_438
	s_and_b64 vcc, exec, s[6:7]
	s_cbranch_vccz .LBB0_441
	s_barrier

.LBB0_452:
	ds_read_b128 v[146:149], v143
	ds_read_b128 v[150:153], v143 offset:1024
	ds_read_b128 v[154:157], v143 offset:2048
	ds_read_b128 v[158:161], v143 offset:3072
	ds_read_b128 v[162:165], v143 offset:16384
	ds_read_b128 v[166:169], v143 offset:17408
	ds_read_b128 v[170:173], v143 offset:18432
	ds_read_b128 v[174:177], v143 offset:19456
	s_add_u32 s8, s52, 0xfff00080
	s_addc_u32 s9, s53, -1
	s_cmp_eq_u32 s91, 28
	s_cselect_b32 s73, s27, s9
	s_cselect_b32 s72, s37, s8
	s_cselect_b32 s55, s39, s90
	s_cselect_b32 s54, s45, s89
	v_lshl_add_u64 v[140:141], s[52:53], 0, v[136:137]
	s_add_i32 m0, s47, 0xc000
	ds_read_b128 v[180:183], v144
	ds_read_b128 v[184:187], v144 offset:1024
	ds_read_b128 v[188:191], v144 offset:2048
	ds_read_b128 v[192:195], v144 offset:3072
	ds_read_b128 v[196:199], v144 offset:4096
	ds_read_b128 v[200:203], v144 offset:5120
	ds_read_b128 v[204:207], v144 offset:6144
	ds_read_b128 v[208:211], v144 offset:7168
	global_load_lds_dwordx4 v[140:141], off
	v_lshl_add_u64 v[140:141], s[52:53], 0, v[138:139]
	s_add_i32 m0, s47, 0xe000
	s_nop 0
	global_load_lds_dwordx4 v[140:141], off
	s_waitcnt vmcnt(8)
	s_waitcnt lgkmcnt(0)
	s_setprio 1
	s_barrier
	v_mfma_f32_16x16x32_bf16 v[126:129], v[146:149], v[180:183], v[126:129]
	v_mfma_f32_16x16x32_bf16 v[122:125], v[154:157], v[180:183], v[122:125]
	v_mfma_f32_16x16x32_bf16 v[118:121], v[146:149], v[188:191], v[118:121]
	v_mfma_f32_16x16x32_bf16 v[114:117], v[154:157], v[188:191], v[114:117]
	v_mfma_f32_16x16x32_bf16 v[110:113], v[146:149], v[196:199], v[110:113]
	v_mfma_f32_16x16x32_bf16 v[106:109], v[154:157], v[196:199], v[106:109]
	v_mfma_f32_16x16x32_bf16 v[102:105], v[146:149], v[204:207], v[102:105]
	v_mfma_f32_16x16x32_bf16 v[98:101], v[154:157], v[204:207], v[98:101]
	v_mfma_f32_16x16x32_bf16 v[126:129], v[150:153], v[184:187], v[126:129]
	v_mfma_f32_16x16x32_bf16 v[122:125], v[158:161], v[184:187], v[122:125]
	v_mfma_f32_16x16x32_bf16 v[118:121], v[150:153], v[192:195], v[118:121]
	v_mfma_f32_16x16x32_bf16 v[114:117], v[158:161], v[192:195], v[114:117]
	v_mfma_f32_16x16x32_bf16 v[110:113], v[150:153], v[200:203], v[110:113]
	v_mfma_f32_16x16x32_bf16 v[106:109], v[158:161], v[200:203], v[106:109]
	v_mfma_f32_16x16x32_bf16 v[102:105], v[150:153], v[208:211], v[102:105]
	v_mfma_f32_16x16x32_bf16 v[98:101], v[158:161], v[208:211], v[98:101]
	s_setprio 0
	s_setprio 1
	v_mfma_f32_16x16x32_bf16 v[90:93], v[162:165], v[180:183], v[90:93]
	v_mfma_f32_16x16x32_bf16 v[82:85], v[170:173], v[180:183], v[82:85]
	v_mfma_f32_16x16x32_bf16 v[74:77], v[162:165], v[188:191], v[74:77]
	v_mfma_f32_16x16x32_bf16 v[66:69], v[170:173], v[188:191], v[66:69]
	v_mfma_f32_16x16x32_bf16 v[58:61], v[162:165], v[196:199], v[58:61]
	v_mfma_f32_16x16x32_bf16 v[50:53], v[170:173], v[196:199], v[50:53]
	v_mfma_f32_16x16x32_bf16 v[42:45], v[162:165], v[204:207], v[42:45]
	v_mfma_f32_16x16x32_bf16 v[34:37], v[170:173], v[204:207], v[34:37]
	v_mfma_f32_16x16x32_bf16 v[90:93], v[166:169], v[184:187], v[90:93]
	v_mfma_f32_16x16x32_bf16 v[82:85], v[174:177], v[184:187], v[82:85]
	v_mfma_f32_16x16x32_bf16 v[74:77], v[166:169], v[192:195], v[74:77]
	v_mfma_f32_16x16x32_bf16 v[66:69], v[174:177], v[192:195], v[66:69]
	v_mfma_f32_16x16x32_bf16 v[58:61], v[166:169], v[200:203], v[58:61]
	v_mfma_f32_16x16x32_bf16 v[50:53], v[174:177], v[200:203], v[50:53]
	v_mfma_f32_16x16x32_bf16 v[42:45], v[166:169], v[208:211], v[42:45]
	v_mfma_f32_16x16x32_bf16 v[34:37], v[174:177], v[208:211], v[34:37]
	s_setprio 0
	s_barrier
	s_mov_b32 m0, s74
	v_lshl_add_u64 v[140:141], s[54:55], 0, v[132:133]
	s_add_u32 s8, s54, 0x100000
	ds_read_b128 v[180:183], v144 offset:16384
	ds_read_b128 v[184:187], v144 offset:17408
	ds_read_b128 v[188:191], v144 offset:18432
	ds_read_b128 v[192:195], v144 offset:19456
	ds_read_b128 v[196:199], v144 offset:20480
	ds_read_b128 v[200:203], v144 offset:21504
	ds_read_b128 v[204:207], v144 offset:22528
	ds_read_b128 v[208:211], v144 offset:23552
	global_load_lds_dwordx4 v[140:141], off
	v_lshl_add_u64 v[212:213], s[54:55], 0, v[130:131]
	s_mov_b32 m0, s75
	s_addc_u32 s9, s55, 0
	global_load_lds_dwordx4 v[212:213], off
	v_lshl_add_u64 v[214:215], s[8:9], 0, v[132:133]
	s_mov_b32 m0, s76
	v_lshl_add_u64 v[216:217], s[72:73], 0, v[130:131]
	global_load_lds_dwordx4 v[214:215], off
	v_lshl_add_u64 v[214:215], s[8:9], 0, v[130:131]
	s_mov_b32 m0, s77
	s_nop 0
	global_load_lds_dwordx4 v[214:215], off
	v_lshl_add_u64 v[214:215], s[72:73], 0, v[132:133]
	s_mov_b32 m0, s47
	s_nop 0
	global_load_lds_dwordx4 v[214:215], off
	s_mov_b32 m0, s78
	s_nop 0
	global_load_lds_dwordx4 v[216:217], off
	s_waitcnt vmcnt(8)
	s_waitcnt lgkmcnt(0)
	s_setprio 1
	s_barrier
	v_mfma_f32_16x16x32_bf16 v[94:97], v[146:149], v[180:183], v[94:97]
	v_mfma_f32_16x16x32_bf16 v[86:89], v[154:157], v[180:183], v[86:89]
	v_mfma_f32_16x16x32_bf16 v[78:81], v[146:149], v[188:191], v[78:81]
	v_mfma_f32_16x16x32_bf16 v[70:73], v[154:157], v[188:191], v[70:73]
	v_mfma_f32_16x16x32_bf16 v[62:65], v[146:149], v[196:199], v[62:65]
	v_mfma_f32_16x16x32_bf16 v[54:57], v[154:157], v[196:199], v[54:57]
	v_mfma_f32_16x16x32_bf16 v[46:49], v[146:149], v[204:207], v[46:49]
	v_mfma_f32_16x16x32_bf16 v[38:41], v[154:157], v[204:207], v[38:41]
	v_mfma_f32_16x16x32_bf16 v[94:97], v[150:153], v[184:187], v[94:97]
	v_mfma_f32_16x16x32_bf16 v[86:89], v[158:161], v[184:187], v[86:89]
	v_mfma_f32_16x16x32_bf16 v[78:81], v[150:153], v[192:195], v[78:81]
	v_mfma_f32_16x16x32_bf16 v[70:73], v[158:161], v[192:195], v[70:73]
	v_mfma_f32_16x16x32_bf16 v[62:65], v[150:153], v[200:203], v[62:65]
	v_mfma_f32_16x16x32_bf16 v[54:57], v[158:161], v[200:203], v[54:57]
	v_mfma_f32_16x16x32_bf16 v[46:49], v[150:153], v[208:211], v[46:49]
	v_mfma_f32_16x16x32_bf16 v[38:41], v[158:161], v[208:211], v[38:41]
	s_setprio 0
	s_setprio 1
	v_mfma_f32_16x16x32_bf16 v[30:33], v[162:165], v[180:183], v[30:33]
	v_mfma_f32_16x16x32_bf16 v[26:29], v[170:173], v[180:183], v[26:29]
	v_mfma_f32_16x16x32_bf16 v[22:25], v[162:165], v[188:191], v[22:25]
	v_mfma_f32_16x16x32_bf16 v[18:21], v[170:173], v[188:191], v[18:21]
	v_mfma_f32_16x16x32_bf16 v[14:17], v[162:165], v[196:199], v[14:17]
	v_mfma_f32_16x16x32_bf16 v[10:13], v[170:173], v[196:199], v[10:13]
	v_mfma_f32_16x16x32_bf16 v[6:9], v[162:165], v[204:207], v[6:9]
	v_mfma_f32_16x16x32_bf16 v[2:5], v[170:173], v[204:207], v[2:5]
	v_mfma_f32_16x16x32_bf16 v[30:33], v[166:169], v[184:187], v[30:33]
	v_mfma_f32_16x16x32_bf16 v[26:29], v[174:177], v[184:187], v[26:29]
	v_mfma_f32_16x16x32_bf16 v[22:25], v[166:169], v[192:195], v[22:25]
	v_mfma_f32_16x16x32_bf16 v[18:21], v[174:177], v[192:195], v[18:21]
	v_mfma_f32_16x16x32_bf16 v[14:17], v[166:169], v[200:203], v[14:17]
	v_mfma_f32_16x16x32_bf16 v[10:13], v[174:177], v[200:203], v[10:13]
	v_mfma_f32_16x16x32_bf16 v[6:9], v[166:169], v[208:211], v[6:9]
	v_mfma_f32_16x16x32_bf16 v[2:5], v[174:177], v[208:211], v[2:5]
	s_setprio 0
	s_barrier
	ds_read_b128 v[146:149], v143 offset:32768
	ds_read_b128 v[150:153], v143 offset:33792
	ds_read_b128 v[154:157], v143 offset:34816
	ds_read_b128 v[158:161], v143 offset:35840
	ds_read_b128 v[162:165], v143 offset:49152
	ds_read_b128 v[166:169], v143 offset:50176
	ds_read_b128 v[170:173], v143 offset:51200
	ds_read_b128 v[174:177], v143 offset:52224
	s_add_u32 s8, s72, 0x100000
	s_addc_u32 s9, s73, 0
	s_mov_b32 m0, s79
	v_lshl_add_u64 v[218:219], s[8:9], 0, v[132:133]
	ds_read_b128 v[180:183], v144 offset:32768
	ds_read_b128 v[184:187], v144 offset:33792
	ds_read_b128 v[188:191], v144 offset:34816
	ds_read_b128 v[192:195], v144 offset:35840
	ds_read_b128 v[196:199], v144 offset:36864
	ds_read_b128 v[200:203], v144 offset:37888
	ds_read_b128 v[204:207], v144 offset:38912
	ds_read_b128 v[208:211], v144 offset:39936
	global_load_lds_dwordx4 v[218:219], off
	v_lshl_add_u64 v[218:219], s[8:9], 0, v[130:131]
	s_mov_b32 m0, s80
	s_nop 0
	global_load_lds_dwordx4 v[218:219], off
	s_waitcnt vmcnt(8)
	s_waitcnt lgkmcnt(0)
	s_setprio 1
	s_barrier
	v_mfma_f32_16x16x32_bf16 v[126:129], v[146:149], v[180:183], v[126:129]
	v_mfma_f32_16x16x32_bf16 v[122:125], v[154:157], v[180:183], v[122:125]
	v_mfma_f32_16x16x32_bf16 v[118:121], v[146:149], v[188:191], v[118:121]
	v_mfma_f32_16x16x32_bf16 v[114:117], v[154:157], v[188:191], v[114:117]
	v_mfma_f32_16x16x32_bf16 v[110:113], v[146:149], v[196:199], v[110:113]
	v_mfma_f32_16x16x32_bf16 v[106:109], v[154:157], v[196:199], v[106:109]
	v_mfma_f32_16x16x32_bf16 v[102:105], v[146:149], v[204:207], v[102:105]
	v_mfma_f32_16x16x32_bf16 v[98:101], v[154:157], v[204:207], v[98:101]
	v_mfma_f32_16x16x32_bf16 v[126:129], v[150:153], v[184:187], v[126:129]
	v_mfma_f32_16x16x32_bf16 v[122:125], v[158:161], v[184:187], v[122:125]
	v_mfma_f32_16x16x32_bf16 v[118:121], v[150:153], v[192:195], v[118:121]
	v_mfma_f32_16x16x32_bf16 v[114:117], v[158:161], v[192:195], v[114:117]
	v_mfma_f32_16x16x32_bf16 v[110:113], v[150:153], v[200:203], v[110:113]
	v_mfma_f32_16x16x32_bf16 v[106:109], v[158:161], v[200:203], v[106:109]
	v_mfma_f32_16x16x32_bf16 v[102:105], v[150:153], v[208:211], v[102:105]
	v_mfma_f32_16x16x32_bf16 v[98:101], v[158:161], v[208:211], v[98:101]
	s_setprio 0
	s_setprio 1
	v_mfma_f32_16x16x32_bf16 v[90:93], v[162:165], v[180:183], v[90:93]
	v_mfma_f32_16x16x32_bf16 v[82:85], v[170:173], v[180:183], v[82:85]
	v_mfma_f32_16x16x32_bf16 v[74:77], v[162:165], v[188:191], v[74:77]
	v_mfma_f32_16x16x32_bf16 v[66:69], v[170:173], v[188:191], v[66:69]
	v_mfma_f32_16x16x32_bf16 v[58:61], v[162:165], v[196:199], v[58:61]
	v_mfma_f32_16x16x32_bf16 v[50:53], v[170:173], v[196:199], v[50:53]
	v_mfma_f32_16x16x32_bf16 v[42:45], v[162:165], v[204:207], v[42:45]
	v_mfma_f32_16x16x32_bf16 v[34:37], v[170:173], v[204:207], v[34:37]
	v_mfma_f32_16x16x32_bf16 v[90:93], v[166:169], v[184:187], v[90:93]
	v_mfma_f32_16x16x32_bf16 v[82:85], v[174:177], v[184:187], v[82:85]
	v_mfma_f32_16x16x32_bf16 v[74:77], v[166:169], v[192:195], v[74:77]
	v_mfma_f32_16x16x32_bf16 v[66:69], v[174:177], v[192:195], v[66:69]
	v_mfma_f32_16x16x32_bf16 v[58:61], v[166:169], v[200:203], v[58:61]
	v_mfma_f32_16x16x32_bf16 v[50:53], v[174:177], v[200:203], v[50:53]
	v_mfma_f32_16x16x32_bf16 v[42:45], v[166:169], v[208:211], v[42:45]
	v_mfma_f32_16x16x32_bf16 v[34:37], v[174:177], v[208:211], v[34:37]
	s_setprio 0
	s_barrier
	s_mov_b32 m0, s81
	v_lshl_add_u64 v[140:141], v[140:141], 0, s[4:5]
	s_add_u32 s8, s54, 0x100080
	ds_read_b128 v[180:183], v144 offset:49152
	ds_read_b128 v[184:187], v144 offset:50176
	ds_read_b128 v[188:191], v144 offset:51200
	ds_read_b128 v[192:195], v144 offset:52224
	ds_read_b128 v[196:199], v144 offset:53248
	ds_read_b128 v[200:203], v144 offset:54272
	ds_read_b128 v[204:207], v144 offset:55296
	ds_read_b128 v[208:211], v144 offset:56320
	global_load_lds_dwordx4 v[140:141], off
	v_lshl_add_u64 v[140:141], v[212:213], 0, s[4:5]
	s_mov_b32 m0, s82
	s_addc_u32 s9, s55, 0
	global_load_lds_dwordx4 v[140:141], off
	v_lshl_add_u64 v[140:141], s[8:9], 0, v[132:133]
	s_mov_b32 m0, s85
	s_nop 0
	global_load_lds_dwordx4 v[140:141], off
	v_lshl_add_u64 v[140:141], s[8:9], 0, v[130:131]
	s_mov_b32 m0, s86
	s_nop 0
	global_load_lds_dwordx4 v[140:141], off
	v_lshl_add_u64 v[140:141], v[214:215], 0, s[4:5]
	s_mov_b32 m0, s83
	s_nop 0
	global_load_lds_dwordx4 v[140:141], off
	v_lshl_add_u64 v[140:141], v[216:217], 0, s[4:5]
	s_mov_b32 m0, s84
	s_nop 0
	global_load_lds_dwordx4 v[140:141], off
	s_waitcnt vmcnt(8)
	s_waitcnt lgkmcnt(0)
	s_setprio 1
	s_barrier
	v_mfma_f32_16x16x32_bf16 v[94:97], v[146:149], v[180:183], v[94:97]
	v_mfma_f32_16x16x32_bf16 v[86:89], v[154:157], v[180:183], v[86:89]
	v_mfma_f32_16x16x32_bf16 v[78:81], v[146:149], v[188:191], v[78:81]
	v_mfma_f32_16x16x32_bf16 v[70:73], v[154:157], v[188:191], v[70:73]
	v_mfma_f32_16x16x32_bf16 v[62:65], v[146:149], v[196:199], v[62:65]
	v_mfma_f32_16x16x32_bf16 v[54:57], v[154:157], v[196:199], v[54:57]
	v_mfma_f32_16x16x32_bf16 v[46:49], v[146:149], v[204:207], v[46:49]
	v_mfma_f32_16x16x32_bf16 v[38:41], v[154:157], v[204:207], v[38:41]
	v_mfma_f32_16x16x32_bf16 v[94:97], v[150:153], v[184:187], v[94:97]
	v_mfma_f32_16x16x32_bf16 v[86:89], v[158:161], v[184:187], v[86:89]
	v_mfma_f32_16x16x32_bf16 v[78:81], v[150:153], v[192:195], v[78:81]
	v_mfma_f32_16x16x32_bf16 v[70:73], v[158:161], v[192:195], v[70:73]
	v_mfma_f32_16x16x32_bf16 v[62:65], v[150:153], v[200:203], v[62:65]
	v_mfma_f32_16x16x32_bf16 v[54:57], v[158:161], v[200:203], v[54:57]
	v_mfma_f32_16x16x32_bf16 v[46:49], v[150:153], v[208:211], v[46:49]
	v_mfma_f32_16x16x32_bf16 v[38:41], v[158:161], v[208:211], v[38:41]
	s_setprio 0
	s_setprio 1
	v_mfma_f32_16x16x32_bf16 v[30:33], v[162:165], v[180:183], v[30:33]
	v_mfma_f32_16x16x32_bf16 v[26:29], v[170:173], v[180:183], v[26:29]
	v_mfma_f32_16x16x32_bf16 v[22:25], v[162:165], v[188:191], v[22:25]
	v_mfma_f32_16x16x32_bf16 v[18:21], v[170:173], v[188:191], v[18:21]
	v_mfma_f32_16x16x32_bf16 v[14:17], v[162:165], v[196:199], v[14:17]
	v_mfma_f32_16x16x32_bf16 v[10:13], v[170:173], v[196:199], v[10:13]
	v_mfma_f32_16x16x32_bf16 v[6:9], v[162:165], v[204:207], v[6:9]
	v_mfma_f32_16x16x32_bf16 v[2:5], v[170:173], v[204:207], v[2:5]
	v_mfma_f32_16x16x32_bf16 v[30:33], v[166:169], v[184:187], v[30:33]
	v_mfma_f32_16x16x32_bf16 v[26:29], v[174:177], v[184:187], v[26:29]
	v_mfma_f32_16x16x32_bf16 v[22:25], v[166:169], v[192:195], v[22:25]
	v_mfma_f32_16x16x32_bf16 v[18:21], v[174:177], v[192:195], v[18:21]
	v_mfma_f32_16x16x32_bf16 v[14:17], v[166:169], v[200:203], v[14:17]
	v_mfma_f32_16x16x32_bf16 v[10:13], v[174:177], v[200:203], v[10:13]
	v_mfma_f32_16x16x32_bf16 v[6:9], v[166:169], v[208:211], v[6:9]
	v_mfma_f32_16x16x32_bf16 v[2:5], v[174:177], v[208:211], v[2:5]
	s_setprio 0
	s_barrier
	s_add_i32 s91, s91, 2
	s_add_u32 s52, s52, 0x100
	s_addc_u32 s53, s53, 0
	s_add_u32 s89, s89, 0x100
	s_addc_u32 s90, s90, 0
	s_cmp_gt_u32 s91, 29
	s_cbranch_scc0 .LBB0_452
	s_and_b64 vcc, exec, s[6:7]
	s_cbranch_vccz .LBB0_455
	s_barrier

.LBB0_600:
	s_ashr_i32 s55, s54, 31
	ds_read_b128 v[18:21], v200
	ds_read_b128 v[22:25], v200 offset:1024
	ds_read_b128 v[26:29], v200 offset:2048
	ds_read_b128 v[30:33], v200 offset:3072
	ds_read_b128 v[2:5], v200 offset:16384
	ds_read_b128 v[6:9], v200 offset:17408
	ds_read_b128 v[10:13], v200 offset:18432
	ds_read_b128 v[14:17], v200 offset:19456
	s_lshl_b64 s[4:5], s[54:55], 18
	s_add_u32 s72, s38, s4
	s_addc_u32 s73, s39, s5
	s_and_b64 s[4:5], s[2:3], exec
	s_cselect_b32 s4, s73, s81
	s_cselect_b32 s5, s72, s80
	s_ashr_i32 s53, s52, 31
	s_lshl_b64 s[8:9], s[52:53], 18
	s_add_u32 s74, s94, s8
	v_readlane_b32 s8, v254, 6
	s_addc_u32 s75, s8, s9
	s_and_b64 s[8:9], s[2:3], exec
	s_cselect_b32 s53, s75, s79
	s_cselect_b32 s55, s74, s78
	s_add_u32 s8, s80, 0x20080
	s_addc_u32 s9, s81, 0
	s_mov_b32 m0, s96
	v_lshl_add_u64 v[226:227], s[8:9], 0, v[162:163]
	ds_read_b128 v[182:185], v201
	ds_read_b128 v[186:189], v201 offset:1024
	ds_read_b128 v[202:205], v201 offset:2048
	ds_read_b128 v[206:209], v201 offset:3072
	ds_read_b128 v[210:213], v201 offset:4096
	ds_read_b128 v[214:217], v201 offset:5120
	ds_read_b128 v[218:221], v201 offset:6144
	ds_read_b128 v[222:225], v201 offset:7168
	global_load_lds_dwordx4 v[226:227], off
	v_lshl_add_u64 v[226:227], s[8:9], 0, v[166:167]
	s_mov_b32 m0, s61
	s_nop 0
	global_load_lds_dwordx4 v[226:227], off
	s_waitcnt vmcnt(8)
	s_waitcnt lgkmcnt(0)
	s_setprio 1
	s_barrier
	v_mfma_f32_16x16x128_f8f6f4 v[158:161], v[18:25], v[182:189], 0
	v_mfma_f32_16x16x128_f8f6f4 v[154:157], v[26:33], v[182:189], 0
	v_mfma_f32_16x16x128_f8f6f4 v[146:149], v[26:33], v[202:209], 0
	v_mfma_f32_16x16x128_f8f6f4 v[150:153], v[18:25], v[202:209], 0
	v_mfma_f32_16x16x128_f8f6f4 v[142:145], v[18:25], v[210:217], 0
	v_mfma_f32_16x16x128_f8f6f4 v[138:141], v[26:33], v[210:217], 0
	v_mfma_f32_16x16x128_f8f6f4 v[130:133], v[26:33], v[218:225], 0
	v_mfma_f32_16x16x128_f8f6f4 v[134:137], v[18:25], v[218:225], 0
	s_setprio 0
	s_setprio 1
	v_mfma_f32_16x16x128_f8f6f4 v[102:105], v[2:9], v[218:225], 0
	v_mfma_f32_16x16x128_f8f6f4 v[98:101], v[10:17], v[218:225], 0
	v_mfma_f32_16x16x128_f8f6f4 v[106:109], v[10:17], v[210:217], 0
	v_mfma_f32_16x16x128_f8f6f4 v[110:113], v[2:9], v[210:217], 0
	v_mfma_f32_16x16x128_f8f6f4 v[118:121], v[2:9], v[202:209], 0
	v_mfma_f32_16x16x128_f8f6f4 v[114:117], v[10:17], v[202:209], 0
	v_mfma_f32_16x16x128_f8f6f4 v[122:125], v[10:17], v[182:189], 0
	v_mfma_f32_16x16x128_f8f6f4 v[126:129], v[2:9], v[182:189], 0
	s_setprio 0
	s_barrier
	v_lshl_add_u64 v[182:183], s[78:79], 0, v[164:165]
	s_mov_b32 m0, s68
	v_lshl_add_u64 v[184:185], v[182:183], 0, s[46:47]
	ds_read_b128 v[202:205], v201 offset:16384
	ds_read_b128 v[206:209], v201 offset:17408
	ds_read_b128 v[210:213], v201 offset:18432
	ds_read_b128 v[214:217], v201 offset:19456
	ds_read_b128 v[218:221], v201 offset:20480
	ds_read_b128 v[222:225], v201 offset:21504
	ds_read_b128 v[226:229], v201 offset:22528
	ds_read_b128 v[230:233], v201 offset:23552
	global_load_lds_dwordx4 v[184:185], off
	v_lshl_add_u64 v[184:185], s[78:79], 0, v[168:169]
	s_add_u32 s8, s78, 0x20100
	v_lshl_add_u64 v[186:187], v[184:185], 0, s[46:47]
	s_mov_b32 m0, s69
	s_addc_u32 s9, s79, 0
	global_load_lds_dwordx4 v[186:187], off
	v_lshl_add_u64 v[186:187], s[8:9], 0, v[164:165]
	s_mov_b32 m0, s77
	s_nop 0
	global_load_lds_dwordx4 v[186:187], off
	v_lshl_add_u64 v[186:187], s[8:9], 0, v[168:169]
	s_mov_b32 m0, s84
	s_nop 0
	global_load_lds_dwordx4 v[186:187], off
	v_lshl_add_u64 v[186:187], s[80:81], 0, v[162:163]
	v_lshl_add_u64 v[188:189], v[186:187], 0, s[46:47]
	s_mov_b32 m0, s33
	s_nop 0
	global_load_lds_dwordx4 v[188:189], off
	v_lshl_add_u64 v[188:189], s[80:81], 0, v[166:167]
	v_lshl_add_u64 v[234:235], v[188:189], 0, s[46:47]
	s_mov_b32 m0, s85
	s_nop 0
	global_load_lds_dwordx4 v[234:235], off
	s_waitcnt vmcnt(8)
	s_waitcnt lgkmcnt(0)
	s_setprio 1
	s_barrier
	v_mfma_f32_16x16x128_f8f6f4 v[94:97], v[18:25], v[202:209], 0
	v_mfma_f32_16x16x128_f8f6f4 v[90:93], v[26:33], v[202:209], 0
	v_mfma_f32_16x16x128_f8f6f4 v[82:85], v[26:33], v[210:217], 0
	v_mfma_f32_16x16x128_f8f6f4 v[86:89], v[18:25], v[210:217], 0
	v_mfma_f32_16x16x128_f8f6f4 v[78:81], v[18:25], v[218:225], 0
	v_mfma_f32_16x16x128_f8f6f4 v[74:77], v[26:33], v[218:225], 0
	v_mfma_f32_16x16x128_f8f6f4 v[66:69], v[26:33], v[226:233], 0
	v_mfma_f32_16x16x128_f8f6f4 v[70:73], v[18:25], v[226:233], 0
	s_setprio 0
	s_setprio 1
	v_mfma_f32_16x16x128_f8f6f4 v[38:41], v[2:9], v[226:233], 0
	v_mfma_f32_16x16x128_f8f6f4 v[34:37], v[10:17], v[226:233], 0
	v_mfma_f32_16x16x128_f8f6f4 v[42:45], v[10:17], v[218:225], 0
	v_mfma_f32_16x16x128_f8f6f4 v[46:49], v[2:9], v[218:225], 0
	v_mfma_f32_16x16x128_f8f6f4 v[54:57], v[2:9], v[210:217], 0
	v_mfma_f32_16x16x128_f8f6f4 v[50:53], v[10:17], v[210:217], 0
	v_mfma_f32_16x16x128_f8f6f4 v[58:61], v[10:17], v[202:209], 0
	v_mfma_f32_16x16x128_f8f6f4 v[62:65], v[2:9], v[202:209], 0
	s_setprio 0
	s_barrier
	ds_read_b128 v[18:21], v200 offset:32768
	ds_read_b128 v[22:25], v200 offset:33792
	ds_read_b128 v[26:29], v200 offset:34816
	ds_read_b128 v[30:33], v200 offset:35840
	ds_read_b128 v[2:5], v200 offset:49152
	ds_read_b128 v[6:9], v200 offset:50176
	ds_read_b128 v[10:13], v200 offset:51200
	ds_read_b128 v[14:17], v200 offset:52224
	s_add_u32 s8, s80, 0x20100
	s_addc_u32 s9, s81, 0
	s_mov_b32 m0, s86
	v_lshl_add_u64 v[234:235], s[8:9], 0, v[162:163]
	ds_read_b128 v[202:205], v201 offset:32768
	ds_read_b128 v[206:209], v201 offset:33792
	ds_read_b128 v[210:213], v201 offset:34816
	ds_read_b128 v[214:217], v201 offset:35840
	ds_read_b128 v[218:221], v201 offset:36864
	ds_read_b128 v[222:225], v201 offset:37888
	ds_read_b128 v[226:229], v201 offset:38912
	ds_read_b128 v[230:233], v201 offset:39936
	global_load_lds_dwordx4 v[234:235], off
	v_lshl_add_u64 v[234:235], s[8:9], 0, v[166:167]
	s_mov_b32 m0, s87
	s_nop 0
	global_load_lds_dwordx4 v[234:235], off
	s_waitcnt vmcnt(8)
	s_waitcnt lgkmcnt(0)
	s_setprio 1
	s_barrier
	v_mfma_f32_16x16x128_f8f6f4 v[158:161], v[18:25], v[202:209], v[158:161]
	v_mfma_f32_16x16x128_f8f6f4 v[154:157], v[26:33], v[202:209], v[154:157]
	v_mfma_f32_16x16x128_f8f6f4 v[146:149], v[26:33], v[210:217], v[146:149]
	v_mfma_f32_16x16x128_f8f6f4 v[150:153], v[18:25], v[210:217], v[150:153]
	v_mfma_f32_16x16x128_f8f6f4 v[142:145], v[18:25], v[218:225], v[142:145]
	v_mfma_f32_16x16x128_f8f6f4 v[138:141], v[26:33], v[218:225], v[138:141]
	v_mfma_f32_16x16x128_f8f6f4 v[130:133], v[26:33], v[226:233], v[130:133]
	v_mfma_f32_16x16x128_f8f6f4 v[134:137], v[18:25], v[226:233], v[134:137]
	s_setprio 0
	s_setprio 1
	v_mfma_f32_16x16x128_f8f6f4 v[102:105], v[2:9], v[226:233], v[102:105]
	v_mfma_f32_16x16x128_f8f6f4 v[98:101], v[10:17], v[226:233], v[98:101]
	v_mfma_f32_16x16x128_f8f6f4 v[106:109], v[10:17], v[218:225], v[106:109]
	v_mfma_f32_16x16x128_f8f6f4 v[110:113], v[2:9], v[218:225], v[110:113]
	v_mfma_f32_16x16x128_f8f6f4 v[118:121], v[2:9], v[210:217], v[118:121]
	v_mfma_f32_16x16x128_f8f6f4 v[114:117], v[10:17], v[210:217], v[114:117]
	v_mfma_f32_16x16x128_f8f6f4 v[122:125], v[10:17], v[202:209], v[122:125]
	v_mfma_f32_16x16x128_f8f6f4 v[126:129], v[2:9], v[202:209], v[126:129]
	s_setprio 0
	s_barrier
	s_mov_b32 m0, s89
	v_lshl_add_u64 v[182:183], v[182:183], 0, s[48:49]
	s_add_u32 s8, s78, 0x20180
	ds_read_b128 v[202:205], v201 offset:49152
	ds_read_b128 v[206:209], v201 offset:50176
	ds_read_b128 v[210:213], v201 offset:51200
	ds_read_b128 v[214:217], v201 offset:52224
	ds_read_b128 v[218:221], v201 offset:53248
	ds_read_b128 v[222:225], v201 offset:54272
	ds_read_b128 v[226:229], v201 offset:55296
	ds_read_b128 v[230:233], v201 offset:56320
	global_load_lds_dwordx4 v[182:183], off
	v_lshl_add_u64 v[182:183], v[184:185], 0, s[48:49]
	s_mov_b32 m0, s90
	s_addc_u32 s9, s79, 0
	global_load_lds_dwordx4 v[182:183], off
	v_lshl_add_u64 v[182:183], s[8:9], 0, v[164:165]
	s_mov_b32 m0, s93
	s_nop 0
	global_load_lds_dwordx4 v[182:183], off
	v_lshl_add_u64 v[182:183], s[8:9], 0, v[168:169]
	s_mov_b32 m0, s95
	s_nop 0
	global_load_lds_dwordx4 v[182:183], off
	v_lshl_add_u64 v[182:183], v[186:187], 0, s[48:49]
	s_mov_b32 m0, s91
	s_nop 0
	global_load_lds_dwordx4 v[182:183], off
	v_lshl_add_u64 v[182:183], v[188:189], 0, s[48:49]
	s_mov_b32 m0, s92
	s_nop 0
	global_load_lds_dwordx4 v[182:183], off
	s_waitcnt vmcnt(8)
	s_waitcnt lgkmcnt(0)
	s_setprio 1
	s_barrier
	v_mfma_f32_16x16x128_f8f6f4 v[94:97], v[18:25], v[202:209], v[94:97]
	v_mfma_f32_16x16x128_f8f6f4 v[90:93], v[26:33], v[202:209], v[90:93]
	v_mfma_f32_16x16x128_f8f6f4 v[82:85], v[26:33], v[210:217], v[82:85]
	v_mfma_f32_16x16x128_f8f6f4 v[86:89], v[18:25], v[210:217], v[86:89]
	v_mfma_f32_16x16x128_f8f6f4 v[78:81], v[18:25], v[218:225], v[78:81]
	v_mfma_f32_16x16x128_f8f6f4 v[74:77], v[26:33], v[218:225], v[74:77]
	v_mfma_f32_16x16x128_f8f6f4 v[66:69], v[26:33], v[226:233], v[66:69]
	v_mfma_f32_16x16x128_f8f6f4 v[70:73], v[18:25], v[226:233], v[70:73]
	s_setprio 0
	s_setprio 1
	v_mfma_f32_16x16x128_f8f6f4 v[38:41], v[2:9], v[226:233], v[38:41]
	v_mfma_f32_16x16x128_f8f6f4 v[34:37], v[10:17], v[226:233], v[34:37]
	v_mfma_f32_16x16x128_f8f6f4 v[42:45], v[10:17], v[218:225], v[42:45]
	v_mfma_f32_16x16x128_f8f6f4 v[46:49], v[2:9], v[218:225], v[46:49]
	v_mfma_f32_16x16x128_f8f6f4 v[54:57], v[2:9], v[210:217], v[54:57]
	v_mfma_f32_16x16x128_f8f6f4 v[50:53], v[10:17], v[210:217], v[50:53]
	v_mfma_f32_16x16x128_f8f6f4 v[58:61], v[10:17], v[202:209], v[58:61]
	v_mfma_f32_16x16x128_f8f6f4 v[62:65], v[2:9], v[202:209], v[62:65]
	s_setprio 0
	s_barrier
	s_add_u32 s80, s80, 0x20180
	s_addc_u32 s81, s81, 0
	s_add_u32 s8, s78, 0x200
	s_addc_u32 s9, s79, 0
	s_mov_b32 s62, 0
.LBB0_601:
	ds_read_b128 v[2:5], v200
	ds_read_b128 v[6:9], v200 offset:1024
	ds_read_b128 v[18:21], v200 offset:2048
	ds_read_b128 v[22:25], v200 offset:3072
	ds_read_b128 v[26:29], v200 offset:16384
	ds_read_b128 v[30:33], v200 offset:17408
	ds_read_b128 v[182:185], v200 offset:18432
	ds_read_b128 v[186:189], v200 offset:19456
	s_add_u32 s63, s80, 0xfffe0080
	s_addc_u32 s71, s81, -1
	s_cmp_eq_u32 s62, 4
	s_cselect_b32 s83, s4, s71
	s_cselect_b32 s82, s5, s63
	s_cselect_b32 s79, s53, s9
	s_cselect_b32 s78, s55, s8
	s_mov_b32 m0, s96
	v_lshl_add_u64 v[226:227], s[80:81], 0, v[170:171]
	ds_read_b128 v[10:13], v201
	ds_read_b128 v[14:17], v201 offset:1024
	ds_read_b128 v[202:205], v201 offset:2048
	ds_read_b128 v[206:209], v201 offset:3072
	ds_read_b128 v[210:213], v201 offset:4096
	ds_read_b128 v[214:217], v201 offset:5120
	ds_read_b128 v[218:221], v201 offset:6144
	ds_read_b128 v[222:225], v201 offset:7168
	global_load_lds_dwordx4 v[226:227], off
	v_lshl_add_u64 v[226:227], s[80:81], 0, v[172:173]
	s_mov_b32 m0, s61
	s_nop 0
	global_load_lds_dwordx4 v[226:227], off
	s_waitcnt vmcnt(8)
	s_waitcnt lgkmcnt(0)
	s_setprio 1
	s_barrier
	v_mfma_f32_16x16x128_f8f6f4 v[158:161], v[2:9], v[10:17], v[158:161]
	v_mfma_f32_16x16x128_f8f6f4 v[154:157], v[18:25], v[10:17], v[154:157]
	v_mfma_f32_16x16x128_f8f6f4 v[146:149], v[18:25], v[202:209], v[146:149]
	v_mfma_f32_16x16x128_f8f6f4 v[150:153], v[2:9], v[202:209], v[150:153]
	v_mfma_f32_16x16x128_f8f6f4 v[142:145], v[2:9], v[210:217], v[142:145]
	v_mfma_f32_16x16x128_f8f6f4 v[138:141], v[18:25], v[210:217], v[138:141]
	v_mfma_f32_16x16x128_f8f6f4 v[130:133], v[18:25], v[218:225], v[130:133]
	v_mfma_f32_16x16x128_f8f6f4 v[134:137], v[2:9], v[218:225], v[134:137]
	s_setprio 0
	s_setprio 1
	v_mfma_f32_16x16x128_f8f6f4 v[102:105], v[26:33], v[218:225], v[102:105]
	v_mfma_f32_16x16x128_f8f6f4 v[98:101], v[182:189], v[218:225], v[98:101]
	v_mfma_f32_16x16x128_f8f6f4 v[106:109], v[182:189], v[210:217], v[106:109]
	v_mfma_f32_16x16x128_f8f6f4 v[110:113], v[26:33], v[210:217], v[110:113]
	v_mfma_f32_16x16x128_f8f6f4 v[118:121], v[26:33], v[202:209], v[118:121]
	v_mfma_f32_16x16x128_f8f6f4 v[114:117], v[182:189], v[202:209], v[114:117]
	v_mfma_f32_16x16x128_f8f6f4 v[122:125], v[182:189], v[10:17], v[122:125]
	v_mfma_f32_16x16x128_f8f6f4 v[126:129], v[26:33], v[10:17], v[126:129]
	s_setprio 0
	s_barrier
	s_mov_b32 m0, s68
	v_lshl_add_u64 v[10:11], s[78:79], 0, v[164:165]
	s_add_u32 vcc_lo, s78, 0x20000
	ds_read_b128 v[202:205], v201 offset:16384
	ds_read_b128 v[206:209], v201 offset:17408
	ds_read_b128 v[210:213], v201 offset:18432
	ds_read_b128 v[214:217], v201 offset:19456
	ds_read_b128 v[218:221], v201 offset:20480
	ds_read_b128 v[222:225], v201 offset:21504
	ds_read_b128 v[226:229], v201 offset:22528
	ds_read_b128 v[230:233], v201 offset:23552
	global_load_lds_dwordx4 v[10:11], off
	v_lshl_add_u64 v[12:13], s[78:79], 0, v[168:169]
	s_mov_b32 m0, s69
	s_addc_u32 vcc_hi, s79, 0
	global_load_lds_dwordx4 v[12:13], off
	v_lshl_add_u64 v[14:15], vcc, 0, v[164:165]
	s_mov_b32 m0, s77
	v_lshl_add_u64 v[16:17], s[82:83], 0, v[166:167]
	global_load_lds_dwordx4 v[14:15], off
	v_lshl_add_u64 v[14:15], vcc, 0, v[168:169]
	s_mov_b32 m0, s84
	s_nop 0
	global_load_lds_dwordx4 v[14:15], off
	v_lshl_add_u64 v[14:15], s[82:83], 0, v[162:163]
	s_mov_b32 m0, s33
	s_nop 0
	global_load_lds_dwordx4 v[14:15], off
	s_mov_b32 m0, s85
	s_nop 0
	global_load_lds_dwordx4 v[16:17], off
	s_waitcnt vmcnt(8)
	s_waitcnt lgkmcnt(0)
	s_setprio 1
	s_barrier
	v_mfma_f32_16x16x128_f8f6f4 v[94:97], v[2:9], v[202:209], v[94:97]
	v_mfma_f32_16x16x128_f8f6f4 v[90:93], v[18:25], v[202:209], v[90:93]
	v_mfma_f32_16x16x128_f8f6f4 v[82:85], v[18:25], v[210:217], v[82:85]
	v_mfma_f32_16x16x128_f8f6f4 v[86:89], v[2:9], v[210:217], v[86:89]
	v_mfma_f32_16x16x128_f8f6f4 v[78:81], v[2:9], v[218:225], v[78:81]
	v_mfma_f32_16x16x128_f8f6f4 v[74:77], v[18:25], v[218:225], v[74:77]
	v_mfma_f32_16x16x128_f8f6f4 v[66:69], v[18:25], v[226:233], v[66:69]
	v_mfma_f32_16x16x128_f8f6f4 v[70:73], v[2:9], v[226:233], v[70:73]
	s_setprio 0
	s_setprio 1
	v_mfma_f32_16x16x128_f8f6f4 v[38:41], v[26:33], v[226:233], v[38:41]
	v_mfma_f32_16x16x128_f8f6f4 v[34:37], v[182:189], v[226:233], v[34:37]
	v_mfma_f32_16x16x128_f8f6f4 v[42:45], v[182:189], v[218:225], v[42:45]
	v_mfma_f32_16x16x128_f8f6f4 v[46:49], v[26:33], v[218:225], v[46:49]
	v_mfma_f32_16x16x128_f8f6f4 v[54:57], v[26:33], v[210:217], v[54:57]
	v_mfma_f32_16x16x128_f8f6f4 v[50:53], v[182:189], v[210:217], v[50:53]
	v_mfma_f32_16x16x128_f8f6f4 v[58:61], v[182:189], v[202:209], v[58:61]
	v_mfma_f32_16x16x128_f8f6f4 v[62:65], v[26:33], v[202:209], v[62:65]
	s_setprio 0
	s_barrier
	ds_read_b128 v[18:21], v200 offset:32768
	ds_read_b128 v[22:25], v200 offset:33792
	ds_read_b128 v[26:29], v200 offset:34816
	ds_read_b128 v[30:33], v200 offset:35840
	ds_read_b128 v[2:5], v200 offset:49152
	ds_read_b128 v[6:9], v200 offset:50176
	ds_read_b128 v[182:185], v200 offset:51200
	ds_read_b128 v[186:189], v200 offset:52224
	s_add_u32 s82, s82, 0x20000
	s_addc_u32 s83, s83, 0
	s_mov_b32 m0, s86
	v_lshl_add_u64 v[234:235], s[82:83], 0, v[162:163]
	ds_read_b128 v[202:205], v201 offset:32768
	ds_read_b128 v[206:209], v201 offset:33792
	ds_read_b128 v[210:213], v201 offset:34816
	ds_read_b128 v[214:217], v201 offset:35840
	ds_read_b128 v[218:221], v201 offset:36864
	ds_read_b128 v[222:225], v201 offset:37888
	ds_read_b128 v[226:229], v201 offset:38912
	ds_read_b128 v[230:233], v201 offset:39936
	global_load_lds_dwordx4 v[234:235], off
	v_lshl_add_u64 v[234:235], s[82:83], 0, v[166:167]
	s_mov_b32 m0, s87
	s_nop 0
	global_load_lds_dwordx4 v[234:235], off
	s_waitcnt vmcnt(8)
	s_waitcnt lgkmcnt(0)
	s_setprio 1
	s_barrier
	v_mfma_f32_16x16x128_f8f6f4 v[158:161], v[18:25], v[202:209], v[158:161]
	v_mfma_f32_16x16x128_f8f6f4 v[154:157], v[26:33], v[202:209], v[154:157]
	v_mfma_f32_16x16x128_f8f6f4 v[146:149], v[26:33], v[210:217], v[146:149]
	v_mfma_f32_16x16x128_f8f6f4 v[150:153], v[18:25], v[210:217], v[150:153]
	v_mfma_f32_16x16x128_f8f6f4 v[142:145], v[18:25], v[218:225], v[142:145]
	v_mfma_f32_16x16x128_f8f6f4 v[138:141], v[26:33], v[218:225], v[138:141]
	v_mfma_f32_16x16x128_f8f6f4 v[130:133], v[26:33], v[226:233], v[130:133]
	v_mfma_f32_16x16x128_f8f6f4 v[134:137], v[18:25], v[226:233], v[134:137]
	s_setprio 0
	s_setprio 1
	v_mfma_f32_16x16x128_f8f6f4 v[102:105], v[2:9], v[226:233], v[102:105]
	v_mfma_f32_16x16x128_f8f6f4 v[98:101], v[182:189], v[226:233], v[98:101]
	v_mfma_f32_16x16x128_f8f6f4 v[106:109], v[182:189], v[218:225], v[106:109]
	v_mfma_f32_16x16x128_f8f6f4 v[110:113], v[2:9], v[218:225], v[110:113]
	v_mfma_f32_16x16x128_f8f6f4 v[118:121], v[2:9], v[210:217], v[118:121]
	v_mfma_f32_16x16x128_f8f6f4 v[114:117], v[182:189], v[210:217], v[114:117]
	v_mfma_f32_16x16x128_f8f6f4 v[122:125], v[182:189], v[202:209], v[122:125]
	v_mfma_f32_16x16x128_f8f6f4 v[126:129], v[2:9], v[202:209], v[126:129]
	s_setprio 0
	s_barrier
	s_mov_b32 m0, s89
	v_lshl_add_u64 v[10:11], v[10:11], 0, s[42:43]
	s_add_u32 s78, s78, 0x20080
	ds_read_b128 v[202:205], v201 offset:49152
	ds_read_b128 v[206:209], v201 offset:50176
	ds_read_b128 v[210:213], v201 offset:51200
	ds_read_b128 v[214:217], v201 offset:52224
	ds_read_b128 v[218:221], v201 offset:53248
	ds_read_b128 v[222:225], v201 offset:54272
	ds_read_b128 v[226:229], v201 offset:55296
	ds_read_b128 v[230:233], v201 offset:56320
	global_load_lds_dwordx4 v[10:11], off
	v_lshl_add_u64 v[10:11], v[12:13], 0, s[42:43]
	s_mov_b32 m0, s90
	s_addc_u32 s79, s79, 0
	global_load_lds_dwordx4 v[10:11], off
	v_lshl_add_u64 v[10:11], s[78:79], 0, v[164:165]
	s_mov_b32 m0, s93
	s_nop 0
	global_load_lds_dwordx4 v[10:11], off
	v_lshl_add_u64 v[10:11], s[78:79], 0, v[168:169]
	s_mov_b32 m0, s95
	s_nop 0
	global_load_lds_dwordx4 v[10:11], off
	v_lshl_add_u64 v[10:11], v[14:15], 0, s[42:43]
	s_mov_b32 m0, s91
	s_nop 0
	global_load_lds_dwordx4 v[10:11], off
	v_lshl_add_u64 v[10:11], v[16:17], 0, s[42:43]
	s_mov_b32 m0, s92
	s_nop 0
	global_load_lds_dwordx4 v[10:11], off
	s_waitcnt vmcnt(8)
	s_waitcnt lgkmcnt(0)
	s_setprio 1
	s_barrier
	v_mfma_f32_16x16x128_f8f6f4 v[94:97], v[18:25], v[202:209], v[94:97]
	v_mfma_f32_16x16x128_f8f6f4 v[90:93], v[26:33], v[202:209], v[90:93]
	v_mfma_f32_16x16x128_f8f6f4 v[82:85], v[26:33], v[210:217], v[82:85]
	v_mfma_f32_16x16x128_f8f6f4 v[86:89], v[18:25], v[210:217], v[86:89]
	v_mfma_f32_16x16x128_f8f6f4 v[78:81], v[18:25], v[218:225], v[78:81]
	v_mfma_f32_16x16x128_f8f6f4 v[74:77], v[26:33], v[218:225], v[74:77]
	v_mfma_f32_16x16x128_f8f6f4 v[66:69], v[26:33], v[226:233], v[66:69]
	v_mfma_f32_16x16x128_f8f6f4 v[70:73], v[18:25], v[226:233], v[70:73]
	s_setprio 0
	s_setprio 1
	v_mfma_f32_16x16x128_f8f6f4 v[38:41], v[2:9], v[226:233], v[38:41]
	v_mfma_f32_16x16x128_f8f6f4 v[34:37], v[182:189], v[226:233], v[34:37]
	v_mfma_f32_16x16x128_f8f6f4 v[42:45], v[182:189], v[218:225], v[42:45]
	v_mfma_f32_16x16x128_f8f6f4 v[46:49], v[2:9], v[218:225], v[46:49]
	v_mfma_f32_16x16x128_f8f6f4 v[54:57], v[2:9], v[210:217], v[54:57]
	v_mfma_f32_16x16x128_f8f6f4 v[50:53], v[182:189], v[210:217], v[50:53]
	v_mfma_f32_16x16x128_f8f6f4 v[58:61], v[182:189], v[202:209], v[58:61]
	v_mfma_f32_16x16x128_f8f6f4 v[62:65], v[2:9], v[202:209], v[62:65]
	s_setprio 0
	s_barrier
	s_add_i32 s62, s62, 2
	s_add_u32 s80, s80, 0x100
	s_addc_u32 s81, s81, 0
	s_add_u32 s8, s8, 0x100
	s_addc_u32 s9, s9, 0
	s_cmp_gt_u32 s62, 5
	s_cbranch_scc0 .LBB0_601
	s_and_b64 vcc, exec, s[44:45]
	s_cbranch_vccz .LBB0_604
	s_barrier

.LBB0_616:
	ds_read_b128 v[18:21], v188
	ds_read_b128 v[22:25], v188 offset:1024
	ds_read_b128 v[26:29], v188 offset:2048
	ds_read_b128 v[30:33], v188 offset:3072
	ds_read_b128 v[2:5], v188 offset:16384
	ds_read_b128 v[6:9], v188 offset:17408
	ds_read_b128 v[10:13], v188 offset:18432
	ds_read_b128 v[14:17], v188 offset:19456
	s_ashr_i32 s55, s54, 31
	s_lshl_b64 s[62:63], s[54:55], 17
	s_add_u32 s72, s36, s62
	s_addc_u32 s73, s37, s63
	s_and_b64 s[62:63], s[2:3], exec
	s_cselect_b32 s85, s73, s79
	s_cselect_b32 s84, s72, s78
	s_ashr_i32 s53, s52, 31
	s_lshl_b64 s[62:63], s[52:53], 17
	s_add_u32 s74, s94, s62
	v_readlane_b32 s5, v254, 8
	s_addc_u32 s75, s5, s63
	s_and_b64 s[62:63], s[2:3], exec
	s_cselect_b32 s83, s75, s81
	s_cselect_b32 s82, s74, s80
	s_add_u32 s62, s78, 0x10080
	s_addc_u32 s63, s79, 0
	s_mov_b32 m0, s96
	v_lshl_add_u64 v[174:175], s[62:63], 0, v[166:167]
	ds_read_b128 v[196:199], v189
	ds_read_b128 v[200:203], v189 offset:1024
	ds_read_b128 v[204:207], v189 offset:2048
	ds_read_b128 v[208:211], v189 offset:3072
	ds_read_b128 v[212:215], v189 offset:4096
	ds_read_b128 v[216:219], v189 offset:5120
	ds_read_b128 v[220:223], v189 offset:6144
	ds_read_b128 v[224:227], v189 offset:7168
	global_load_lds_dwordx4 v[174:175], off
	v_lshl_add_u64 v[174:175], s[62:63], 0, v[168:169]
	s_mov_b32 m0, s97
	s_nop 0
	global_load_lds_dwordx4 v[174:175], off
	s_waitcnt vmcnt(8)
	s_waitcnt lgkmcnt(0)
	s_setprio 1
	s_barrier
	v_mfma_f32_16x16x128_f8f6f4 v[158:161], v[18:25], v[196:203], 0
	v_mfma_f32_16x16x128_f8f6f4 v[154:157], v[26:33], v[196:203], 0
	v_mfma_f32_16x16x128_f8f6f4 v[146:149], v[26:33], v[204:211], 0
	v_mfma_f32_16x16x128_f8f6f4 v[150:153], v[18:25], v[204:211], 0
	v_mfma_f32_16x16x128_f8f6f4 v[142:145], v[18:25], v[212:219], 0
	v_mfma_f32_16x16x128_f8f6f4 v[138:141], v[26:33], v[212:219], 0
	v_mfma_f32_16x16x128_f8f6f4 v[130:133], v[26:33], v[220:227], 0
	v_mfma_f32_16x16x128_f8f6f4 v[134:137], v[18:25], v[220:227], 0
	s_setprio 0
	s_setprio 1
	v_mfma_f32_16x16x128_f8f6f4 v[102:105], v[2:9], v[220:227], 0
	v_mfma_f32_16x16x128_f8f6f4 v[98:101], v[10:17], v[220:227], 0
	v_mfma_f32_16x16x128_f8f6f4 v[106:109], v[10:17], v[212:219], 0
	v_mfma_f32_16x16x128_f8f6f4 v[110:113], v[2:9], v[212:219], 0
	v_mfma_f32_16x16x128_f8f6f4 v[118:121], v[2:9], v[204:211], 0
	v_mfma_f32_16x16x128_f8f6f4 v[114:117], v[10:17], v[204:211], 0
	v_mfma_f32_16x16x128_f8f6f4 v[122:125], v[10:17], v[196:203], 0
	v_mfma_f32_16x16x128_f8f6f4 v[126:129], v[2:9], v[196:203], 0
	s_setprio 0
	s_barrier
	v_lshl_add_u64 v[174:175], s[80:81], 0, v[162:163]
	s_mov_b32 m0, s61
	v_lshl_add_u64 v[176:177], v[174:175], 0, s[46:47]
	ds_read_b128 v[196:199], v189 offset:16384
	ds_read_b128 v[200:203], v189 offset:17408
	ds_read_b128 v[204:207], v189 offset:18432
	ds_read_b128 v[208:211], v189 offset:19456
	ds_read_b128 v[212:215], v189 offset:20480
	ds_read_b128 v[216:219], v189 offset:21504
	ds_read_b128 v[220:223], v189 offset:22528
	ds_read_b128 v[224:227], v189 offset:23552
	global_load_lds_dwordx4 v[176:177], off
	v_lshl_add_u64 v[176:177], s[80:81], 0, v[164:165]
	s_add_u32 s62, s80, 0x10100
	v_lshl_add_u64 v[182:183], v[176:177], 0, s[46:47]
	s_mov_b32 m0, s68
	s_addc_u32 s63, s81, 0
	global_load_lds_dwordx4 v[182:183], off
	v_lshl_add_u64 v[182:183], s[62:63], 0, v[162:163]
	s_mov_b32 m0, s69
	s_nop 0
	global_load_lds_dwordx4 v[182:183], off
	v_lshl_add_u64 v[182:183], s[62:63], 0, v[164:165]
	s_mov_b32 m0, s77
	s_nop 0
	global_load_lds_dwordx4 v[182:183], off
	v_lshl_add_u64 v[182:183], s[78:79], 0, v[166:167]
	v_lshl_add_u64 v[184:185], v[182:183], 0, s[46:47]
	s_mov_b32 m0, s51
	s_nop 0
	global_load_lds_dwordx4 v[184:185], off
	v_lshl_add_u64 v[184:185], s[78:79], 0, v[168:169]
	v_lshl_add_u64 v[228:229], v[184:185], 0, s[46:47]
	s_mov_b32 m0, s86
	s_nop 0
	global_load_lds_dwordx4 v[228:229], off
	s_waitcnt vmcnt(8)
	s_waitcnt lgkmcnt(0)
	s_setprio 1
	s_barrier
	v_mfma_f32_16x16x128_f8f6f4 v[94:97], v[18:25], v[196:203], 0
	v_mfma_f32_16x16x128_f8f6f4 v[90:93], v[26:33], v[196:203], 0
	v_mfma_f32_16x16x128_f8f6f4 v[82:85], v[26:33], v[204:211], 0
	v_mfma_f32_16x16x128_f8f6f4 v[86:89], v[18:25], v[204:211], 0
	v_mfma_f32_16x16x128_f8f6f4 v[78:81], v[18:25], v[212:219], 0
	v_mfma_f32_16x16x128_f8f6f4 v[74:77], v[26:33], v[212:219], 0
	v_mfma_f32_16x16x128_f8f6f4 v[66:69], v[26:33], v[220:227], 0
	v_mfma_f32_16x16x128_f8f6f4 v[70:73], v[18:25], v[220:227], 0
	s_setprio 0
	s_setprio 1
	v_mfma_f32_16x16x128_f8f6f4 v[38:41], v[2:9], v[220:227], 0
	v_mfma_f32_16x16x128_f8f6f4 v[34:37], v[10:17], v[220:227], 0
	v_mfma_f32_16x16x128_f8f6f4 v[42:45], v[10:17], v[212:219], 0
	v_mfma_f32_16x16x128_f8f6f4 v[46:49], v[2:9], v[212:219], 0
	v_mfma_f32_16x16x128_f8f6f4 v[54:57], v[2:9], v[204:211], 0
	v_mfma_f32_16x16x128_f8f6f4 v[50:53], v[10:17], v[204:211], 0
	v_mfma_f32_16x16x128_f8f6f4 v[58:61], v[10:17], v[196:203], 0
	v_mfma_f32_16x16x128_f8f6f4 v[62:65], v[2:9], v[196:203], 0
	s_setprio 0
	s_barrier
	ds_read_b128 v[2:5], v188 offset:32768
	ds_read_b128 v[6:9], v188 offset:33792
	ds_read_b128 v[10:13], v188 offset:34816
	ds_read_b128 v[14:17], v188 offset:35840
	ds_read_b128 v[18:21], v188 offset:49152
	ds_read_b128 v[22:25], v188 offset:50176
	ds_read_b128 v[26:29], v188 offset:51200
	ds_read_b128 v[30:33], v188 offset:52224
	s_add_u32 s62, s78, 0x10100
	s_addc_u32 s63, s79, 0
	s_mov_b32 m0, s87
	v_lshl_add_u64 v[228:229], s[62:63], 0, v[166:167]
	ds_read_b128 v[196:199], v189 offset:32768
	ds_read_b128 v[200:203], v189 offset:33792
	ds_read_b128 v[204:207], v189 offset:34816
	ds_read_b128 v[208:211], v189 offset:35840
	ds_read_b128 v[212:215], v189 offset:36864
	ds_read_b128 v[216:219], v189 offset:37888
	ds_read_b128 v[220:223], v189 offset:38912
	ds_read_b128 v[224:227], v189 offset:39936
	global_load_lds_dwordx4 v[228:229], off
	v_lshl_add_u64 v[228:229], s[62:63], 0, v[168:169]
	s_mov_b32 m0, s88
	s_nop 0
	global_load_lds_dwordx4 v[228:229], off
	s_waitcnt vmcnt(8)
	s_waitcnt lgkmcnt(0)
	s_setprio 1
	s_barrier
	v_mfma_f32_16x16x128_f8f6f4 v[158:161], v[2:9], v[196:203], v[158:161]
	v_mfma_f32_16x16x128_f8f6f4 v[154:157], v[10:17], v[196:203], v[154:157]
	v_mfma_f32_16x16x128_f8f6f4 v[146:149], v[10:17], v[204:211], v[146:149]
	v_mfma_f32_16x16x128_f8f6f4 v[150:153], v[2:9], v[204:211], v[150:153]
	v_mfma_f32_16x16x128_f8f6f4 v[142:145], v[2:9], v[212:219], v[142:145]
	v_mfma_f32_16x16x128_f8f6f4 v[138:141], v[10:17], v[212:219], v[138:141]
	v_mfma_f32_16x16x128_f8f6f4 v[130:133], v[10:17], v[220:227], v[130:133]
	v_mfma_f32_16x16x128_f8f6f4 v[134:137], v[2:9], v[220:227], v[134:137]
	s_setprio 0
	s_setprio 1
	v_mfma_f32_16x16x128_f8f6f4 v[102:105], v[18:25], v[220:227], v[102:105]
	v_mfma_f32_16x16x128_f8f6f4 v[98:101], v[26:33], v[220:227], v[98:101]
	v_mfma_f32_16x16x128_f8f6f4 v[106:109], v[26:33], v[212:219], v[106:109]
	v_mfma_f32_16x16x128_f8f6f4 v[110:113], v[18:25], v[212:219], v[110:113]
	v_mfma_f32_16x16x128_f8f6f4 v[118:121], v[18:25], v[204:211], v[118:121]
	v_mfma_f32_16x16x128_f8f6f4 v[114:117], v[26:33], v[204:211], v[114:117]
	v_mfma_f32_16x16x128_f8f6f4 v[122:125], v[26:33], v[196:203], v[122:125]
	v_mfma_f32_16x16x128_f8f6f4 v[126:129], v[18:25], v[196:203], v[126:129]
	s_setprio 0
	s_barrier
	s_mov_b32 m0, s89
	v_lshl_add_u64 v[174:175], v[174:175], 0, s[48:49]
	s_add_u32 s62, s80, 0x10180
	ds_read_b128 v[196:199], v189 offset:49152
	ds_read_b128 v[200:203], v189 offset:50176
	ds_read_b128 v[204:207], v189 offset:51200
	ds_read_b128 v[208:211], v189 offset:52224
	ds_read_b128 v[212:215], v189 offset:53248
	ds_read_b128 v[216:219], v189 offset:54272
	ds_read_b128 v[220:223], v189 offset:55296
	ds_read_b128 v[224:227], v189 offset:56320
	global_load_lds_dwordx4 v[174:175], off
	v_lshl_add_u64 v[174:175], v[176:177], 0, s[48:49]
	s_mov_b32 m0, s90
	s_addc_u32 s63, s81, 0
	global_load_lds_dwordx4 v[174:175], off
	v_lshl_add_u64 v[174:175], s[62:63], 0, v[162:163]
	s_mov_b32 m0, s93
	s_nop 0
	global_load_lds_dwordx4 v[174:175], off
	v_lshl_add_u64 v[174:175], s[62:63], 0, v[164:165]
	s_mov_b32 m0, s95
	s_nop 0
	global_load_lds_dwordx4 v[174:175], off
	v_lshl_add_u64 v[174:175], v[182:183], 0, s[48:49]
	s_mov_b32 m0, s91
	s_nop 0
	global_load_lds_dwordx4 v[174:175], off
	v_lshl_add_u64 v[174:175], v[184:185], 0, s[48:49]
	s_mov_b32 m0, s92
	s_nop 0
	global_load_lds_dwordx4 v[174:175], off
	s_waitcnt vmcnt(8)
	s_waitcnt lgkmcnt(0)
	s_setprio 1
	s_barrier
	v_mfma_f32_16x16x128_f8f6f4 v[94:97], v[2:9], v[196:203], v[94:97]
	v_mfma_f32_16x16x128_f8f6f4 v[90:93], v[10:17], v[196:203], v[90:93]
	v_mfma_f32_16x16x128_f8f6f4 v[82:85], v[10:17], v[204:211], v[82:85]
	v_mfma_f32_16x16x128_f8f6f4 v[86:89], v[2:9], v[204:211], v[86:89]
	v_mfma_f32_16x16x128_f8f6f4 v[78:81], v[2:9], v[212:219], v[78:81]
	v_mfma_f32_16x16x128_f8f6f4 v[74:77], v[10:17], v[212:219], v[74:77]
	v_mfma_f32_16x16x128_f8f6f4 v[66:69], v[10:17], v[220:227], v[66:69]
	v_mfma_f32_16x16x128_f8f6f4 v[70:73], v[2:9], v[220:227], v[70:73]
	s_setprio 0
	s_setprio 1
	v_mfma_f32_16x16x128_f8f6f4 v[38:41], v[18:25], v[220:227], v[38:41]
	v_mfma_f32_16x16x128_f8f6f4 v[34:37], v[26:33], v[220:227], v[34:37]
	v_mfma_f32_16x16x128_f8f6f4 v[42:45], v[26:33], v[212:219], v[42:45]
	v_mfma_f32_16x16x128_f8f6f4 v[46:49], v[18:25], v[212:219], v[46:49]
	v_mfma_f32_16x16x128_f8f6f4 v[54:57], v[18:25], v[204:211], v[54:57]
	v_mfma_f32_16x16x128_f8f6f4 v[50:53], v[26:33], v[204:211], v[50:53]
	v_mfma_f32_16x16x128_f8f6f4 v[58:61], v[26:33], v[196:203], v[58:61]
	v_mfma_f32_16x16x128_f8f6f4 v[62:65], v[18:25], v[196:203], v[62:65]
	s_setprio 0
	s_barrier
	ds_read_b128 v[2:5], v188
	ds_read_b128 v[6:9], v188 offset:1024
	ds_read_b128 v[10:13], v188 offset:2048
	ds_read_b128 v[14:17], v188 offset:3072
	ds_read_b128 v[18:21], v188 offset:16384
	ds_read_b128 v[22:25], v188 offset:17408
	ds_read_b128 v[26:29], v188 offset:18432
	ds_read_b128 v[30:33], v188 offset:19456
	s_add_u32 s62, s78, 0x10180
	s_addc_u32 s63, s79, 0
	s_mov_b32 m0, s96
	v_lshl_add_u64 v[174:175], s[62:63], 0, v[166:167]
	ds_read_b128 v[196:199], v189
	ds_read_b128 v[200:203], v189 offset:1024
	ds_read_b128 v[204:207], v189 offset:2048
	ds_read_b128 v[208:211], v189 offset:3072
	ds_read_b128 v[212:215], v189 offset:4096
	ds_read_b128 v[216:219], v189 offset:5120
	ds_read_b128 v[220:223], v189 offset:6144
	ds_read_b128 v[224:227], v189 offset:7168
	global_load_lds_dwordx4 v[174:175], off
	v_lshl_add_u64 v[174:175], s[62:63], 0, v[168:169]
	s_mov_b32 m0, s97
	s_nop 0
	global_load_lds_dwordx4 v[174:175], off
	s_waitcnt vmcnt(8)
	s_waitcnt lgkmcnt(0)
	s_setprio 1
	s_barrier
	v_mfma_f32_16x16x128_f8f6f4 v[158:161], v[2:9], v[196:203], v[158:161]
	v_mfma_f32_16x16x128_f8f6f4 v[154:157], v[10:17], v[196:203], v[154:157]
	v_mfma_f32_16x16x128_f8f6f4 v[146:149], v[10:17], v[204:211], v[146:149]
	v_mfma_f32_16x16x128_f8f6f4 v[150:153], v[2:9], v[204:211], v[150:153]
	v_mfma_f32_16x16x128_f8f6f4 v[142:145], v[2:9], v[212:219], v[142:145]
	v_mfma_f32_16x16x128_f8f6f4 v[138:141], v[10:17], v[212:219], v[138:141]
	v_mfma_f32_16x16x128_f8f6f4 v[130:133], v[10:17], v[220:227], v[130:133]
	v_mfma_f32_16x16x128_f8f6f4 v[134:137], v[2:9], v[220:227], v[134:137]
	s_setprio 0
	s_setprio 1
	v_mfma_f32_16x16x128_f8f6f4 v[102:105], v[18:25], v[220:227], v[102:105]
	v_mfma_f32_16x16x128_f8f6f4 v[98:101], v[26:33], v[220:227], v[98:101]
	v_mfma_f32_16x16x128_f8f6f4 v[106:109], v[26:33], v[212:219], v[106:109]
	v_mfma_f32_16x16x128_f8f6f4 v[110:113], v[18:25], v[212:219], v[110:113]
	v_mfma_f32_16x16x128_f8f6f4 v[118:121], v[18:25], v[204:211], v[118:121]
	v_mfma_f32_16x16x128_f8f6f4 v[114:117], v[26:33], v[204:211], v[114:117]
	v_mfma_f32_16x16x128_f8f6f4 v[122:125], v[26:33], v[196:203], v[122:125]
	v_mfma_f32_16x16x128_f8f6f4 v[126:129], v[18:25], v[196:203], v[126:129]
	s_setprio 0
	s_barrier
	s_mov_b32 m0, s61
	v_lshl_add_u64 v[174:175], s[82:83], 0, v[162:163]
	s_add_u32 s62, s82, 0x10000
	ds_read_b128 v[196:199], v189 offset:16384
	ds_read_b128 v[200:203], v189 offset:17408
	ds_read_b128 v[204:207], v189 offset:18432
	ds_read_b128 v[208:211], v189 offset:19456
	ds_read_b128 v[212:215], v189 offset:20480
	ds_read_b128 v[216:219], v189 offset:21504
	ds_read_b128 v[220:223], v189 offset:22528
	ds_read_b128 v[224:227], v189 offset:23552
	global_load_lds_dwordx4 v[174:175], off
	v_lshl_add_u64 v[176:177], s[82:83], 0, v[164:165]
	s_mov_b32 m0, s68
	s_addc_u32 s63, s83, 0
	global_load_lds_dwordx4 v[176:177], off
	v_lshl_add_u64 v[182:183], s[62:63], 0, v[162:163]
	s_mov_b32 m0, s69
	v_lshl_add_u64 v[184:185], s[84:85], 0, v[168:169]
	global_load_lds_dwordx4 v[182:183], off
	v_lshl_add_u64 v[182:183], s[62:63], 0, v[164:165]
	s_mov_b32 m0, s77
	s_nop 0
	global_load_lds_dwordx4 v[182:183], off
	v_lshl_add_u64 v[182:183], s[84:85], 0, v[166:167]
	s_mov_b32 m0, s51
	s_nop 0
	global_load_lds_dwordx4 v[182:183], off
	s_mov_b32 m0, s86
	s_nop 0
	global_load_lds_dwordx4 v[184:185], off
	s_waitcnt vmcnt(8)
	s_waitcnt lgkmcnt(0)
	s_setprio 1
	s_barrier
	v_mfma_f32_16x16x128_f8f6f4 v[94:97], v[2:9], v[196:203], v[94:97]
	v_mfma_f32_16x16x128_f8f6f4 v[90:93], v[10:17], v[196:203], v[90:93]
	v_mfma_f32_16x16x128_f8f6f4 v[82:85], v[10:17], v[204:211], v[82:85]
	v_mfma_f32_16x16x128_f8f6f4 v[86:89], v[2:9], v[204:211], v[86:89]
	v_mfma_f32_16x16x128_f8f6f4 v[78:81], v[2:9], v[212:219], v[78:81]
	v_mfma_f32_16x16x128_f8f6f4 v[74:77], v[10:17], v[212:219], v[74:77]
	v_mfma_f32_16x16x128_f8f6f4 v[66:69], v[10:17], v[220:227], v[66:69]
	v_mfma_f32_16x16x128_f8f6f4 v[70:73], v[2:9], v[220:227], v[70:73]
	s_setprio 0
	s_setprio 1
	v_mfma_f32_16x16x128_f8f6f4 v[38:41], v[18:25], v[220:227], v[38:41]
	v_mfma_f32_16x16x128_f8f6f4 v[34:37], v[26:33], v[220:227], v[34:37]
	v_mfma_f32_16x16x128_f8f6f4 v[42:45], v[26:33], v[212:219], v[42:45]
	v_mfma_f32_16x16x128_f8f6f4 v[46:49], v[18:25], v[212:219], v[46:49]
	v_mfma_f32_16x16x128_f8f6f4 v[54:57], v[18:25], v[204:211], v[54:57]
	v_mfma_f32_16x16x128_f8f6f4 v[50:53], v[26:33], v[204:211], v[50:53]
	v_mfma_f32_16x16x128_f8f6f4 v[58:61], v[26:33], v[196:203], v[58:61]
	v_mfma_f32_16x16x128_f8f6f4 v[62:65], v[18:25], v[196:203], v[62:65]
	s_setprio 0
	s_barrier
	ds_read_b128 v[2:5], v188 offset:32768
	ds_read_b128 v[6:9], v188 offset:33792
	ds_read_b128 v[10:13], v188 offset:34816
	ds_read_b128 v[14:17], v188 offset:35840
	ds_read_b128 v[18:21], v188 offset:49152
	ds_read_b128 v[22:25], v188 offset:50176
	ds_read_b128 v[26:29], v188 offset:51200
	ds_read_b128 v[30:33], v188 offset:52224
	s_add_u32 s62, s84, 0x10000
	s_addc_u32 s63, s85, 0
	s_mov_b32 m0, s87
	v_lshl_add_u64 v[228:229], s[62:63], 0, v[166:167]
	ds_read_b128 v[196:199], v189 offset:32768
	ds_read_b128 v[200:203], v189 offset:33792
	ds_read_b128 v[204:207], v189 offset:34816
	ds_read_b128 v[208:211], v189 offset:35840
	ds_read_b128 v[212:215], v189 offset:36864
	ds_read_b128 v[216:219], v189 offset:37888
	ds_read_b128 v[220:223], v189 offset:38912
	ds_read_b128 v[224:227], v189 offset:39936
	global_load_lds_dwordx4 v[228:229], off
	v_lshl_add_u64 v[228:229], s[62:63], 0, v[168:169]
	s_mov_b32 m0, s88
	s_nop 0
	global_load_lds_dwordx4 v[228:229], off
	s_waitcnt vmcnt(8)
	s_waitcnt lgkmcnt(0)
	s_setprio 1
	s_barrier
	v_mfma_f32_16x16x128_f8f6f4 v[158:161], v[2:9], v[196:203], v[158:161]
	v_mfma_f32_16x16x128_f8f6f4 v[154:157], v[10:17], v[196:203], v[154:157]
	v_mfma_f32_16x16x128_f8f6f4 v[146:149], v[10:17], v[204:211], v[146:149]
	v_mfma_f32_16x16x128_f8f6f4 v[150:153], v[2:9], v[204:211], v[150:153]
	v_mfma_f32_16x16x128_f8f6f4 v[142:145], v[2:9], v[212:219], v[142:145]
	v_mfma_f32_16x16x128_f8f6f4 v[138:141], v[10:17], v[212:219], v[138:141]
	v_mfma_f32_16x16x128_f8f6f4 v[130:133], v[10:17], v[220:227], v[130:133]
	v_mfma_f32_16x16x128_f8f6f4 v[134:137], v[2:9], v[220:227], v[134:137]
	s_setprio 0
	s_setprio 1
	v_mfma_f32_16x16x128_f8f6f4 v[102:105], v[18:25], v[220:227], v[102:105]
	v_mfma_f32_16x16x128_f8f6f4 v[98:101], v[26:33], v[220:227], v[98:101]
	v_mfma_f32_16x16x128_f8f6f4 v[106:109], v[26:33], v[212:219], v[106:109]
	v_mfma_f32_16x16x128_f8f6f4 v[110:113], v[18:25], v[212:219], v[110:113]
	v_mfma_f32_16x16x128_f8f6f4 v[118:121], v[18:25], v[204:211], v[118:121]
	v_mfma_f32_16x16x128_f8f6f4 v[114:117], v[26:33], v[204:211], v[114:117]
	v_mfma_f32_16x16x128_f8f6f4 v[122:125], v[26:33], v[196:203], v[122:125]
	v_mfma_f32_16x16x128_f8f6f4 v[126:129], v[18:25], v[196:203], v[126:129]
	s_setprio 0
	s_barrier
	s_mov_b32 m0, s89
	v_lshl_add_u64 v[174:175], v[174:175], 0, s[40:41]
	s_add_u32 s62, s82, 0x10080
	ds_read_b128 v[196:199], v189 offset:49152
	ds_read_b128 v[200:203], v189 offset:50176
	ds_read_b128 v[204:207], v189 offset:51200
	ds_read_b128 v[208:211], v189 offset:52224
	ds_read_b128 v[212:215], v189 offset:53248
	ds_read_b128 v[216:219], v189 offset:54272
	ds_read_b128 v[220:223], v189 offset:55296
	ds_read_b128 v[224:227], v189 offset:56320
	global_load_lds_dwordx4 v[174:175], off
	v_lshl_add_u64 v[174:175], v[176:177], 0, s[40:41]
	s_mov_b32 m0, s90
	s_addc_u32 s63, s83, 0
	global_load_lds_dwordx4 v[174:175], off
	v_lshl_add_u64 v[174:175], s[62:63], 0, v[162:163]
	s_mov_b32 m0, s93
	s_nop 0
	global_load_lds_dwordx4 v[174:175], off
	v_lshl_add_u64 v[174:175], s[62:63], 0, v[164:165]
	s_mov_b32 m0, s95
	s_nop 0
	global_load_lds_dwordx4 v[174:175], off
	v_lshl_add_u64 v[174:175], v[182:183], 0, s[40:41]
	s_mov_b32 m0, s91
	s_nop 0
	global_load_lds_dwordx4 v[174:175], off
	v_lshl_add_u64 v[174:175], v[184:185], 0, s[40:41]
	s_mov_b32 m0, s92
	s_nop 0
	global_load_lds_dwordx4 v[174:175], off
	s_waitcnt vmcnt(8)
	s_waitcnt lgkmcnt(0)
	s_setprio 1
	s_barrier
	v_mfma_f32_16x16x128_f8f6f4 v[94:97], v[2:9], v[196:203], v[94:97]
	v_mfma_f32_16x16x128_f8f6f4 v[90:93], v[10:17], v[196:203], v[90:93]
	v_mfma_f32_16x16x128_f8f6f4 v[82:85], v[10:17], v[204:211], v[82:85]
	v_mfma_f32_16x16x128_f8f6f4 v[86:89], v[2:9], v[204:211], v[86:89]
	v_mfma_f32_16x16x128_f8f6f4 v[78:81], v[2:9], v[212:219], v[78:81]
	v_mfma_f32_16x16x128_f8f6f4 v[74:77], v[10:17], v[212:219], v[74:77]
	v_mfma_f32_16x16x128_f8f6f4 v[66:69], v[10:17], v[220:227], v[66:69]
	v_mfma_f32_16x16x128_f8f6f4 v[70:73], v[2:9], v[220:227], v[70:73]
	s_setprio 0
	s_setprio 1
	v_mfma_f32_16x16x128_f8f6f4 v[38:41], v[18:25], v[220:227], v[38:41]
	v_mfma_f32_16x16x128_f8f6f4 v[34:37], v[26:33], v[220:227], v[34:37]
	v_mfma_f32_16x16x128_f8f6f4 v[42:45], v[26:33], v[212:219], v[42:45]
	v_mfma_f32_16x16x128_f8f6f4 v[46:49], v[18:25], v[212:219], v[46:49]
	v_mfma_f32_16x16x128_f8f6f4 v[54:57], v[18:25], v[204:211], v[54:57]
	v_mfma_f32_16x16x128_f8f6f4 v[50:53], v[26:33], v[204:211], v[50:53]
	v_mfma_f32_16x16x128_f8f6f4 v[58:61], v[26:33], v[196:203], v[58:61]
	v_mfma_f32_16x16x128_f8f6f4 v[62:65], v[18:25], v[196:203], v[62:65]
	s_setprio 0
	s_barrier
	s_andn2_b64 vcc, exec, s[42:43]
	s_cbranch_vccnz .LBB0_618
	s_barrier

.LBB0_630:
	s_ashr_i32 s54, s48, 1
	s_ashr_i32 s51, s50, 31
	s_ashr_i32 s55, s54, 31
	s_lshl_b64 s[52:53], s[50:51], 19
	s_lshl_b64 s[54:55], s[54:55], 9
	s_waitcnt vmcnt(0)
	ds_read_b128 v[18:21], v181
	ds_read_b128 v[22:25], v181 offset:1024
	ds_read_b128 v[26:29], v181 offset:2048
	ds_read_b128 v[30:33], v181 offset:3072
	ds_read_b128 v[2:5], v181 offset:16384
	ds_read_b128 v[6:9], v181 offset:17408
	ds_read_b128 v[10:13], v181 offset:18432
	ds_read_b128 v[14:17], v181 offset:19456
	s_add_u32 s5, s26, s52
	s_addc_u32 s33, s27, s53
	s_add_u32 s52, s5, s54
	s_addc_u32 s53, s33, s55
	s_and_b64 s[54:55], s[2:3], exec
	s_cselect_b32 s81, s53, s75
	s_cselect_b32 s80, s52, s74
	s_ashr_i32 s49, s48, 31
	s_lshl_b64 s[54:55], s[48:49], 17
	v_readlane_b32 s5, v254, 9
	s_add_u32 s54, s5, s54
	v_readlane_b32 s5, v254, 10
	s_addc_u32 s55, s5, s55
	s_and_b64 s[62:63], s[2:3], exec
	s_cselect_b32 s79, s55, s77
	s_cselect_b32 s78, s54, s76
	s_add_u32 s62, s74, 0x40080
	s_addc_u32 s63, s75, 0
	s_add_i32 s33, s8, 0xc000
	v_lshl_add_u64 v[174:175], s[62:63], 0, v[166:167]
	s_mov_b32 m0, s33
	s_add_i32 s5, s8, 0xe000
	ds_read_b128 v[190:193], v187
	ds_read_b128 v[194:197], v187 offset:1024
	ds_read_b128 v[198:201], v187 offset:2048
	ds_read_b128 v[202:205], v187 offset:3072
	ds_read_b128 v[206:209], v187 offset:4096
	ds_read_b128 v[210:213], v187 offset:5120
	ds_read_b128 v[214:217], v187 offset:6144
	ds_read_b128 v[218:221], v187 offset:7168
	global_load_lds_dwordx4 v[174:175], off
	v_lshl_add_u64 v[174:175], s[62:63], 0, v[168:169]
	s_mov_b32 m0, s5
	s_nop 0
	global_load_lds_dwordx4 v[174:175], off
	s_waitcnt vmcnt(8)
	s_waitcnt lgkmcnt(0)
	s_setprio 1
	s_barrier
	v_mfma_f32_16x16x128_f8f6f4 v[158:161], v[18:25], v[190:197], 0
	v_mfma_f32_16x16x128_f8f6f4 v[154:157], v[26:33], v[190:197], 0
	v_mfma_f32_16x16x128_f8f6f4 v[146:149], v[26:33], v[198:205], 0
	v_mfma_f32_16x16x128_f8f6f4 v[150:153], v[18:25], v[198:205], 0
	v_mfma_f32_16x16x128_f8f6f4 v[142:145], v[18:25], v[206:213], 0
	v_mfma_f32_16x16x128_f8f6f4 v[138:141], v[26:33], v[206:213], 0
	v_mfma_f32_16x16x128_f8f6f4 v[130:133], v[26:33], v[214:221], 0
	v_mfma_f32_16x16x128_f8f6f4 v[134:137], v[18:25], v[214:221], 0
	s_setprio 0
	s_setprio 1
	v_mfma_f32_16x16x128_f8f6f4 v[102:105], v[2:9], v[214:221], 0
	v_mfma_f32_16x16x128_f8f6f4 v[98:101], v[10:17], v[214:221], 0
	v_mfma_f32_16x16x128_f8f6f4 v[106:109], v[10:17], v[206:213], 0
	v_mfma_f32_16x16x128_f8f6f4 v[110:113], v[2:9], v[206:213], 0
	v_mfma_f32_16x16x128_f8f6f4 v[118:121], v[2:9], v[198:205], 0
	v_mfma_f32_16x16x128_f8f6f4 v[114:117], v[10:17], v[198:205], 0
	v_mfma_f32_16x16x128_f8f6f4 v[122:125], v[10:17], v[190:197], 0
	v_mfma_f32_16x16x128_f8f6f4 v[126:129], v[2:9], v[190:197], 0
	s_setprio 0
	s_barrier
	v_lshl_add_u64 v[174:175], s[76:77], 0, v[162:163]
	s_mov_b32 m0, s9
	v_lshl_add_u64 v[176:177], v[174:175], 0, s[44:45]
	ds_read_b128 v[190:193], v187 offset:16384
	ds_read_b128 v[194:197], v187 offset:17408
	ds_read_b128 v[198:201], v187 offset:18432
	ds_read_b128 v[202:205], v187 offset:19456
	ds_read_b128 v[206:209], v187 offset:20480
	ds_read_b128 v[210:213], v187 offset:21504
	ds_read_b128 v[214:217], v187 offset:22528
	ds_read_b128 v[218:221], v187 offset:23552
	global_load_lds_dwordx4 v[176:177], off
	v_lshl_add_u64 v[176:177], s[76:77], 0, v[164:165]
	s_add_u32 s62, s76, 0x10100
	v_lshl_add_u64 v[182:183], v[176:177], 0, s[44:45]
	s_mov_b32 m0, s61
	s_addc_u32 s63, s77, 0
	global_load_lds_dwordx4 v[182:183], off
	v_lshl_add_u64 v[182:183], s[62:63], 0, v[162:163]
	s_mov_b32 m0, s68
	s_nop 0
	global_load_lds_dwordx4 v[182:183], off
	v_lshl_add_u64 v[182:183], s[62:63], 0, v[164:165]
	s_mov_b32 m0, s69
	s_nop 0
	global_load_lds_dwordx4 v[182:183], off
	v_lshl_add_u64 v[182:183], s[74:75], 0, v[166:167]
	v_lshl_add_u64 v[184:185], v[182:183], 0, s[44:45]
	s_mov_b32 m0, s8
	s_nop 0
	global_load_lds_dwordx4 v[184:185], off
	v_lshl_add_u64 v[184:185], s[74:75], 0, v[168:169]
	v_lshl_add_u64 v[222:223], v[184:185], 0, s[44:45]
	s_mov_b32 m0, s71
	s_nop 0
	global_load_lds_dwordx4 v[222:223], off
	s_waitcnt vmcnt(8)
	s_waitcnt lgkmcnt(0)
	s_setprio 1
	s_barrier
	v_mfma_f32_16x16x128_f8f6f4 v[94:97], v[18:25], v[190:197], 0
	v_mfma_f32_16x16x128_f8f6f4 v[90:93], v[26:33], v[190:197], 0
	v_mfma_f32_16x16x128_f8f6f4 v[82:85], v[26:33], v[198:205], 0
	v_mfma_f32_16x16x128_f8f6f4 v[86:89], v[18:25], v[198:205], 0
	v_mfma_f32_16x16x128_f8f6f4 v[78:81], v[18:25], v[206:213], 0
	v_mfma_f32_16x16x128_f8f6f4 v[74:77], v[26:33], v[206:213], 0
	v_mfma_f32_16x16x128_f8f6f4 v[66:69], v[26:33], v[214:221], 0
	v_mfma_f32_16x16x128_f8f6f4 v[70:73], v[18:25], v[214:221], 0
	s_setprio 0
	s_setprio 1
	v_mfma_f32_16x16x128_f8f6f4 v[38:41], v[2:9], v[214:221], 0
	v_mfma_f32_16x16x128_f8f6f4 v[34:37], v[10:17], v[214:221], 0
	v_mfma_f32_16x16x128_f8f6f4 v[42:45], v[10:17], v[206:213], 0
	v_mfma_f32_16x16x128_f8f6f4 v[46:49], v[2:9], v[206:213], 0
	v_mfma_f32_16x16x128_f8f6f4 v[54:57], v[2:9], v[198:205], 0
	v_mfma_f32_16x16x128_f8f6f4 v[50:53], v[10:17], v[198:205], 0
	v_mfma_f32_16x16x128_f8f6f4 v[58:61], v[10:17], v[190:197], 0
	v_mfma_f32_16x16x128_f8f6f4 v[62:65], v[2:9], v[190:197], 0
	s_setprio 0
	s_barrier
	ds_read_b128 v[2:5], v181 offset:32768
	ds_read_b128 v[6:9], v181 offset:33792
	ds_read_b128 v[10:13], v181 offset:34816
	ds_read_b128 v[14:17], v181 offset:35840
	ds_read_b128 v[18:21], v181 offset:49152
	ds_read_b128 v[22:25], v181 offset:50176
	ds_read_b128 v[26:29], v181 offset:51200
	ds_read_b128 v[30:33], v181 offset:52224
	s_add_u32 s62, s74, 0x40100
	s_addc_u32 s63, s75, 0
	s_mov_b32 m0, s73
	v_lshl_add_u64 v[222:223], s[62:63], 0, v[166:167]
	ds_read_b128 v[190:193], v187 offset:32768
	ds_read_b128 v[194:197], v187 offset:33792
	ds_read_b128 v[198:201], v187 offset:34816
	ds_read_b128 v[202:205], v187 offset:35840
	ds_read_b128 v[206:209], v187 offset:36864
	ds_read_b128 v[210:213], v187 offset:37888
	ds_read_b128 v[214:217], v187 offset:38912
	ds_read_b128 v[218:221], v187 offset:39936
	global_load_lds_dwordx4 v[222:223], off
	v_lshl_add_u64 v[222:223], s[62:63], 0, v[168:169]
	s_mov_b32 m0, s82
	s_nop 0
	global_load_lds_dwordx4 v[222:223], off
	s_waitcnt vmcnt(8)
	s_waitcnt lgkmcnt(0)
	s_setprio 1
	s_barrier
	v_mfma_f32_16x16x128_f8f6f4 v[158:161], v[2:9], v[190:197], v[158:161]
	v_mfma_f32_16x16x128_f8f6f4 v[154:157], v[10:17], v[190:197], v[154:157]
	v_mfma_f32_16x16x128_f8f6f4 v[146:149], v[10:17], v[198:205], v[146:149]
	v_mfma_f32_16x16x128_f8f6f4 v[150:153], v[2:9], v[198:205], v[150:153]
	v_mfma_f32_16x16x128_f8f6f4 v[142:145], v[2:9], v[206:213], v[142:145]
	v_mfma_f32_16x16x128_f8f6f4 v[138:141], v[10:17], v[206:213], v[138:141]
	v_mfma_f32_16x16x128_f8f6f4 v[130:133], v[10:17], v[214:221], v[130:133]
	v_mfma_f32_16x16x128_f8f6f4 v[134:137], v[2:9], v[214:221], v[134:137]
	s_setprio 0
	s_setprio 1
	v_mfma_f32_16x16x128_f8f6f4 v[102:105], v[18:25], v[214:221], v[102:105]
	v_mfma_f32_16x16x128_f8f6f4 v[98:101], v[26:33], v[214:221], v[98:101]
	v_mfma_f32_16x16x128_f8f6f4 v[106:109], v[26:33], v[206:213], v[106:109]
	v_mfma_f32_16x16x128_f8f6f4 v[110:113], v[18:25], v[206:213], v[110:113]
	v_mfma_f32_16x16x128_f8f6f4 v[118:121], v[18:25], v[198:205], v[118:121]
	v_mfma_f32_16x16x128_f8f6f4 v[114:117], v[26:33], v[198:205], v[114:117]
	v_mfma_f32_16x16x128_f8f6f4 v[122:125], v[26:33], v[190:197], v[122:125]
	v_mfma_f32_16x16x128_f8f6f4 v[126:129], v[18:25], v[190:197], v[126:129]
	s_setprio 0
	s_barrier
	s_mov_b32 m0, s83
	v_lshl_add_u64 v[174:175], v[174:175], 0, s[46:47]
	s_add_u32 s62, s76, 0x10180
	ds_read_b128 v[190:193], v187 offset:49152
	ds_read_b128 v[194:197], v187 offset:50176
	ds_read_b128 v[198:201], v187 offset:51200
	ds_read_b128 v[202:205], v187 offset:52224
	ds_read_b128 v[206:209], v187 offset:53248
	ds_read_b128 v[210:213], v187 offset:54272
	ds_read_b128 v[214:217], v187 offset:55296
	ds_read_b128 v[218:221], v187 offset:56320
	global_load_lds_dwordx4 v[174:175], off
	v_lshl_add_u64 v[174:175], v[176:177], 0, s[46:47]
	s_mov_b32 m0, s84
	s_addc_u32 s63, s77, 0
	global_load_lds_dwordx4 v[174:175], off
	v_lshl_add_u64 v[174:175], s[62:63], 0, v[162:163]
	s_mov_b32 m0, s87
	s_nop 0
	global_load_lds_dwordx4 v[174:175], off
	v_lshl_add_u64 v[174:175], s[62:63], 0, v[164:165]
	s_mov_b32 m0, s88
	s_nop 0
	global_load_lds_dwordx4 v[174:175], off
	v_lshl_add_u64 v[174:175], v[182:183], 0, s[46:47]
	s_mov_b32 m0, s85
	s_nop 0
	global_load_lds_dwordx4 v[174:175], off
	v_lshl_add_u64 v[174:175], v[184:185], 0, s[46:47]
	s_mov_b32 m0, s86
	s_nop 0
	global_load_lds_dwordx4 v[174:175], off
	s_waitcnt vmcnt(8)
	s_waitcnt lgkmcnt(0)
	s_setprio 1
	s_barrier
	v_mfma_f32_16x16x128_f8f6f4 v[94:97], v[2:9], v[190:197], v[94:97]
	v_mfma_f32_16x16x128_f8f6f4 v[90:93], v[10:17], v[190:197], v[90:93]
	v_mfma_f32_16x16x128_f8f6f4 v[82:85], v[10:17], v[198:205], v[82:85]
	v_mfma_f32_16x16x128_f8f6f4 v[86:89], v[2:9], v[198:205], v[86:89]
	v_mfma_f32_16x16x128_f8f6f4 v[78:81], v[2:9], v[206:213], v[78:81]
	v_mfma_f32_16x16x128_f8f6f4 v[74:77], v[10:17], v[206:213], v[74:77]
	v_mfma_f32_16x16x128_f8f6f4 v[66:69], v[10:17], v[214:221], v[66:69]
	v_mfma_f32_16x16x128_f8f6f4 v[70:73], v[2:9], v[214:221], v[70:73]
	s_setprio 0
	s_setprio 1
	v_mfma_f32_16x16x128_f8f6f4 v[38:41], v[18:25], v[214:221], v[38:41]
	v_mfma_f32_16x16x128_f8f6f4 v[34:37], v[26:33], v[214:221], v[34:37]
	v_mfma_f32_16x16x128_f8f6f4 v[42:45], v[26:33], v[206:213], v[42:45]
	v_mfma_f32_16x16x128_f8f6f4 v[46:49], v[18:25], v[206:213], v[46:49]
	v_mfma_f32_16x16x128_f8f6f4 v[54:57], v[18:25], v[198:205], v[54:57]
	v_mfma_f32_16x16x128_f8f6f4 v[50:53], v[26:33], v[198:205], v[50:53]
	v_mfma_f32_16x16x128_f8f6f4 v[58:61], v[26:33], v[190:197], v[58:61]
	v_mfma_f32_16x16x128_f8f6f4 v[62:65], v[18:25], v[190:197], v[62:65]
	s_setprio 0
	s_barrier
	ds_read_b128 v[2:5], v181
	ds_read_b128 v[6:9], v181 offset:1024
	ds_read_b128 v[10:13], v181 offset:2048
	ds_read_b128 v[14:17], v181 offset:3072
	ds_read_b128 v[18:21], v181 offset:16384
	ds_read_b128 v[22:25], v181 offset:17408
	ds_read_b128 v[26:29], v181 offset:18432
	ds_read_b128 v[30:33], v181 offset:19456
	s_add_u32 s62, s74, 0x40180
	s_addc_u32 s63, s75, 0
	s_mov_b32 m0, s33
	v_lshl_add_u64 v[174:175], s[62:63], 0, v[166:167]
	ds_read_b128 v[190:193], v187
	ds_read_b128 v[194:197], v187 offset:1024
	ds_read_b128 v[198:201], v187 offset:2048
	ds_read_b128 v[202:205], v187 offset:3072
	ds_read_b128 v[206:209], v187 offset:4096
	ds_read_b128 v[210:213], v187 offset:5120
	ds_read_b128 v[214:217], v187 offset:6144
	ds_read_b128 v[218:221], v187 offset:7168
	global_load_lds_dwordx4 v[174:175], off
	v_lshl_add_u64 v[174:175], s[62:63], 0, v[168:169]
	s_mov_b32 m0, s5
	s_nop 0
	global_load_lds_dwordx4 v[174:175], off
	s_waitcnt vmcnt(8)
	s_waitcnt lgkmcnt(0)
	s_setprio 1
	s_barrier
	v_mfma_f32_16x16x128_f8f6f4 v[158:161], v[2:9], v[190:197], v[158:161]
	v_mfma_f32_16x16x128_f8f6f4 v[154:157], v[10:17], v[190:197], v[154:157]
	v_mfma_f32_16x16x128_f8f6f4 v[146:149], v[10:17], v[198:205], v[146:149]
	v_mfma_f32_16x16x128_f8f6f4 v[150:153], v[2:9], v[198:205], v[150:153]
	v_mfma_f32_16x16x128_f8f6f4 v[142:145], v[2:9], v[206:213], v[142:145]
	v_mfma_f32_16x16x128_f8f6f4 v[138:141], v[10:17], v[206:213], v[138:141]
	v_mfma_f32_16x16x128_f8f6f4 v[130:133], v[10:17], v[214:221], v[130:133]
	v_mfma_f32_16x16x128_f8f6f4 v[134:137], v[2:9], v[214:221], v[134:137]
	s_setprio 0
	s_setprio 1
	v_mfma_f32_16x16x128_f8f6f4 v[102:105], v[18:25], v[214:221], v[102:105]
	v_mfma_f32_16x16x128_f8f6f4 v[98:101], v[26:33], v[214:221], v[98:101]
	v_mfma_f32_16x16x128_f8f6f4 v[106:109], v[26:33], v[206:213], v[106:109]
	v_mfma_f32_16x16x128_f8f6f4 v[110:113], v[18:25], v[206:213], v[110:113]
	v_mfma_f32_16x16x128_f8f6f4 v[118:121], v[18:25], v[198:205], v[118:121]
	v_mfma_f32_16x16x128_f8f6f4 v[114:117], v[26:33], v[198:205], v[114:117]
	v_mfma_f32_16x16x128_f8f6f4 v[122:125], v[26:33], v[190:197], v[122:125]
	v_mfma_f32_16x16x128_f8f6f4 v[126:129], v[18:25], v[190:197], v[126:129]
	s_setprio 0
	s_barrier
	s_mov_b32 m0, s9
	v_lshl_add_u64 v[174:175], s[78:79], 0, v[162:163]
	s_add_u32 s62, s78, 0x10000
	ds_read_b128 v[190:193], v187 offset:16384
	ds_read_b128 v[194:197], v187 offset:17408
	ds_read_b128 v[198:201], v187 offset:18432
	ds_read_b128 v[202:205], v187 offset:19456
	ds_read_b128 v[206:209], v187 offset:20480
	ds_read_b128 v[210:213], v187 offset:21504
	ds_read_b128 v[214:217], v187 offset:22528
	ds_read_b128 v[218:221], v187 offset:23552
	global_load_lds_dwordx4 v[174:175], off
	v_lshl_add_u64 v[176:177], s[78:79], 0, v[164:165]
	s_mov_b32 m0, s61
	s_addc_u32 s63, s79, 0
	global_load_lds_dwordx4 v[176:177], off
	v_lshl_add_u64 v[182:183], s[62:63], 0, v[162:163]
	s_mov_b32 m0, s68
	v_lshl_add_u64 v[184:185], s[80:81], 0, v[168:169]
	global_load_lds_dwordx4 v[182:183], off
	v_lshl_add_u64 v[182:183], s[62:63], 0, v[164:165]
	s_mov_b32 m0, s69
	s_nop 0
	global_load_lds_dwordx4 v[182:183], off
	v_lshl_add_u64 v[182:183], s[80:81], 0, v[166:167]
	s_mov_b32 m0, s8
	s_nop 0
	global_load_lds_dwordx4 v[182:183], off
	s_mov_b32 m0, s71
	s_nop 0
	global_load_lds_dwordx4 v[184:185], off
	s_waitcnt vmcnt(8)
	s_waitcnt lgkmcnt(0)
	s_setprio 1
	s_barrier
	v_mfma_f32_16x16x128_f8f6f4 v[94:97], v[2:9], v[190:197], v[94:97]
	v_mfma_f32_16x16x128_f8f6f4 v[90:93], v[10:17], v[190:197], v[90:93]
	v_mfma_f32_16x16x128_f8f6f4 v[82:85], v[10:17], v[198:205], v[82:85]
	v_mfma_f32_16x16x128_f8f6f4 v[86:89], v[2:9], v[198:205], v[86:89]
	v_mfma_f32_16x16x128_f8f6f4 v[78:81], v[2:9], v[206:213], v[78:81]
	v_mfma_f32_16x16x128_f8f6f4 v[74:77], v[10:17], v[206:213], v[74:77]
	v_mfma_f32_16x16x128_f8f6f4 v[66:69], v[10:17], v[214:221], v[66:69]
	v_mfma_f32_16x16x128_f8f6f4 v[70:73], v[2:9], v[214:221], v[70:73]
	s_setprio 0
	s_setprio 1
	v_mfma_f32_16x16x128_f8f6f4 v[38:41], v[18:25], v[214:221], v[38:41]
	v_mfma_f32_16x16x128_f8f6f4 v[34:37], v[26:33], v[214:221], v[34:37]
	v_mfma_f32_16x16x128_f8f6f4 v[42:45], v[26:33], v[206:213], v[42:45]
	v_mfma_f32_16x16x128_f8f6f4 v[46:49], v[18:25], v[206:213], v[46:49]
	v_mfma_f32_16x16x128_f8f6f4 v[54:57], v[18:25], v[198:205], v[54:57]
	v_mfma_f32_16x16x128_f8f6f4 v[50:53], v[26:33], v[198:205], v[50:53]
	v_mfma_f32_16x16x128_f8f6f4 v[58:61], v[26:33], v[190:197], v[58:61]
	v_mfma_f32_16x16x128_f8f6f4 v[62:65], v[18:25], v[190:197], v[62:65]
	s_setprio 0
	s_barrier
	ds_read_b128 v[2:5], v181 offset:32768
	ds_read_b128 v[6:9], v181 offset:33792
	ds_read_b128 v[10:13], v181 offset:34816
	ds_read_b128 v[14:17], v181 offset:35840
	ds_read_b128 v[18:21], v181 offset:49152
	ds_read_b128 v[22:25], v181 offset:50176
	ds_read_b128 v[26:29], v181 offset:51200
	ds_read_b128 v[30:33], v181 offset:52224
	s_add_u32 s62, s80, 0x40000
	s_addc_u32 s63, s81, 0
	s_mov_b32 m0, s73
	v_lshl_add_u64 v[222:223], s[62:63], 0, v[166:167]
	ds_read_b128 v[190:193], v187 offset:32768
	ds_read_b128 v[194:197], v187 offset:33792
	ds_read_b128 v[198:201], v187 offset:34816
	ds_read_b128 v[202:205], v187 offset:35840
	ds_read_b128 v[206:209], v187 offset:36864
	ds_read_b128 v[210:213], v187 offset:37888
	ds_read_b128 v[214:217], v187 offset:38912
	ds_read_b128 v[218:221], v187 offset:39936
	global_load_lds_dwordx4 v[222:223], off
	v_lshl_add_u64 v[222:223], s[62:63], 0, v[168:169]
	s_mov_b32 m0, s82
	s_nop 0
	global_load_lds_dwordx4 v[222:223], off
	s_waitcnt vmcnt(8)
	s_waitcnt lgkmcnt(0)
	s_setprio 1
	s_barrier
	v_mfma_f32_16x16x128_f8f6f4 v[158:161], v[2:9], v[190:197], v[158:161]
	v_mfma_f32_16x16x128_f8f6f4 v[154:157], v[10:17], v[190:197], v[154:157]
	v_mfma_f32_16x16x128_f8f6f4 v[146:149], v[10:17], v[198:205], v[146:149]
	v_mfma_f32_16x16x128_f8f6f4 v[150:153], v[2:9], v[198:205], v[150:153]
	v_mfma_f32_16x16x128_f8f6f4 v[142:145], v[2:9], v[206:213], v[142:145]
	v_mfma_f32_16x16x128_f8f6f4 v[138:141], v[10:17], v[206:213], v[138:141]
	v_mfma_f32_16x16x128_f8f6f4 v[130:133], v[10:17], v[214:221], v[130:133]
	v_mfma_f32_16x16x128_f8f6f4 v[134:137], v[2:9], v[214:221], v[134:137]
	s_setprio 0
	s_setprio 1
	v_mfma_f32_16x16x128_f8f6f4 v[102:105], v[18:25], v[214:221], v[102:105]
	v_mfma_f32_16x16x128_f8f6f4 v[98:101], v[26:33], v[214:221], v[98:101]
	v_mfma_f32_16x16x128_f8f6f4 v[106:109], v[26:33], v[206:213], v[106:109]
	v_mfma_f32_16x16x128_f8f6f4 v[110:113], v[18:25], v[206:213], v[110:113]
	v_mfma_f32_16x16x128_f8f6f4 v[118:121], v[18:25], v[198:205], v[118:121]
	v_mfma_f32_16x16x128_f8f6f4 v[114:117], v[26:33], v[198:205], v[114:117]
	v_mfma_f32_16x16x128_f8f6f4 v[122:125], v[26:33], v[190:197], v[122:125]
	v_mfma_f32_16x16x128_f8f6f4 v[126:129], v[18:25], v[190:197], v[126:129]
	s_setprio 0
	s_barrier
	s_mov_b32 m0, s83
	v_lshl_add_u64 v[174:175], v[174:175], 0, s[38:39]
	s_add_u32 s62, s78, 0x10080
	ds_read_b128 v[190:193], v187 offset:49152
	ds_read_b128 v[194:197], v187 offset:50176
	ds_read_b128 v[198:201], v187 offset:51200
	ds_read_b128 v[202:205], v187 offset:52224
	ds_read_b128 v[206:209], v187 offset:53248
	ds_read_b128 v[210:213], v187 offset:54272
	ds_read_b128 v[214:217], v187 offset:55296
	ds_read_b128 v[218:221], v187 offset:56320
	global_load_lds_dwordx4 v[174:175], off
	v_lshl_add_u64 v[174:175], v[176:177], 0, s[38:39]
	s_mov_b32 m0, s84
	s_addc_u32 s63, s79, 0
	global_load_lds_dwordx4 v[174:175], off
	v_lshl_add_u64 v[174:175], s[62:63], 0, v[162:163]
	s_mov_b32 m0, s87
	s_nop 0
	global_load_lds_dwordx4 v[174:175], off
	v_lshl_add_u64 v[174:175], s[62:63], 0, v[164:165]
	s_mov_b32 m0, s88
	s_nop 0
	global_load_lds_dwordx4 v[174:175], off
	v_lshl_add_u64 v[174:175], v[182:183], 0, s[38:39]
	s_mov_b32 m0, s85
	s_nop 0
	global_load_lds_dwordx4 v[174:175], off
	v_lshl_add_u64 v[174:175], v[184:185], 0, s[38:39]
	s_mov_b32 m0, s86
	s_nop 0
	global_load_lds_dwordx4 v[174:175], off
	s_waitcnt vmcnt(8)
	s_waitcnt lgkmcnt(0)
	s_setprio 1
	s_barrier
	v_mfma_f32_16x16x128_f8f6f4 v[94:97], v[2:9], v[190:197], v[94:97]
	v_mfma_f32_16x16x128_f8f6f4 v[90:93], v[10:17], v[190:197], v[90:93]
	v_mfma_f32_16x16x128_f8f6f4 v[82:85], v[10:17], v[198:205], v[82:85]
	v_mfma_f32_16x16x128_f8f6f4 v[86:89], v[2:9], v[198:205], v[86:89]
	v_mfma_f32_16x16x128_f8f6f4 v[78:81], v[2:9], v[206:213], v[78:81]
	v_mfma_f32_16x16x128_f8f6f4 v[74:77], v[10:17], v[206:213], v[74:77]
	v_mfma_f32_16x16x128_f8f6f4 v[66:69], v[10:17], v[214:221], v[66:69]
	v_mfma_f32_16x16x128_f8f6f4 v[70:73], v[2:9], v[214:221], v[70:73]
	s_setprio 0
	s_setprio 1
	v_mfma_f32_16x16x128_f8f6f4 v[38:41], v[18:25], v[214:221], v[38:41]
	v_mfma_f32_16x16x128_f8f6f4 v[34:37], v[26:33], v[214:221], v[34:37]
	v_mfma_f32_16x16x128_f8f6f4 v[42:45], v[26:33], v[206:213], v[42:45]
	v_mfma_f32_16x16x128_f8f6f4 v[46:49], v[18:25], v[206:213], v[46:49]
	v_mfma_f32_16x16x128_f8f6f4 v[54:57], v[18:25], v[198:205], v[54:57]
	v_mfma_f32_16x16x128_f8f6f4 v[50:53], v[26:33], v[198:205], v[50:53]
	v_mfma_f32_16x16x128_f8f6f4 v[58:61], v[26:33], v[190:197], v[58:61]
	v_mfma_f32_16x16x128_f8f6f4 v[62:65], v[18:25], v[190:197], v[62:65]
	s_setprio 0
	s_barrier
	s_andn2_b64 vcc, exec, s[40:41]
	s_cbranch_vccnz .LBB0_632
	s_barrier

.LBB0_791:
	ds_read_b128 v[2:5], v189
	ds_read_b128 v[6:9], v189 offset:1024
	ds_read_b128 v[192:195], v189 offset:2048
	ds_read_b128 v[196:199], v189 offset:3072
	ds_read_b128 v[200:203], v189 offset:16384
	ds_read_b128 v[204:207], v189 offset:17408
	ds_read_b128 v[208:211], v189 offset:18432
	ds_read_b128 v[212:215], v189 offset:19456
	s_add_u32 s37, s46, 0x100
	s_addc_u32 s39, s47, 0
	s_and_b64 s[50:51], s[48:49], exec
	s_cselect_b32 s51, s1, s39
	s_cselect_b32 s50, s0, s37
	s_add_u32 s37, s44, 0x100
	s_addc_u32 s39, s45, 0
	s_and_b64 s[48:49], s[48:49], exec
	s_cselect_b32 s49, s5, s39
	s_cselect_b32 s48, s4, s37
	s_add_u32 s88, s46, 0x80080
	s_addc_u32 s89, s47, 0
	s_add_i32 s37, s8, 0xc000
	v_lshl_add_u64 v[174:175], s[88:89], 0, v[154:155]
	s_mov_b32 m0, s37
	s_add_i32 s39, s8, 0xe000
	ds_read_b128 v[216:219], v190
	ds_read_b128 v[220:223], v190 offset:1024
	ds_read_b128 v[224:227], v190 offset:2048
	ds_read_b128 v[228:231], v190 offset:3072
	ds_read_b128 v[242:245], v190 offset:4096
	ds_read_b128 v[246:249], v190 offset:5120
	ds_read_b128 v[232:235], v190 offset:6144
	ds_read_b128 v[236:239], v190 offset:7168
	global_load_lds_dwordx4 v[174:175], off
	v_lshl_add_u64 v[174:175], s[88:89], 0, v[158:159]
	s_mov_b32 m0, s39
	s_nop 0
	global_load_lds_dwordx4 v[174:175], off
	s_waitcnt vmcnt(8)
	s_waitcnt lgkmcnt(0)
	s_setprio 1
	s_barrier
	v_mfma_f32_16x16x128_f8f6f4 v[134:137], v[2:9], v[216:223], 0
	v_mfma_f32_16x16x128_f8f6f4 v[130:133], v[192:199], v[216:223], 0
	v_mfma_f32_16x16x128_f8f6f4 v[122:125], v[192:199], v[224:231], 0
	v_mfma_f32_16x16x128_f8f6f4 v[126:129], v[2:9], v[224:231], 0
	v_mfma_f32_16x16x128_f8f6f4 v[118:121], v[2:9], v[242:249], 0
	v_mfma_f32_16x16x128_f8f6f4 v[114:117], v[192:199], v[242:249], 0
	v_mfma_f32_16x16x128_f8f6f4 v[106:109], v[192:199], v[232:239], 0
	v_mfma_f32_16x16x128_f8f6f4 v[110:113], v[2:9], v[232:239], 0
	s_setprio 0
	s_setprio 1
	v_mfma_f32_16x16x128_f8f6f4 v[78:81], v[200:207], v[232:239], 0
	v_mfma_f32_16x16x128_f8f6f4 v[74:77], v[208:215], v[232:239], 0
	v_mfma_f32_16x16x128_f8f6f4 v[82:85], v[208:215], v[242:249], 0
	v_mfma_f32_16x16x128_f8f6f4 v[86:89], v[200:207], v[242:249], 0
	v_mfma_f32_16x16x128_f8f6f4 v[94:97], v[200:207], v[224:231], 0
	v_mfma_f32_16x16x128_f8f6f4 v[90:93], v[208:215], v[224:231], 0
	v_mfma_f32_16x16x128_f8f6f4 v[98:101], v[208:215], v[216:223], 0
	v_mfma_f32_16x16x128_f8f6f4 v[102:105], v[200:207], v[216:223], 0
	s_setprio 0
	s_barrier
	s_mov_b32 m0, s9
	v_lshl_add_u64 v[174:175], s[48:49], 0, v[156:157]
	s_add_u32 s88, s48, 0x80000
	ds_read_b128 v[216:219], v190 offset:16384
	ds_read_b128 v[220:223], v190 offset:17408
	ds_read_b128 v[224:227], v190 offset:18432
	ds_read_b128 v[228:231], v190 offset:19456
	ds_read_b128 v[232:235], v190 offset:20480
	ds_read_b128 v[236:239], v190 offset:21504
	ds_read_b128 v[242:245], v190 offset:22528
	ds_read_b128 v[246:249], v190 offset:23552
	global_load_lds_dwordx4 v[174:175], off
	v_lshl_add_u64 v[176:177], s[48:49], 0, v[160:161]
	s_mov_b32 m0, s27
	s_addc_u32 s89, s49, 0
	global_load_lds_dwordx4 v[176:177], off
	v_lshl_add_u64 v[182:183], s[88:89], 0, v[156:157]
	s_mov_b32 m0, s33
	v_lshl_add_u64 v[184:185], s[50:51], 0, v[158:159]
	global_load_lds_dwordx4 v[182:183], off
	v_lshl_add_u64 v[182:183], s[88:89], 0, v[160:161]
	s_mov_b32 m0, s35
	s_nop 0
	global_load_lds_dwordx4 v[182:183], off
	v_lshl_add_u64 v[182:183], s[50:51], 0, v[154:155]
	s_mov_b32 m0, s8
	s_nop 0
	global_load_lds_dwordx4 v[182:183], off
	s_mov_b32 m0, s43
	s_nop 0
	global_load_lds_dwordx4 v[184:185], off
	s_waitcnt vmcnt(8)
	s_waitcnt lgkmcnt(0)
	s_setprio 1
	s_barrier
	v_mfma_f32_16x16x128_f8f6f4 v[70:73], v[2:9], v[216:223], 0
	v_mfma_f32_16x16x128_f8f6f4 v[66:69], v[192:199], v[216:223], 0
	v_mfma_f32_16x16x128_f8f6f4 v[58:61], v[192:199], v[224:231], 0
	v_mfma_f32_16x16x128_f8f6f4 v[62:65], v[2:9], v[224:231], 0
	v_mfma_f32_16x16x128_f8f6f4 v[54:57], v[2:9], v[232:239], 0
	v_mfma_f32_16x16x128_f8f6f4 v[50:53], v[192:199], v[232:239], 0
	v_mfma_f32_16x16x128_f8f6f4 v[42:45], v[192:199], v[242:249], 0
	v_mfma_f32_16x16x128_f8f6f4 v[46:49], v[2:9], v[242:249], 0
	s_setprio 0
	s_setprio 1
	v_mfma_f32_16x16x128_f8f6f4 v[14:17], v[200:207], v[242:249], 0
	v_mfma_f32_16x16x128_f8f6f4 v[10:13], v[208:215], v[242:249], 0
	v_mfma_f32_16x16x128_f8f6f4 v[18:21], v[208:215], v[232:239], 0
	v_mfma_f32_16x16x128_f8f6f4 v[22:25], v[200:207], v[232:239], 0
	v_mfma_f32_16x16x128_f8f6f4 v[30:33], v[200:207], v[224:231], 0
	v_mfma_f32_16x16x128_f8f6f4 v[26:29], v[208:215], v[224:231], 0
	v_mfma_f32_16x16x128_f8f6f4 v[34:37], v[208:215], v[216:223], 0
	v_mfma_f32_16x16x128_f8f6f4 v[38:41], v[200:207], v[216:223], 0
	s_setprio 0
	s_barrier
	ds_read_b128 v[2:5], v189 offset:32768
	ds_read_b128 v[6:9], v189 offset:33792
	ds_read_b128 v[192:195], v189 offset:34816
	ds_read_b128 v[196:199], v189 offset:35840
	ds_read_b128 v[200:203], v189 offset:49152
	ds_read_b128 v[204:207], v189 offset:50176
	ds_read_b128 v[208:211], v189 offset:51200
	ds_read_b128 v[212:215], v189 offset:52224
	s_add_u32 s50, s50, 0x80000
	s_addc_u32 s51, s51, 0
	s_mov_b32 m0, s52
	v_lshl_add_u64 v[186:187], s[50:51], 0, v[154:155]
	ds_read_b128 v[216:219], v190 offset:32768
	ds_read_b128 v[220:223], v190 offset:33792
	ds_read_b128 v[224:227], v190 offset:34816
	ds_read_b128 v[228:231], v190 offset:35840
	ds_read_b128 v[232:235], v190 offset:36864
	ds_read_b128 v[236:239], v190 offset:37888
	ds_read_b128 v[242:245], v190 offset:38912
	ds_read_b128 v[246:249], v190 offset:39936
	global_load_lds_dwordx4 v[186:187], off
	v_lshl_add_u64 v[186:187], s[50:51], 0, v[158:159]
	s_mov_b32 m0, s53
	s_nop 0
	global_load_lds_dwordx4 v[186:187], off
	s_waitcnt vmcnt(8)
	s_waitcnt lgkmcnt(0)
	s_setprio 1
	s_barrier
	v_mfma_f32_16x16x128_f8f6f4 v[134:137], v[2:9], v[216:223], v[134:137]
	v_mfma_f32_16x16x128_f8f6f4 v[130:133], v[192:199], v[216:223], v[130:133]
	v_mfma_f32_16x16x128_f8f6f4 v[122:125], v[192:199], v[224:231], v[122:125]
	v_mfma_f32_16x16x128_f8f6f4 v[126:129], v[2:9], v[224:231], v[126:129]
	v_mfma_f32_16x16x128_f8f6f4 v[118:121], v[2:9], v[232:239], v[118:121]
	v_mfma_f32_16x16x128_f8f6f4 v[114:117], v[192:199], v[232:239], v[114:117]
	v_mfma_f32_16x16x128_f8f6f4 v[106:109], v[192:199], v[242:249], v[106:109]
	v_mfma_f32_16x16x128_f8f6f4 v[110:113], v[2:9], v[242:249], v[110:113]
	s_setprio 0
	s_setprio 1
	v_mfma_f32_16x16x128_f8f6f4 v[78:81], v[200:207], v[242:249], v[78:81]
	v_mfma_f32_16x16x128_f8f6f4 v[74:77], v[208:215], v[242:249], v[74:77]
	v_mfma_f32_16x16x128_f8f6f4 v[82:85], v[208:215], v[232:239], v[82:85]
	v_mfma_f32_16x16x128_f8f6f4 v[86:89], v[200:207], v[232:239], v[86:89]
	v_mfma_f32_16x16x128_f8f6f4 v[94:97], v[200:207], v[224:231], v[94:97]
	v_mfma_f32_16x16x128_f8f6f4 v[90:93], v[208:215], v[224:231], v[90:93]
	v_mfma_f32_16x16x128_f8f6f4 v[98:101], v[208:215], v[216:223], v[98:101]
	v_mfma_f32_16x16x128_f8f6f4 v[102:105], v[200:207], v[216:223], v[102:105]
	s_setprio 0
	s_barrier
	s_mov_b32 m0, s70
	v_lshl_add_u64 v[174:175], v[174:175], 0, s[18:19]
	s_add_u32 s48, s48, 0x80080
	ds_read_b128 v[216:219], v190 offset:49152
	ds_read_b128 v[220:223], v190 offset:50176
	ds_read_b128 v[224:227], v190 offset:51200
	ds_read_b128 v[228:231], v190 offset:52224
	ds_read_b128 v[232:235], v190 offset:53248
	ds_read_b128 v[236:239], v190 offset:54272
	ds_read_b128 v[242:245], v190 offset:55296
	ds_read_b128 v[246:249], v190 offset:56320
	global_load_lds_dwordx4 v[174:175], off
	v_lshl_add_u64 v[174:175], v[176:177], 0, s[18:19]
	s_mov_b32 m0, s71
	s_addc_u32 s49, s49, 0
	global_load_lds_dwordx4 v[174:175], off
	v_lshl_add_u64 v[174:175], s[48:49], 0, v[156:157]
	s_mov_b32 m0, s74
	s_nop 0
	global_load_lds_dwordx4 v[174:175], off
	v_lshl_add_u64 v[174:175], s[48:49], 0, v[160:161]
	s_mov_b32 m0, s75
	s_nop 0
	global_load_lds_dwordx4 v[174:175], off
	v_lshl_add_u64 v[174:175], v[182:183], 0, s[18:19]
	s_mov_b32 m0, s72
	s_nop 0
	global_load_lds_dwordx4 v[174:175], off
	v_lshl_add_u64 v[174:175], v[184:185], 0, s[18:19]
	s_mov_b32 m0, s73
	s_nop 0
	global_load_lds_dwordx4 v[174:175], off
	s_waitcnt vmcnt(8)
	s_waitcnt lgkmcnt(0)
	s_setprio 1
	s_barrier
	v_mfma_f32_16x16x128_f8f6f4 v[70:73], v[2:9], v[216:223], v[70:73]
	v_mfma_f32_16x16x128_f8f6f4 v[66:69], v[192:199], v[216:223], v[66:69]
	v_mfma_f32_16x16x128_f8f6f4 v[58:61], v[192:199], v[224:231], v[58:61]
	v_mfma_f32_16x16x128_f8f6f4 v[62:65], v[2:9], v[224:231], v[62:65]
	v_mfma_f32_16x16x128_f8f6f4 v[54:57], v[2:9], v[232:239], v[54:57]
	v_mfma_f32_16x16x128_f8f6f4 v[50:53], v[192:199], v[232:239], v[50:53]
	v_mfma_f32_16x16x128_f8f6f4 v[42:45], v[192:199], v[242:249], v[42:45]
	v_mfma_f32_16x16x128_f8f6f4 v[46:49], v[2:9], v[242:249], v[46:49]
	s_setprio 0
	s_setprio 1
	v_mfma_f32_16x16x128_f8f6f4 v[14:17], v[200:207], v[242:249], v[14:17]
	v_mfma_f32_16x16x128_f8f6f4 v[10:13], v[208:215], v[242:249], v[10:13]
	v_mfma_f32_16x16x128_f8f6f4 v[18:21], v[208:215], v[232:239], v[18:21]
	v_mfma_f32_16x16x128_f8f6f4 v[22:25], v[200:207], v[232:239], v[22:25]
	v_mfma_f32_16x16x128_f8f6f4 v[30:33], v[200:207], v[224:231], v[30:33]
	v_mfma_f32_16x16x128_f8f6f4 v[26:29], v[208:215], v[224:231], v[26:29]
	v_mfma_f32_16x16x128_f8f6f4 v[34:37], v[208:215], v[216:223], v[34:37]
	v_mfma_f32_16x16x128_f8f6f4 v[38:41], v[200:207], v[216:223], v[38:41]
	s_setprio 0
	s_barrier
	s_cmp_lt_u32 s86, 3
	s_cbranch_scc1 .LBB0_796
	s_add_u32 s48, s55, s62
	s_addc_u32 s49, s61, s41
	s_add_u32 s46, s46, 0x80180
	s_addc_u32 s47, s47, 0
	s_add_u32 s41, s44, 0x200
	v_lshl_add_u64 v[174:175], v[172:173], 2, s[48:49]
	s_addc_u32 s50, s45, 0
	s_mov_b32 s51, 4
	s_cmp_eq_u32 s86, s51
	s_cselect_b64 s[44:45], -1, 0
	s_cmp_lg_u32 s86, s51
	s_cbranch_scc1 .LBB0_794

.LBB0_794:
	ds_read_b128 v[2:5], v189
	ds_read_b128 v[6:9], v189 offset:1024
	ds_read_b128 v[192:195], v189 offset:2048
	ds_read_b128 v[196:199], v189 offset:3072
	ds_read_b128 v[200:203], v189 offset:16384
	ds_read_b128 v[204:207], v189 offset:17408
	ds_read_b128 v[208:211], v189 offset:18432
	ds_read_b128 v[212:215], v189 offset:19456
	s_add_u32 s48, s46, 0xfff80080
	s_addc_u32 s49, s47, -1
	s_and_b64 s[44:45], s[44:45], exec
	s_cselect_b32 s44, s4, s41
	s_cselect_b32 s49, s1, s49
	s_cselect_b32 s48, s0, s48
	s_cselect_b32 s45, s5, s50
	s_mov_b32 m0, s37
	v_lshl_add_u64 v[176:177], s[46:47], 0, v[162:163]
	ds_read_b128 v[216:219], v190
	ds_read_b128 v[220:223], v190 offset:1024
	ds_read_b128 v[224:227], v190 offset:2048
	ds_read_b128 v[228:231], v190 offset:3072
	ds_read_b128 v[232:235], v190 offset:4096
	ds_read_b128 v[236:239], v190 offset:5120
	ds_read_b128 v[242:245], v190 offset:6144
	ds_read_b128 v[246:249], v190 offset:7168
	global_load_lds_dwordx4 v[176:177], off
	v_lshl_add_u64 v[176:177], s[46:47], 0, v[164:165]
	s_mov_b32 m0, s39
	s_nop 0
	global_load_lds_dwordx4 v[176:177], off
	s_waitcnt vmcnt(8)
	s_waitcnt lgkmcnt(0)
	s_setprio 1
	s_barrier
	v_mfma_f32_16x16x128_f8f6f4 v[134:137], v[2:9], v[216:223], v[134:137]
	v_mfma_f32_16x16x128_f8f6f4 v[130:133], v[192:199], v[216:223], v[130:133]
	v_mfma_f32_16x16x128_f8f6f4 v[122:125], v[192:199], v[224:231], v[122:125]
	v_mfma_f32_16x16x128_f8f6f4 v[126:129], v[2:9], v[224:231], v[126:129]
	v_mfma_f32_16x16x128_f8f6f4 v[118:121], v[2:9], v[232:239], v[118:121]
	v_mfma_f32_16x16x128_f8f6f4 v[114:117], v[192:199], v[232:239], v[114:117]
	v_mfma_f32_16x16x128_f8f6f4 v[106:109], v[192:199], v[242:249], v[106:109]
	v_mfma_f32_16x16x128_f8f6f4 v[110:113], v[2:9], v[242:249], v[110:113]
	s_setprio 0
	s_setprio 1
	v_mfma_f32_16x16x128_f8f6f4 v[78:81], v[200:207], v[242:249], v[78:81]
	v_mfma_f32_16x16x128_f8f6f4 v[74:77], v[208:215], v[242:249], v[74:77]
	v_mfma_f32_16x16x128_f8f6f4 v[82:85], v[208:215], v[232:239], v[82:85]
	v_mfma_f32_16x16x128_f8f6f4 v[86:89], v[200:207], v[232:239], v[86:89]
	v_mfma_f32_16x16x128_f8f6f4 v[94:97], v[200:207], v[224:231], v[94:97]
	v_mfma_f32_16x16x128_f8f6f4 v[90:93], v[208:215], v[224:231], v[90:93]
	v_mfma_f32_16x16x128_f8f6f4 v[98:101], v[208:215], v[216:223], v[98:101]
	v_mfma_f32_16x16x128_f8f6f4 v[102:105], v[200:207], v[216:223], v[102:105]
	s_setprio 0
	s_barrier
	s_mov_b32 m0, s9
	v_lshl_add_u64 v[176:177], s[44:45], 0, v[156:157]
	s_add_u32 s62, s44, 0x80000
	ds_read_b128 v[216:219], v190 offset:16384
	ds_read_b128 v[220:223], v190 offset:17408
	ds_read_b128 v[224:227], v190 offset:18432
	ds_read_b128 v[228:231], v190 offset:19456
	ds_read_b128 v[232:235], v190 offset:20480
	ds_read_b128 v[236:239], v190 offset:21504
	ds_read_b128 v[242:245], v190 offset:22528
	ds_read_b128 v[246:249], v190 offset:23552
	global_load_lds_dwordx4 v[176:177], off
	v_lshl_add_u64 v[182:183], s[44:45], 0, v[160:161]
	s_mov_b32 m0, s27
	s_addc_u32 s63, s45, 0
	global_load_lds_dwordx4 v[182:183], off
	v_lshl_add_u64 v[184:185], s[62:63], 0, v[156:157]
	s_mov_b32 m0, s33
	v_lshl_add_u64 v[186:187], s[48:49], 0, v[158:159]
	global_load_lds_dwordx4 v[184:185], off
	v_lshl_add_u64 v[184:185], s[62:63], 0, v[160:161]
	s_mov_b32 m0, s35
	s_nop 0
	global_load_lds_dwordx4 v[184:185], off
	v_lshl_add_u64 v[184:185], s[48:49], 0, v[154:155]
	s_mov_b32 m0, s8
	s_nop 0
	global_load_lds_dwordx4 v[184:185], off
	s_mov_b32 m0, s43
	s_nop 0
	global_load_lds_dwordx4 v[186:187], off
	s_waitcnt vmcnt(8)
	s_waitcnt lgkmcnt(0)
	s_setprio 1
	s_barrier
	v_mfma_f32_16x16x128_f8f6f4 v[70:73], v[2:9], v[216:223], v[70:73]
	v_mfma_f32_16x16x128_f8f6f4 v[66:69], v[192:199], v[216:223], v[66:69]
	v_mfma_f32_16x16x128_f8f6f4 v[58:61], v[192:199], v[224:231], v[58:61]
	v_mfma_f32_16x16x128_f8f6f4 v[62:65], v[2:9], v[224:231], v[62:65]
	v_mfma_f32_16x16x128_f8f6f4 v[54:57], v[2:9], v[232:239], v[54:57]
	v_mfma_f32_16x16x128_f8f6f4 v[50:53], v[192:199], v[232:239], v[50:53]
	v_mfma_f32_16x16x128_f8f6f4 v[42:45], v[192:199], v[242:249], v[42:45]
	v_mfma_f32_16x16x128_f8f6f4 v[46:49], v[2:9], v[242:249], v[46:49]
	s_setprio 0
	s_setprio 1
	v_mfma_f32_16x16x128_f8f6f4 v[14:17], v[200:207], v[242:249], v[14:17]
	v_mfma_f32_16x16x128_f8f6f4 v[10:13], v[208:215], v[242:249], v[10:13]
	v_mfma_f32_16x16x128_f8f6f4 v[18:21], v[208:215], v[232:239], v[18:21]
	v_mfma_f32_16x16x128_f8f6f4 v[22:25], v[200:207], v[232:239], v[22:25]
	v_mfma_f32_16x16x128_f8f6f4 v[30:33], v[200:207], v[224:231], v[30:33]
	v_mfma_f32_16x16x128_f8f6f4 v[26:29], v[208:215], v[224:231], v[26:29]
	v_mfma_f32_16x16x128_f8f6f4 v[34:37], v[208:215], v[216:223], v[34:37]
	v_mfma_f32_16x16x128_f8f6f4 v[38:41], v[200:207], v[216:223], v[38:41]
	s_setprio 0
	s_barrier
	ds_read_b128 v[192:195], v189 offset:32768
	ds_read_b128 v[196:199], v189 offset:33792
	ds_read_b128 v[200:203], v189 offset:34816
	ds_read_b128 v[204:207], v189 offset:35840
	ds_read_b128 v[2:5], v189 offset:49152
	ds_read_b128 v[6:9], v189 offset:50176
	ds_read_b128 v[208:211], v189 offset:51200
	ds_read_b128 v[212:215], v189 offset:52224
	s_add_u32 s48, s48, 0x80000
	s_addc_u32 s49, s49, 0
	s_mov_b32 m0, s52
	v_lshl_add_u64 v[252:253], s[48:49], 0, v[154:155]
	ds_read_b128 v[216:219], v190 offset:32768
	ds_read_b128 v[220:223], v190 offset:33792
	ds_read_b128 v[224:227], v190 offset:34816
	ds_read_b128 v[228:231], v190 offset:35840
	ds_read_b128 v[232:235], v190 offset:36864
	ds_read_b128 v[236:239], v190 offset:37888
	ds_read_b128 v[242:245], v190 offset:38912
	ds_read_b128 v[246:249], v190 offset:39936
	global_load_lds_dwordx4 v[252:253], off
	v_lshl_add_u64 v[252:253], s[48:49], 0, v[158:159]
	s_mov_b32 m0, s53
	s_nop 0
	global_load_lds_dwordx4 v[252:253], off
	s_waitcnt vmcnt(8)
	s_waitcnt lgkmcnt(0)
	s_setprio 1
	s_barrier
	v_mfma_f32_16x16x128_f8f6f4 v[134:137], v[192:199], v[216:223], v[134:137]
	v_mfma_f32_16x16x128_f8f6f4 v[130:133], v[200:207], v[216:223], v[130:133]
	v_mfma_f32_16x16x128_f8f6f4 v[122:125], v[200:207], v[224:231], v[122:125]
	v_mfma_f32_16x16x128_f8f6f4 v[126:129], v[192:199], v[224:231], v[126:129]
	v_mfma_f32_16x16x128_f8f6f4 v[118:121], v[192:199], v[232:239], v[118:121]
	v_mfma_f32_16x16x128_f8f6f4 v[114:117], v[200:207], v[232:239], v[114:117]
	v_mfma_f32_16x16x128_f8f6f4 v[106:109], v[200:207], v[242:249], v[106:109]
	v_mfma_f32_16x16x128_f8f6f4 v[110:113], v[192:199], v[242:249], v[110:113]
	s_setprio 0
	s_setprio 1
	v_mfma_f32_16x16x128_f8f6f4 v[78:81], v[2:9], v[242:249], v[78:81]
	v_mfma_f32_16x16x128_f8f6f4 v[74:77], v[208:215], v[242:249], v[74:77]
	v_mfma_f32_16x16x128_f8f6f4 v[82:85], v[208:215], v[232:239], v[82:85]
	v_mfma_f32_16x16x128_f8f6f4 v[86:89], v[2:9], v[232:239], v[86:89]
	v_mfma_f32_16x16x128_f8f6f4 v[94:97], v[2:9], v[224:231], v[94:97]
	v_mfma_f32_16x16x128_f8f6f4 v[90:93], v[208:215], v[224:231], v[90:93]
	v_mfma_f32_16x16x128_f8f6f4 v[98:101], v[208:215], v[216:223], v[98:101]
	v_mfma_f32_16x16x128_f8f6f4 v[102:105], v[2:9], v[216:223], v[102:105]
	s_setprio 0
	s_barrier
	s_mov_b32 m0, s70
	v_lshl_add_u64 v[176:177], v[176:177], 0, s[18:19]
	s_add_u32 s44, s44, 0x80080
	ds_read_b128 v[216:219], v190 offset:49152
	ds_read_b128 v[220:223], v190 offset:50176
	ds_read_b128 v[224:227], v190 offset:51200
	ds_read_b128 v[228:231], v190 offset:52224
	ds_read_b128 v[232:235], v190 offset:53248
	ds_read_b128 v[236:239], v190 offset:54272
	ds_read_b128 v[242:245], v190 offset:55296
	ds_read_b128 v[246:249], v190 offset:56320
	global_load_lds_dwordx4 v[176:177], off
	v_lshl_add_u64 v[176:177], v[182:183], 0, s[18:19]
	s_mov_b32 m0, s71
	s_addc_u32 s45, s45, 0
	global_load_lds_dwordx4 v[176:177], off
	v_lshl_add_u64 v[176:177], s[44:45], 0, v[156:157]
	s_mov_b32 m0, s74
	s_nop 0
	global_load_lds_dwordx4 v[176:177], off
	v_lshl_add_u64 v[176:177], s[44:45], 0, v[160:161]
	s_mov_b32 m0, s75
	s_nop 0
	global_load_lds_dwordx4 v[176:177], off
	v_lshl_add_u64 v[176:177], v[184:185], 0, s[18:19]
	s_mov_b32 m0, s72
	s_nop 0
	global_load_lds_dwordx4 v[176:177], off
	v_lshl_add_u64 v[176:177], v[186:187], 0, s[18:19]
	s_mov_b32 m0, s73
	s_nop 0
	global_load_lds_dwordx4 v[176:177], off
	s_waitcnt vmcnt(8)
	s_waitcnt lgkmcnt(0)
	s_setprio 1
	s_barrier
	v_mfma_f32_16x16x128_f8f6f4 v[70:73], v[192:199], v[216:223], v[70:73]
	v_mfma_f32_16x16x128_f8f6f4 v[66:69], v[200:207], v[216:223], v[66:69]
	v_mfma_f32_16x16x128_f8f6f4 v[58:61], v[200:207], v[224:231], v[58:61]
	v_mfma_f32_16x16x128_f8f6f4 v[62:65], v[192:199], v[224:231], v[62:65]
	v_mfma_f32_16x16x128_f8f6f4 v[54:57], v[192:199], v[232:239], v[54:57]
	v_mfma_f32_16x16x128_f8f6f4 v[50:53], v[200:207], v[232:239], v[50:53]
	v_mfma_f32_16x16x128_f8f6f4 v[42:45], v[200:207], v[242:249], v[42:45]
	v_mfma_f32_16x16x128_f8f6f4 v[46:49], v[192:199], v[242:249], v[46:49]
	s_setprio 0
	s_setprio 1
	v_mfma_f32_16x16x128_f8f6f4 v[14:17], v[2:9], v[242:249], v[14:17]
	v_mfma_f32_16x16x128_f8f6f4 v[10:13], v[208:215], v[242:249], v[10:13]
	v_mfma_f32_16x16x128_f8f6f4 v[18:21], v[208:215], v[232:239], v[18:21]
	v_mfma_f32_16x16x128_f8f6f4 v[22:25], v[2:9], v[232:239], v[22:25]
	v_mfma_f32_16x16x128_f8f6f4 v[30:33], v[2:9], v[224:231], v[30:33]
	v_mfma_f32_16x16x128_f8f6f4 v[26:29], v[208:215], v[224:231], v[26:29]
	v_mfma_f32_16x16x128_f8f6f4 v[34:37], v[208:215], v[216:223], v[34:37]
	v_mfma_f32_16x16x128_f8f6f4 v[38:41], v[2:9], v[216:223], v[38:41]
	s_setprio 0
	s_barrier
	s_add_i32 s44, s51, 2
	s_add_u32 s46, s46, 0x100
	s_addc_u32 s47, s47, 0
	s_add_u32 s41, s41, 0x100
	s_addc_u32 s50, s50, 0
	s_cmp_ge_i32 s51, s86
	s_cbranch_scc1 .LBB0_796
	s_mov_b32 s51, s44
	s_cmp_eq_u32 s86, s51
	s_cselect_b64 s[44:45], -1, 0
	s_cmp_lg_u32 s86, s51
	s_cbranch_scc0 .LBB0_793
	s_branch .LBB0_794

.LBB0_946:
	s_ashr_i32 s37, s36, 31
	ds_read_b128 v[18:21], v192
	ds_read_b128 v[22:25], v192 offset:1024
	ds_read_b128 v[26:29], v192 offset:2048
	ds_read_b128 v[30:33], v192 offset:3072
	ds_read_b128 v[2:5], v192 offset:16384
	ds_read_b128 v[6:9], v192 offset:17408
	ds_read_b128 v[10:13], v192 offset:18432
	ds_read_b128 v[14:17], v192 offset:19456
	s_lshl_b64 s[38:39], s[36:37], 20
	s_add_u32 s38, s22, s38
	s_addc_u32 s39, s23, s39
	s_and_b64 s[40:41], s[2:3], exec
	s_cselect_b32 s37, s39, s47
	s_cselect_b32 s84, s38, s46
	s_ashr_i32 s27, s26, 31
	s_lshl_b64 s[40:41], s[26:27], 20
	s_add_u32 s40, s25, s40
	s_addc_u32 s41, s35, s41
	s_and_b64 s[48:49], s[2:3], exec
	s_cselect_b32 s27, s41, s45
	s_cselect_b32 s85, s40, s44
	s_add_u32 s48, s46, 0x80080
	s_addc_u32 s49, s47, 0
	s_mov_b32 m0, s80
	v_lshl_add_u64 v[218:219], s[48:49], 0, v[164:165]
	ds_read_b128 v[184:187], v193
	ds_read_b128 v[188:191], v193 offset:1024
	ds_read_b128 v[194:197], v193 offset:2048
	ds_read_b128 v[198:201], v193 offset:3072
	ds_read_b128 v[202:205], v193 offset:4096
	ds_read_b128 v[206:209], v193 offset:5120
	ds_read_b128 v[210:213], v193 offset:6144
	ds_read_b128 v[214:217], v193 offset:7168
	global_load_lds_dwordx4 v[218:219], off
	v_lshl_add_u64 v[218:219], s[48:49], 0, v[168:169]
	s_mov_b32 m0, s81
	s_nop 0
	global_load_lds_dwordx4 v[218:219], off
	s_waitcnt vmcnt(8)
	s_waitcnt lgkmcnt(0)
	s_setprio 1
	s_barrier
	v_mfma_f32_16x16x128_f8f6f4 v[158:161], v[18:25], v[184:191], 0
	v_mfma_f32_16x16x128_f8f6f4 v[154:157], v[26:33], v[184:191], 0
	v_mfma_f32_16x16x128_f8f6f4 v[146:149], v[26:33], v[194:201], 0
	v_mfma_f32_16x16x128_f8f6f4 v[150:153], v[18:25], v[194:201], 0
	v_mfma_f32_16x16x128_f8f6f4 v[142:145], v[18:25], v[202:209], 0
	v_mfma_f32_16x16x128_f8f6f4 v[138:141], v[26:33], v[202:209], 0
	v_mfma_f32_16x16x128_f8f6f4 v[130:133], v[26:33], v[210:217], 0
	v_mfma_f32_16x16x128_f8f6f4 v[134:137], v[18:25], v[210:217], 0
	s_setprio 0
	s_setprio 1
	v_mfma_f32_16x16x128_f8f6f4 v[102:105], v[2:9], v[210:217], 0
	v_mfma_f32_16x16x128_f8f6f4 v[98:101], v[10:17], v[210:217], 0
	v_mfma_f32_16x16x128_f8f6f4 v[106:109], v[10:17], v[202:209], 0
	v_mfma_f32_16x16x128_f8f6f4 v[110:113], v[2:9], v[202:209], 0
	v_mfma_f32_16x16x128_f8f6f4 v[118:121], v[2:9], v[194:201], 0
	v_mfma_f32_16x16x128_f8f6f4 v[114:117], v[10:17], v[194:201], 0
	v_mfma_f32_16x16x128_f8f6f4 v[122:125], v[10:17], v[184:191], 0
	v_mfma_f32_16x16x128_f8f6f4 v[126:129], v[2:9], v[184:191], 0
	s_setprio 0
	s_barrier
	v_lshl_add_u64 v[184:185], s[44:45], 0, v[166:167]
	s_mov_b32 m0, s52
	v_lshl_add_u64 v[186:187], v[184:185], 0, s[14:15]
	ds_read_b128 v[194:197], v193 offset:16384
	ds_read_b128 v[198:201], v193 offset:17408
	ds_read_b128 v[202:205], v193 offset:18432
	ds_read_b128 v[206:209], v193 offset:19456
	ds_read_b128 v[210:213], v193 offset:20480
	ds_read_b128 v[214:217], v193 offset:21504
	ds_read_b128 v[218:221], v193 offset:22528
	ds_read_b128 v[222:225], v193 offset:23552
	global_load_lds_dwordx4 v[186:187], off
	v_lshl_add_u64 v[186:187], s[44:45], 0, v[170:171]
	s_add_u32 s48, s44, 0x80100
	v_lshl_add_u64 v[188:189], v[186:187], 0, s[14:15]
	s_mov_b32 m0, s53
	s_addc_u32 s49, s45, 0
	global_load_lds_dwordx4 v[188:189], off
	v_lshl_add_u64 v[188:189], s[48:49], 0, v[166:167]
	s_mov_b32 m0, s54
	s_nop 0
	global_load_lds_dwordx4 v[188:189], off
	v_lshl_add_u64 v[188:189], s[48:49], 0, v[170:171]
	s_mov_b32 m0, s55
	s_nop 0
	global_load_lds_dwordx4 v[188:189], off
	v_lshl_add_u64 v[188:189], s[46:47], 0, v[164:165]
	v_lshl_add_u64 v[190:191], v[188:189], 0, s[14:15]
	s_mov_b32 m0, s43
	s_nop 0
	global_load_lds_dwordx4 v[190:191], off
	v_lshl_add_u64 v[190:191], s[46:47], 0, v[168:169]
	v_lshl_add_u64 v[226:227], v[190:191], 0, s[14:15]
	s_mov_b32 m0, s61
	s_nop 0
	global_load_lds_dwordx4 v[226:227], off
	s_waitcnt vmcnt(8)
	s_waitcnt lgkmcnt(0)
	s_setprio 1
	s_barrier
	v_mfma_f32_16x16x128_f8f6f4 v[94:97], v[18:25], v[194:201], 0
	v_mfma_f32_16x16x128_f8f6f4 v[90:93], v[26:33], v[194:201], 0
	v_mfma_f32_16x16x128_f8f6f4 v[82:85], v[26:33], v[202:209], 0
	v_mfma_f32_16x16x128_f8f6f4 v[86:89], v[18:25], v[202:209], 0
	v_mfma_f32_16x16x128_f8f6f4 v[78:81], v[18:25], v[210:217], 0
	v_mfma_f32_16x16x128_f8f6f4 v[74:77], v[26:33], v[210:217], 0
	v_mfma_f32_16x16x128_f8f6f4 v[66:69], v[26:33], v[218:225], 0
	v_mfma_f32_16x16x128_f8f6f4 v[70:73], v[18:25], v[218:225], 0
	s_setprio 0
	s_setprio 1
	v_mfma_f32_16x16x128_f8f6f4 v[38:41], v[2:9], v[218:225], 0
	v_mfma_f32_16x16x128_f8f6f4 v[34:37], v[10:17], v[218:225], 0
	v_mfma_f32_16x16x128_f8f6f4 v[42:45], v[10:17], v[210:217], 0
	v_mfma_f32_16x16x128_f8f6f4 v[46:49], v[2:9], v[210:217], 0
	v_mfma_f32_16x16x128_f8f6f4 v[54:57], v[2:9], v[202:209], 0
	v_mfma_f32_16x16x128_f8f6f4 v[50:53], v[10:17], v[202:209], 0
	v_mfma_f32_16x16x128_f8f6f4 v[58:61], v[10:17], v[194:201], 0
	v_mfma_f32_16x16x128_f8f6f4 v[62:65], v[2:9], v[194:201], 0
	s_setprio 0
	s_barrier
	ds_read_b128 v[18:21], v192 offset:32768
	ds_read_b128 v[22:25], v192 offset:33792
	ds_read_b128 v[26:29], v192 offset:34816
	ds_read_b128 v[30:33], v192 offset:35840
	ds_read_b128 v[2:5], v192 offset:49152
	ds_read_b128 v[6:9], v192 offset:50176
	ds_read_b128 v[10:13], v192 offset:51200
	ds_read_b128 v[14:17], v192 offset:52224
	s_add_u32 s48, s46, 0x80100
	s_addc_u32 s49, s47, 0
	s_mov_b32 m0, s68
	v_lshl_add_u64 v[226:227], s[48:49], 0, v[164:165]
	ds_read_b128 v[194:197], v193 offset:32768
	ds_read_b128 v[198:201], v193 offset:33792
	ds_read_b128 v[202:205], v193 offset:34816
	ds_read_b128 v[206:209], v193 offset:35840
	ds_read_b128 v[210:213], v193 offset:36864
	ds_read_b128 v[214:217], v193 offset:37888
	ds_read_b128 v[218:221], v193 offset:38912
	ds_read_b128 v[222:225], v193 offset:39936
	global_load_lds_dwordx4 v[226:227], off
	v_lshl_add_u64 v[226:227], s[48:49], 0, v[168:169]
	s_mov_b32 m0, s69
	s_nop 0
	global_load_lds_dwordx4 v[226:227], off
	s_waitcnt vmcnt(8)
	s_waitcnt lgkmcnt(0)
	s_setprio 1
	s_barrier
	v_mfma_f32_16x16x128_f8f6f4 v[158:161], v[18:25], v[194:201], v[158:161]
	v_mfma_f32_16x16x128_f8f6f4 v[154:157], v[26:33], v[194:201], v[154:157]
	v_mfma_f32_16x16x128_f8f6f4 v[146:149], v[26:33], v[202:209], v[146:149]
	v_mfma_f32_16x16x128_f8f6f4 v[150:153], v[18:25], v[202:209], v[150:153]
	v_mfma_f32_16x16x128_f8f6f4 v[142:145], v[18:25], v[210:217], v[142:145]
	v_mfma_f32_16x16x128_f8f6f4 v[138:141], v[26:33], v[210:217], v[138:141]
	v_mfma_f32_16x16x128_f8f6f4 v[130:133], v[26:33], v[218:225], v[130:133]
	v_mfma_f32_16x16x128_f8f6f4 v[134:137], v[18:25], v[218:225], v[134:137]
	s_setprio 0
	s_setprio 1
	v_mfma_f32_16x16x128_f8f6f4 v[102:105], v[2:9], v[218:225], v[102:105]
	v_mfma_f32_16x16x128_f8f6f4 v[98:101], v[10:17], v[218:225], v[98:101]
	v_mfma_f32_16x16x128_f8f6f4 v[106:109], v[10:17], v[210:217], v[106:109]
	v_mfma_f32_16x16x128_f8f6f4 v[110:113], v[2:9], v[210:217], v[110:113]
	v_mfma_f32_16x16x128_f8f6f4 v[118:121], v[2:9], v[202:209], v[118:121]
	v_mfma_f32_16x16x128_f8f6f4 v[114:117], v[10:17], v[202:209], v[114:117]
	v_mfma_f32_16x16x128_f8f6f4 v[122:125], v[10:17], v[194:201], v[122:125]
	v_mfma_f32_16x16x128_f8f6f4 v[126:129], v[2:9], v[194:201], v[126:129]
	s_setprio 0
	s_barrier
	s_mov_b32 m0, s74
	v_lshl_add_u64 v[184:185], v[184:185], 0, s[18:19]
	s_add_u32 s48, s44, 0x80180
	ds_read_b128 v[194:197], v193 offset:49152
	ds_read_b128 v[198:201], v193 offset:50176
	ds_read_b128 v[202:205], v193 offset:51200
	ds_read_b128 v[206:209], v193 offset:52224
	ds_read_b128 v[210:213], v193 offset:53248
	ds_read_b128 v[214:217], v193 offset:54272
	ds_read_b128 v[218:221], v193 offset:55296
	ds_read_b128 v[222:225], v193 offset:56320
	global_load_lds_dwordx4 v[184:185], off
	v_lshl_add_u64 v[184:185], v[186:187], 0, s[18:19]
	s_mov_b32 m0, s75
	s_addc_u32 s49, s45, 0
	global_load_lds_dwordx4 v[184:185], off
	v_lshl_add_u64 v[184:185], s[48:49], 0, v[166:167]
	s_mov_b32 m0, s78
	s_nop 0
	global_load_lds_dwordx4 v[184:185], off
	v_lshl_add_u64 v[184:185], s[48:49], 0, v[170:171]
	s_mov_b32 m0, s79
	s_nop 0
	global_load_lds_dwordx4 v[184:185], off
	v_lshl_add_u64 v[184:185], v[188:189], 0, s[18:19]
	s_mov_b32 m0, s76
	s_nop 0
	global_load_lds_dwordx4 v[184:185], off
	v_lshl_add_u64 v[184:185], v[190:191], 0, s[18:19]
	s_mov_b32 m0, s77
	s_nop 0
	global_load_lds_dwordx4 v[184:185], off
	s_waitcnt vmcnt(8)
	s_waitcnt lgkmcnt(0)
	s_setprio 1
	s_barrier
	v_mfma_f32_16x16x128_f8f6f4 v[94:97], v[18:25], v[194:201], v[94:97]
	v_mfma_f32_16x16x128_f8f6f4 v[90:93], v[26:33], v[194:201], v[90:93]
	v_mfma_f32_16x16x128_f8f6f4 v[82:85], v[26:33], v[202:209], v[82:85]
	v_mfma_f32_16x16x128_f8f6f4 v[86:89], v[18:25], v[202:209], v[86:89]
	v_mfma_f32_16x16x128_f8f6f4 v[78:81], v[18:25], v[210:217], v[78:81]
	v_mfma_f32_16x16x128_f8f6f4 v[74:77], v[26:33], v[210:217], v[74:77]
	v_mfma_f32_16x16x128_f8f6f4 v[66:69], v[26:33], v[218:225], v[66:69]
	v_mfma_f32_16x16x128_f8f6f4 v[70:73], v[18:25], v[218:225], v[70:73]
	s_setprio 0
	s_setprio 1
	v_mfma_f32_16x16x128_f8f6f4 v[38:41], v[2:9], v[218:225], v[38:41]
	v_mfma_f32_16x16x128_f8f6f4 v[34:37], v[10:17], v[218:225], v[34:37]
	v_mfma_f32_16x16x128_f8f6f4 v[42:45], v[10:17], v[210:217], v[42:45]
	v_mfma_f32_16x16x128_f8f6f4 v[46:49], v[2:9], v[210:217], v[46:49]
	v_mfma_f32_16x16x128_f8f6f4 v[54:57], v[2:9], v[202:209], v[54:57]
	v_mfma_f32_16x16x128_f8f6f4 v[50:53], v[10:17], v[202:209], v[50:53]
	v_mfma_f32_16x16x128_f8f6f4 v[58:61], v[10:17], v[194:201], v[58:61]
	v_mfma_f32_16x16x128_f8f6f4 v[62:65], v[2:9], v[194:201], v[62:65]
	s_setprio 0
	s_barrier
	s_add_u32 s46, s46, 0x80180
	s_addc_u32 s47, s47, 0
	s_add_u32 s62, s44, 0x200
	s_addc_u32 s63, s45, 0
	s_mov_b32 s86, 0
.LBB0_947:
	ds_read_b128 v[2:5], v192
	ds_read_b128 v[6:9], v192 offset:1024
	ds_read_b128 v[18:21], v192 offset:2048
	ds_read_b128 v[22:25], v192 offset:3072
	ds_read_b128 v[26:29], v192 offset:16384
	ds_read_b128 v[30:33], v192 offset:17408
	ds_read_b128 v[184:187], v192 offset:18432
	ds_read_b128 v[188:191], v192 offset:19456
	s_add_u32 s44, s46, 0xfff80080
	s_addc_u32 s45, s47, -1
	s_cmp_eq_u32 s86, 28
	s_cselect_b32 s49, s37, s45
	s_cselect_b32 s48, s84, s44
	s_cselect_b32 s45, s27, s63
	s_cselect_b32 s44, s85, s62
	s_mov_b32 m0, s80
	v_lshl_add_u64 v[218:219], s[46:47], 0, v[172:173]
	ds_read_b128 v[10:13], v193
	ds_read_b128 v[14:17], v193 offset:1024
	ds_read_b128 v[194:197], v193 offset:2048
	ds_read_b128 v[198:201], v193 offset:3072
	ds_read_b128 v[202:205], v193 offset:4096
	ds_read_b128 v[206:209], v193 offset:5120
	ds_read_b128 v[210:213], v193 offset:6144
	ds_read_b128 v[214:217], v193 offset:7168
	global_load_lds_dwordx4 v[218:219], off
	v_lshl_add_u64 v[218:219], s[46:47], 0, v[174:175]
	s_mov_b32 m0, s81
	s_nop 0
	global_load_lds_dwordx4 v[218:219], off
	s_waitcnt vmcnt(8)
	s_waitcnt lgkmcnt(0)
	s_setprio 1
	s_barrier
	v_mfma_f32_16x16x128_f8f6f4 v[158:161], v[2:9], v[10:17], v[158:161]
	v_mfma_f32_16x16x128_f8f6f4 v[154:157], v[18:25], v[10:17], v[154:157]
	v_mfma_f32_16x16x128_f8f6f4 v[146:149], v[18:25], v[194:201], v[146:149]
	v_mfma_f32_16x16x128_f8f6f4 v[150:153], v[2:9], v[194:201], v[150:153]
	v_mfma_f32_16x16x128_f8f6f4 v[142:145], v[2:9], v[202:209], v[142:145]
	v_mfma_f32_16x16x128_f8f6f4 v[138:141], v[18:25], v[202:209], v[138:141]
	v_mfma_f32_16x16x128_f8f6f4 v[130:133], v[18:25], v[210:217], v[130:133]
	v_mfma_f32_16x16x128_f8f6f4 v[134:137], v[2:9], v[210:217], v[134:137]
	s_setprio 0
	s_setprio 1
	v_mfma_f32_16x16x128_f8f6f4 v[102:105], v[26:33], v[210:217], v[102:105]
	v_mfma_f32_16x16x128_f8f6f4 v[98:101], v[184:191], v[210:217], v[98:101]
	v_mfma_f32_16x16x128_f8f6f4 v[106:109], v[184:191], v[202:209], v[106:109]
	v_mfma_f32_16x16x128_f8f6f4 v[110:113], v[26:33], v[202:209], v[110:113]
	v_mfma_f32_16x16x128_f8f6f4 v[118:121], v[26:33], v[194:201], v[118:121]
	v_mfma_f32_16x16x128_f8f6f4 v[114:117], v[184:191], v[194:201], v[114:117]
	v_mfma_f32_16x16x128_f8f6f4 v[122:125], v[184:191], v[10:17], v[122:125]
	v_mfma_f32_16x16x128_f8f6f4 v[126:129], v[26:33], v[10:17], v[126:129]
	s_setprio 0
	s_barrier
	s_mov_b32 m0, s52
	v_lshl_add_u64 v[10:11], s[44:45], 0, v[166:167]
	s_add_u32 s88, s44, 0x80000
	ds_read_b128 v[194:197], v193 offset:16384
	ds_read_b128 v[198:201], v193 offset:17408
	ds_read_b128 v[202:205], v193 offset:18432
	ds_read_b128 v[206:209], v193 offset:19456
	ds_read_b128 v[210:213], v193 offset:20480
	ds_read_b128 v[214:217], v193 offset:21504
	ds_read_b128 v[218:221], v193 offset:22528
	ds_read_b128 v[222:225], v193 offset:23552
	global_load_lds_dwordx4 v[10:11], off
	v_lshl_add_u64 v[12:13], s[44:45], 0, v[170:171]
	s_mov_b32 m0, s53
	s_addc_u32 s89, s45, 0
	global_load_lds_dwordx4 v[12:13], off
	v_lshl_add_u64 v[14:15], s[88:89], 0, v[166:167]
	s_mov_b32 m0, s54
	v_lshl_add_u64 v[16:17], s[48:49], 0, v[168:169]
	global_load_lds_dwordx4 v[14:15], off
	v_lshl_add_u64 v[14:15], s[88:89], 0, v[170:171]
	s_mov_b32 m0, s55
	s_nop 0
	global_load_lds_dwordx4 v[14:15], off
	v_lshl_add_u64 v[14:15], s[48:49], 0, v[164:165]
	s_mov_b32 m0, s43
	s_nop 0
	global_load_lds_dwordx4 v[14:15], off
	s_mov_b32 m0, s61
	s_nop 0
	global_load_lds_dwordx4 v[16:17], off
	s_waitcnt vmcnt(8)
	s_waitcnt lgkmcnt(0)
	s_setprio 1
	s_barrier
	v_mfma_f32_16x16x128_f8f6f4 v[94:97], v[2:9], v[194:201], v[94:97]
	v_mfma_f32_16x16x128_f8f6f4 v[90:93], v[18:25], v[194:201], v[90:93]
	v_mfma_f32_16x16x128_f8f6f4 v[82:85], v[18:25], v[202:209], v[82:85]
	v_mfma_f32_16x16x128_f8f6f4 v[86:89], v[2:9], v[202:209], v[86:89]
	v_mfma_f32_16x16x128_f8f6f4 v[78:81], v[2:9], v[210:217], v[78:81]
	v_mfma_f32_16x16x128_f8f6f4 v[74:77], v[18:25], v[210:217], v[74:77]
	v_mfma_f32_16x16x128_f8f6f4 v[66:69], v[18:25], v[218:225], v[66:69]
	v_mfma_f32_16x16x128_f8f6f4 v[70:73], v[2:9], v[218:225], v[70:73]
	s_setprio 0
	s_setprio 1
	v_mfma_f32_16x16x128_f8f6f4 v[38:41], v[26:33], v[218:225], v[38:41]
	v_mfma_f32_16x16x128_f8f6f4 v[34:37], v[184:191], v[218:225], v[34:37]
	v_mfma_f32_16x16x128_f8f6f4 v[42:45], v[184:191], v[210:217], v[42:45]
	v_mfma_f32_16x16x128_f8f6f4 v[46:49], v[26:33], v[210:217], v[46:49]
	v_mfma_f32_16x16x128_f8f6f4 v[54:57], v[26:33], v[202:209], v[54:57]
	v_mfma_f32_16x16x128_f8f6f4 v[50:53], v[184:191], v[202:209], v[50:53]
	v_mfma_f32_16x16x128_f8f6f4 v[58:61], v[184:191], v[194:201], v[58:61]
	v_mfma_f32_16x16x128_f8f6f4 v[62:65], v[26:33], v[194:201], v[62:65]
	s_setprio 0
	s_barrier
	ds_read_b128 v[18:21], v192 offset:32768
	ds_read_b128 v[22:25], v192 offset:33792
	ds_read_b128 v[26:29], v192 offset:34816
	ds_read_b128 v[30:33], v192 offset:35840
	ds_read_b128 v[2:5], v192 offset:49152
	ds_read_b128 v[6:9], v192 offset:50176
	ds_read_b128 v[184:187], v192 offset:51200
	ds_read_b128 v[188:191], v192 offset:52224
	s_add_u32 s48, s48, 0x80000
	s_addc_u32 s49, s49, 0
	s_mov_b32 m0, s68
	v_lshl_add_u64 v[226:227], s[48:49], 0, v[164:165]
	ds_read_b128 v[194:197], v193 offset:32768
	ds_read_b128 v[198:201], v193 offset:33792
	ds_read_b128 v[202:205], v193 offset:34816
	ds_read_b128 v[206:209], v193 offset:35840
	ds_read_b128 v[210:213], v193 offset:36864
	ds_read_b128 v[214:217], v193 offset:37888
	ds_read_b128 v[218:221], v193 offset:38912
	ds_read_b128 v[222:225], v193 offset:39936
	global_load_lds_dwordx4 v[226:227], off
	v_lshl_add_u64 v[226:227], s[48:49], 0, v[168:169]
	s_mov_b32 m0, s69
	s_nop 0
	global_load_lds_dwordx4 v[226:227], off
	s_waitcnt vmcnt(8)
	s_waitcnt lgkmcnt(0)
	s_setprio 1
	s_barrier
	v_mfma_f32_16x16x128_f8f6f4 v[158:161], v[18:25], v[194:201], v[158:161]
	v_mfma_f32_16x16x128_f8f6f4 v[154:157], v[26:33], v[194:201], v[154:157]
	v_mfma_f32_16x16x128_f8f6f4 v[146:149], v[26:33], v[202:209], v[146:149]
	v_mfma_f32_16x16x128_f8f6f4 v[150:153], v[18:25], v[202:209], v[150:153]
	v_mfma_f32_16x16x128_f8f6f4 v[142:145], v[18:25], v[210:217], v[142:145]
	v_mfma_f32_16x16x128_f8f6f4 v[138:141], v[26:33], v[210:217], v[138:141]
	v_mfma_f32_16x16x128_f8f6f4 v[130:133], v[26:33], v[218:225], v[130:133]
	v_mfma_f32_16x16x128_f8f6f4 v[134:137], v[18:25], v[218:225], v[134:137]
	s_setprio 0
	s_setprio 1
	v_mfma_f32_16x16x128_f8f6f4 v[102:105], v[2:9], v[218:225], v[102:105]
	v_mfma_f32_16x16x128_f8f6f4 v[98:101], v[184:191], v[218:225], v[98:101]
	v_mfma_f32_16x16x128_f8f6f4 v[106:109], v[184:191], v[210:217], v[106:109]
	v_mfma_f32_16x16x128_f8f6f4 v[110:113], v[2:9], v[210:217], v[110:113]
	v_mfma_f32_16x16x128_f8f6f4 v[118:121], v[2:9], v[202:209], v[118:121]
	v_mfma_f32_16x16x128_f8f6f4 v[114:117], v[184:191], v[202:209], v[114:117]
	v_mfma_f32_16x16x128_f8f6f4 v[122:125], v[184:191], v[194:201], v[122:125]
	v_mfma_f32_16x16x128_f8f6f4 v[126:129], v[2:9], v[194:201], v[126:129]
	s_setprio 0
	s_barrier
	s_mov_b32 m0, s74
	v_lshl_add_u64 v[10:11], v[10:11], 0, s[4:5]
	s_add_u32 s44, s44, 0x80080
	ds_read_b128 v[194:197], v193 offset:49152
	ds_read_b128 v[198:201], v193 offset:50176
	ds_read_b128 v[202:205], v193 offset:51200
	ds_read_b128 v[206:209], v193 offset:52224
	ds_read_b128 v[210:213], v193 offset:53248
	ds_read_b128 v[214:217], v193 offset:54272
	ds_read_b128 v[218:221], v193 offset:55296
	ds_read_b128 v[222:225], v193 offset:56320
	global_load_lds_dwordx4 v[10:11], off
	v_lshl_add_u64 v[10:11], v[12:13], 0, s[4:5]
	s_mov_b32 m0, s75
	s_addc_u32 s45, s45, 0
	global_load_lds_dwordx4 v[10:11], off
	v_lshl_add_u64 v[10:11], s[44:45], 0, v[166:167]
	s_mov_b32 m0, s78
	s_nop 0
	global_load_lds_dwordx4 v[10:11], off
	v_lshl_add_u64 v[10:11], s[44:45], 0, v[170:171]
	s_mov_b32 m0, s79
	s_nop 0
	global_load_lds_dwordx4 v[10:11], off
	v_lshl_add_u64 v[10:11], v[14:15], 0, s[4:5]
	s_mov_b32 m0, s76
	s_nop 0
	global_load_lds_dwordx4 v[10:11], off
	v_lshl_add_u64 v[10:11], v[16:17], 0, s[4:5]
	s_mov_b32 m0, s77
	s_nop 0
	global_load_lds_dwordx4 v[10:11], off
	s_waitcnt vmcnt(8)
	s_waitcnt lgkmcnt(0)
	s_setprio 1
	s_barrier
	v_mfma_f32_16x16x128_f8f6f4 v[94:97], v[18:25], v[194:201], v[94:97]
	v_mfma_f32_16x16x128_f8f6f4 v[90:93], v[26:33], v[194:201], v[90:93]
	v_mfma_f32_16x16x128_f8f6f4 v[82:85], v[26:33], v[202:209], v[82:85]
	v_mfma_f32_16x16x128_f8f6f4 v[86:89], v[18:25], v[202:209], v[86:89]
	v_mfma_f32_16x16x128_f8f6f4 v[78:81], v[18:25], v[210:217], v[78:81]
	v_mfma_f32_16x16x128_f8f6f4 v[74:77], v[26:33], v[210:217], v[74:77]
	v_mfma_f32_16x16x128_f8f6f4 v[66:69], v[26:33], v[218:225], v[66:69]
	v_mfma_f32_16x16x128_f8f6f4 v[70:73], v[18:25], v[218:225], v[70:73]
	s_setprio 0
	s_setprio 1
	v_mfma_f32_16x16x128_f8f6f4 v[38:41], v[2:9], v[218:225], v[38:41]
	v_mfma_f32_16x16x128_f8f6f4 v[34:37], v[184:191], v[218:225], v[34:37]
	v_mfma_f32_16x16x128_f8f6f4 v[42:45], v[184:191], v[210:217], v[42:45]
	v_mfma_f32_16x16x128_f8f6f4 v[46:49], v[2:9], v[210:217], v[46:49]
	v_mfma_f32_16x16x128_f8f6f4 v[54:57], v[2:9], v[202:209], v[54:57]
	v_mfma_f32_16x16x128_f8f6f4 v[50:53], v[184:191], v[202:209], v[50:53]
	v_mfma_f32_16x16x128_f8f6f4 v[58:61], v[184:191], v[194:201], v[58:61]
	v_mfma_f32_16x16x128_f8f6f4 v[62:65], v[2:9], v[194:201], v[62:65]
	s_setprio 0
	s_barrier
	s_add_i32 s86, s86, 2
	s_add_u32 s46, s46, 0x100
	s_addc_u32 s47, s47, 0
	s_add_u32 s62, s62, 0x100
	s_addc_u32 s63, s63, 0
	s_cmp_gt_u32 s86, 29
	s_cbranch_scc0 .LBB0_947
	s_and_b64 vcc, exec, s[6:7]
	s_cbranch_vccz .LBB0_950
	s_barrier

.LBB0_1031:
	ds_read_b128 v[2:5], v189
	ds_read_b128 v[6:9], v189 offset:1024
	ds_read_b128 v[192:195], v189 offset:2048
	ds_read_b128 v[196:199], v189 offset:3072
	ds_read_b128 v[200:203], v189 offset:16384
	ds_read_b128 v[204:207], v189 offset:17408
	ds_read_b128 v[208:211], v189 offset:18432
	ds_read_b128 v[212:215], v189 offset:19456
	s_add_u32 s25, s36, 0x100
	s_addc_u32 s83, s37, 0
	s_and_b64 s[40:41], s[38:39], exec
	s_cselect_b32 s41, s1, s83
	s_cselect_b32 s40, s0, s25
	s_add_u32 s25, s26, 0x100
	s_addc_u32 s83, s27, 0
	s_and_b64 s[38:39], s[38:39], exec
	s_cselect_b32 s39, s5, s83
	s_cselect_b32 s38, s4, s25
	s_add_u32 s84, s36, 0x158080
	s_addc_u32 s85, s37, 0
	s_add_i32 s25, s23, 0xc000
	v_lshl_add_u64 v[174:175], s[84:85], 0, v[154:155]
	s_mov_b32 m0, s25
	s_add_i32 s83, s23, 0xe000
	ds_read_b128 v[216:219], v190
	ds_read_b128 v[220:223], v190 offset:1024
	ds_read_b128 v[224:227], v190 offset:2048
	ds_read_b128 v[228:231], v190 offset:3072
	ds_read_b128 v[232:235], v190 offset:4096
	ds_read_b128 v[236:239], v190 offset:5120
	ds_read_b128 v[240:243], v190 offset:6144
	ds_read_b128 v[244:247], v190 offset:7168
	global_load_lds_dwordx4 v[174:175], off
	v_lshl_add_u64 v[174:175], s[84:85], 0, v[158:159]
	s_mov_b32 m0, s83
	s_nop 0
	global_load_lds_dwordx4 v[174:175], off
	s_waitcnt vmcnt(8)
	s_waitcnt lgkmcnt(0)
	s_setprio 1
	s_barrier
	v_mfma_f32_16x16x128_f8f6f4 v[134:137], v[2:9], v[216:223], 0
	v_mfma_f32_16x16x128_f8f6f4 v[130:133], v[192:199], v[216:223], 0
	v_mfma_f32_16x16x128_f8f6f4 v[122:125], v[192:199], v[224:231], 0
	v_mfma_f32_16x16x128_f8f6f4 v[126:129], v[2:9], v[224:231], 0
	v_mfma_f32_16x16x128_f8f6f4 v[118:121], v[2:9], v[232:239], 0
	v_mfma_f32_16x16x128_f8f6f4 v[114:117], v[192:199], v[232:239], 0
	v_mfma_f32_16x16x128_f8f6f4 v[106:109], v[192:199], v[240:247], 0
	v_mfma_f32_16x16x128_f8f6f4 v[110:113], v[2:9], v[240:247], 0
	s_setprio 0
	s_setprio 1
	v_mfma_f32_16x16x128_f8f6f4 v[78:81], v[200:207], v[240:247], 0
	v_mfma_f32_16x16x128_f8f6f4 v[74:77], v[208:215], v[240:247], 0
	v_mfma_f32_16x16x128_f8f6f4 v[82:85], v[208:215], v[232:239], 0
	v_mfma_f32_16x16x128_f8f6f4 v[86:89], v[200:207], v[232:239], 0
	v_mfma_f32_16x16x128_f8f6f4 v[94:97], v[200:207], v[224:231], 0
	v_mfma_f32_16x16x128_f8f6f4 v[90:93], v[208:215], v[224:231], 0
	v_mfma_f32_16x16x128_f8f6f4 v[98:101], v[208:215], v[216:223], 0
	v_mfma_f32_16x16x128_f8f6f4 v[102:105], v[200:207], v[216:223], 0
	s_setprio 0
	s_barrier
	s_mov_b32 m0, s33
	v_lshl_add_u64 v[174:175], s[38:39], 0, v[156:157]
	s_add_u32 s84, s38, 0x158000
	ds_read_b128 v[216:219], v190 offset:16384
	ds_read_b128 v[220:223], v190 offset:17408
	ds_read_b128 v[224:227], v190 offset:18432
	ds_read_b128 v[228:231], v190 offset:19456
	ds_read_b128 v[232:235], v190 offset:20480
	ds_read_b128 v[236:239], v190 offset:21504
	ds_read_b128 v[240:243], v190 offset:22528
	ds_read_b128 v[244:247], v190 offset:23552
	global_load_lds_dwordx4 v[174:175], off
	v_lshl_add_u64 v[176:177], s[38:39], 0, v[160:161]
	s_mov_b32 m0, s35
	s_addc_u32 s85, s39, 0
	global_load_lds_dwordx4 v[176:177], off
	v_lshl_add_u64 v[182:183], s[84:85], 0, v[156:157]
	s_mov_b32 m0, s42
	v_lshl_add_u64 v[184:185], s[40:41], 0, v[158:159]
	global_load_lds_dwordx4 v[182:183], off
	v_lshl_add_u64 v[182:183], s[84:85], 0, v[160:161]
	s_mov_b32 m0, s43
	s_nop 0
	global_load_lds_dwordx4 v[182:183], off
	v_lshl_add_u64 v[182:183], s[40:41], 0, v[154:155]
	s_mov_b32 m0, s23
	s_nop 0
	global_load_lds_dwordx4 v[182:183], off
	s_mov_b32 m0, s44
	s_nop 0
	global_load_lds_dwordx4 v[184:185], off
	s_waitcnt vmcnt(8)
	s_waitcnt lgkmcnt(0)
	s_setprio 1
	s_barrier
	v_mfma_f32_16x16x128_f8f6f4 v[70:73], v[2:9], v[216:223], 0
	v_mfma_f32_16x16x128_f8f6f4 v[66:69], v[192:199], v[216:223], 0
	v_mfma_f32_16x16x128_f8f6f4 v[58:61], v[192:199], v[224:231], 0
	v_mfma_f32_16x16x128_f8f6f4 v[62:65], v[2:9], v[224:231], 0
	v_mfma_f32_16x16x128_f8f6f4 v[54:57], v[2:9], v[232:239], 0
	v_mfma_f32_16x16x128_f8f6f4 v[50:53], v[192:199], v[232:239], 0
	v_mfma_f32_16x16x128_f8f6f4 v[42:45], v[192:199], v[240:247], 0
	v_mfma_f32_16x16x128_f8f6f4 v[46:49], v[2:9], v[240:247], 0
	s_setprio 0
	s_setprio 1
	v_mfma_f32_16x16x128_f8f6f4 v[14:17], v[200:207], v[240:247], 0
	v_mfma_f32_16x16x128_f8f6f4 v[10:13], v[208:215], v[240:247], 0
	v_mfma_f32_16x16x128_f8f6f4 v[18:21], v[208:215], v[232:239], 0
	v_mfma_f32_16x16x128_f8f6f4 v[22:25], v[200:207], v[232:239], 0
	v_mfma_f32_16x16x128_f8f6f4 v[30:33], v[200:207], v[224:231], 0
	v_mfma_f32_16x16x128_f8f6f4 v[26:29], v[208:215], v[224:231], 0
	v_mfma_f32_16x16x128_f8f6f4 v[34:37], v[208:215], v[216:223], 0
	v_mfma_f32_16x16x128_f8f6f4 v[38:41], v[200:207], v[216:223], 0
	s_setprio 0
	s_barrier
	ds_read_b128 v[2:5], v189 offset:32768
	ds_read_b128 v[6:9], v189 offset:33792
	ds_read_b128 v[192:195], v189 offset:34816
	ds_read_b128 v[196:199], v189 offset:35840
	ds_read_b128 v[200:203], v189 offset:49152
	ds_read_b128 v[204:207], v189 offset:50176
	ds_read_b128 v[208:211], v189 offset:51200
	ds_read_b128 v[212:215], v189 offset:52224
	s_add_u32 s40, s40, 0x158000
	s_addc_u32 s41, s41, 0
	s_mov_b32 m0, s45
	v_lshl_add_u64 v[186:187], s[40:41], 0, v[154:155]
	ds_read_b128 v[216:219], v190 offset:32768
	ds_read_b128 v[220:223], v190 offset:33792
	ds_read_b128 v[224:227], v190 offset:34816
	ds_read_b128 v[228:231], v190 offset:35840
	ds_read_b128 v[232:235], v190 offset:36864
	ds_read_b128 v[236:239], v190 offset:37888
	ds_read_b128 v[240:243], v190 offset:38912
	ds_read_b128 v[244:247], v190 offset:39936
	global_load_lds_dwordx4 v[186:187], off
	v_lshl_add_u64 v[186:187], s[40:41], 0, v[158:159]
	s_mov_b32 m0, s46
	s_nop 0
	global_load_lds_dwordx4 v[186:187], off
	s_waitcnt vmcnt(8)
	s_waitcnt lgkmcnt(0)
	s_setprio 1
	s_barrier
	v_mfma_f32_16x16x128_f8f6f4 v[134:137], v[2:9], v[216:223], v[134:137]
	v_mfma_f32_16x16x128_f8f6f4 v[130:133], v[192:199], v[216:223], v[130:133]
	v_mfma_f32_16x16x128_f8f6f4 v[122:125], v[192:199], v[224:231], v[122:125]
	v_mfma_f32_16x16x128_f8f6f4 v[126:129], v[2:9], v[224:231], v[126:129]
	v_mfma_f32_16x16x128_f8f6f4 v[118:121], v[2:9], v[232:239], v[118:121]
	v_mfma_f32_16x16x128_f8f6f4 v[114:117], v[192:199], v[232:239], v[114:117]
	v_mfma_f32_16x16x128_f8f6f4 v[106:109], v[192:199], v[240:247], v[106:109]
	v_mfma_f32_16x16x128_f8f6f4 v[110:113], v[2:9], v[240:247], v[110:113]
	s_setprio 0
	s_setprio 1
	v_mfma_f32_16x16x128_f8f6f4 v[78:81], v[200:207], v[240:247], v[78:81]
	v_mfma_f32_16x16x128_f8f6f4 v[74:77], v[208:215], v[240:247], v[74:77]
	v_mfma_f32_16x16x128_f8f6f4 v[82:85], v[208:215], v[232:239], v[82:85]
	v_mfma_f32_16x16x128_f8f6f4 v[86:89], v[200:207], v[232:239], v[86:89]
	v_mfma_f32_16x16x128_f8f6f4 v[94:97], v[200:207], v[224:231], v[94:97]
	v_mfma_f32_16x16x128_f8f6f4 v[90:93], v[208:215], v[224:231], v[90:93]
	v_mfma_f32_16x16x128_f8f6f4 v[98:101], v[208:215], v[216:223], v[98:101]
	v_mfma_f32_16x16x128_f8f6f4 v[102:105], v[200:207], v[216:223], v[102:105]
	s_setprio 0
	s_barrier
	s_mov_b32 m0, s52
	v_lshl_add_u64 v[174:175], v[174:175], 0, s[14:15]
	s_add_u32 s38, s38, 0x158080
	ds_read_b128 v[216:219], v190 offset:49152
	ds_read_b128 v[220:223], v190 offset:50176
	ds_read_b128 v[224:227], v190 offset:51200
	ds_read_b128 v[228:231], v190 offset:52224
	ds_read_b128 v[232:235], v190 offset:53248
	ds_read_b128 v[236:239], v190 offset:54272
	ds_read_b128 v[240:243], v190 offset:55296
	ds_read_b128 v[244:247], v190 offset:56320
	global_load_lds_dwordx4 v[174:175], off
	v_lshl_add_u64 v[174:175], v[176:177], 0, s[14:15]
	s_mov_b32 m0, s53
	s_addc_u32 s39, s39, 0
	global_load_lds_dwordx4 v[174:175], off
	v_lshl_add_u64 v[174:175], s[38:39], 0, v[156:157]
	s_mov_b32 m0, s56
	s_nop 0
	global_load_lds_dwordx4 v[174:175], off
	v_lshl_add_u64 v[174:175], s[38:39], 0, v[160:161]
	s_mov_b32 m0, s57
	s_nop 0
	global_load_lds_dwordx4 v[174:175], off
	v_lshl_add_u64 v[174:175], v[182:183], 0, s[14:15]
	s_mov_b32 m0, s54
	s_nop 0
	global_load_lds_dwordx4 v[174:175], off
	v_lshl_add_u64 v[174:175], v[184:185], 0, s[14:15]
	s_mov_b32 m0, s55
	s_nop 0
	global_load_lds_dwordx4 v[174:175], off
	s_waitcnt vmcnt(8)
	s_waitcnt lgkmcnt(0)
	s_setprio 1
	s_barrier
	v_mfma_f32_16x16x128_f8f6f4 v[70:73], v[2:9], v[216:223], v[70:73]
	v_mfma_f32_16x16x128_f8f6f4 v[66:69], v[192:199], v[216:223], v[66:69]
	v_mfma_f32_16x16x128_f8f6f4 v[58:61], v[192:199], v[224:231], v[58:61]
	v_mfma_f32_16x16x128_f8f6f4 v[62:65], v[2:9], v[224:231], v[62:65]
	v_mfma_f32_16x16x128_f8f6f4 v[54:57], v[2:9], v[232:239], v[54:57]
	v_mfma_f32_16x16x128_f8f6f4 v[50:53], v[192:199], v[232:239], v[50:53]
	v_mfma_f32_16x16x128_f8f6f4 v[42:45], v[192:199], v[240:247], v[42:45]
	v_mfma_f32_16x16x128_f8f6f4 v[46:49], v[2:9], v[240:247], v[46:49]
	s_setprio 0
	s_setprio 1
	v_mfma_f32_16x16x128_f8f6f4 v[14:17], v[200:207], v[240:247], v[14:17]
	v_mfma_f32_16x16x128_f8f6f4 v[10:13], v[208:215], v[240:247], v[10:13]
	v_mfma_f32_16x16x128_f8f6f4 v[18:21], v[208:215], v[232:239], v[18:21]
	v_mfma_f32_16x16x128_f8f6f4 v[22:25], v[200:207], v[232:239], v[22:25]
	v_mfma_f32_16x16x128_f8f6f4 v[30:33], v[200:207], v[224:231], v[30:33]
	v_mfma_f32_16x16x128_f8f6f4 v[26:29], v[208:215], v[224:231], v[26:29]
	v_mfma_f32_16x16x128_f8f6f4 v[34:37], v[208:215], v[216:223], v[34:37]
	v_mfma_f32_16x16x128_f8f6f4 v[38:41], v[200:207], v[216:223], v[38:41]
	s_setprio 0
	s_barrier
	s_cmp_lt_u32 s82, 3
	s_cbranch_scc1 .LBB0_1036
	s_add_u32 s38, s48, s63
	s_addc_u32 s39, s49, s62
	s_add_u32 s36, s36, 0x158180
	s_addc_u32 s37, s37, 0
	s_add_u32 s40, s26, 0x200
	v_lshl_add_u64 v[174:175], v[172:173], 2, s[38:39]
	s_addc_u32 s41, s27, 0
	s_mov_b32 s84, 4
	s_cmp_eq_u32 s82, s84
	s_cselect_b64 s[26:27], -1, 0
	s_cmp_lg_u32 s82, s84
	s_cbranch_scc1 .LBB0_1034

.LBB0_1034:
	ds_read_b128 v[2:5], v189
	ds_read_b128 v[6:9], v189 offset:1024
	ds_read_b128 v[192:195], v189 offset:2048
	ds_read_b128 v[196:199], v189 offset:3072
	ds_read_b128 v[200:203], v189 offset:16384
	ds_read_b128 v[204:207], v189 offset:17408
	ds_read_b128 v[208:211], v189 offset:18432
	ds_read_b128 v[212:215], v189 offset:19456
	s_add_u32 s38, s36, 0xffea8080
	s_addc_u32 s39, s37, -1
	s_and_b64 s[26:27], s[26:27], exec
	s_cselect_b32 s26, s4, s40
	s_cselect_b32 s39, s1, s39
	s_cselect_b32 s38, s0, s38
	s_cselect_b32 s27, s5, s41
	s_mov_b32 m0, s25
	v_lshl_add_u64 v[176:177], s[36:37], 0, v[162:163]
	ds_read_b128 v[216:219], v190
	ds_read_b128 v[220:223], v190 offset:1024
	ds_read_b128 v[224:227], v190 offset:2048
	ds_read_b128 v[228:231], v190 offset:3072
	ds_read_b128 v[232:235], v190 offset:4096
	ds_read_b128 v[236:239], v190 offset:5120
	ds_read_b128 v[240:243], v190 offset:6144
	ds_read_b128 v[244:247], v190 offset:7168
	global_load_lds_dwordx4 v[176:177], off
	v_lshl_add_u64 v[176:177], s[36:37], 0, v[164:165]
	s_mov_b32 m0, s83
	s_nop 0
	global_load_lds_dwordx4 v[176:177], off
	s_waitcnt vmcnt(8)
	s_waitcnt lgkmcnt(0)
	s_setprio 1
	s_barrier
	v_mfma_f32_16x16x128_f8f6f4 v[134:137], v[2:9], v[216:223], v[134:137]
	v_mfma_f32_16x16x128_f8f6f4 v[130:133], v[192:199], v[216:223], v[130:133]
	v_mfma_f32_16x16x128_f8f6f4 v[122:125], v[192:199], v[224:231], v[122:125]
	v_mfma_f32_16x16x128_f8f6f4 v[126:129], v[2:9], v[224:231], v[126:129]
	v_mfma_f32_16x16x128_f8f6f4 v[118:121], v[2:9], v[232:239], v[118:121]
	v_mfma_f32_16x16x128_f8f6f4 v[114:117], v[192:199], v[232:239], v[114:117]
	v_mfma_f32_16x16x128_f8f6f4 v[106:109], v[192:199], v[240:247], v[106:109]
	v_mfma_f32_16x16x128_f8f6f4 v[110:113], v[2:9], v[240:247], v[110:113]
	s_setprio 0
	s_setprio 1
	v_mfma_f32_16x16x128_f8f6f4 v[78:81], v[200:207], v[240:247], v[78:81]
	v_mfma_f32_16x16x128_f8f6f4 v[74:77], v[208:215], v[240:247], v[74:77]
	v_mfma_f32_16x16x128_f8f6f4 v[82:85], v[208:215], v[232:239], v[82:85]
	v_mfma_f32_16x16x128_f8f6f4 v[86:89], v[200:207], v[232:239], v[86:89]
	v_mfma_f32_16x16x128_f8f6f4 v[94:97], v[200:207], v[224:231], v[94:97]
	v_mfma_f32_16x16x128_f8f6f4 v[90:93], v[208:215], v[224:231], v[90:93]
	v_mfma_f32_16x16x128_f8f6f4 v[98:101], v[208:215], v[216:223], v[98:101]
	v_mfma_f32_16x16x128_f8f6f4 v[102:105], v[200:207], v[216:223], v[102:105]
	s_setprio 0
	s_barrier
	s_mov_b32 m0, s33
	v_lshl_add_u64 v[176:177], s[26:27], 0, v[156:157]
	s_add_u32 s62, s26, 0x158000
	ds_read_b128 v[216:219], v190 offset:16384
	ds_read_b128 v[220:223], v190 offset:17408
	ds_read_b128 v[224:227], v190 offset:18432
	ds_read_b128 v[228:231], v190 offset:19456
	ds_read_b128 v[232:235], v190 offset:20480
	ds_read_b128 v[236:239], v190 offset:21504
	ds_read_b128 v[240:243], v190 offset:22528
	ds_read_b128 v[244:247], v190 offset:23552
	global_load_lds_dwordx4 v[176:177], off
	v_lshl_add_u64 v[182:183], s[26:27], 0, v[160:161]
	s_mov_b32 m0, s35
	s_addc_u32 s63, s27, 0
	global_load_lds_dwordx4 v[182:183], off
	v_lshl_add_u64 v[184:185], s[62:63], 0, v[156:157]
	s_mov_b32 m0, s42
	v_lshl_add_u64 v[186:187], s[38:39], 0, v[158:159]
	global_load_lds_dwordx4 v[184:185], off
	v_lshl_add_u64 v[184:185], s[62:63], 0, v[160:161]
	s_mov_b32 m0, s43
	s_nop 0
	global_load_lds_dwordx4 v[184:185], off
	v_lshl_add_u64 v[184:185], s[38:39], 0, v[154:155]
	s_mov_b32 m0, s23
	s_nop 0
	global_load_lds_dwordx4 v[184:185], off
	s_mov_b32 m0, s44
	s_nop 0
	global_load_lds_dwordx4 v[186:187], off
	s_waitcnt vmcnt(8)
	s_waitcnt lgkmcnt(0)
	s_setprio 1
	s_barrier
	v_mfma_f32_16x16x128_f8f6f4 v[70:73], v[2:9], v[216:223], v[70:73]
	v_mfma_f32_16x16x128_f8f6f4 v[66:69], v[192:199], v[216:223], v[66:69]
	v_mfma_f32_16x16x128_f8f6f4 v[58:61], v[192:199], v[224:231], v[58:61]
	v_mfma_f32_16x16x128_f8f6f4 v[62:65], v[2:9], v[224:231], v[62:65]
	v_mfma_f32_16x16x128_f8f6f4 v[54:57], v[2:9], v[232:239], v[54:57]
	v_mfma_f32_16x16x128_f8f6f4 v[50:53], v[192:199], v[232:239], v[50:53]
	v_mfma_f32_16x16x128_f8f6f4 v[42:45], v[192:199], v[240:247], v[42:45]
	v_mfma_f32_16x16x128_f8f6f4 v[46:49], v[2:9], v[240:247], v[46:49]
	s_setprio 0
	s_setprio 1
	v_mfma_f32_16x16x128_f8f6f4 v[14:17], v[200:207], v[240:247], v[14:17]
	v_mfma_f32_16x16x128_f8f6f4 v[10:13], v[208:215], v[240:247], v[10:13]
	v_mfma_f32_16x16x128_f8f6f4 v[18:21], v[208:215], v[232:239], v[18:21]
	v_mfma_f32_16x16x128_f8f6f4 v[22:25], v[200:207], v[232:239], v[22:25]
	v_mfma_f32_16x16x128_f8f6f4 v[30:33], v[200:207], v[224:231], v[30:33]
	v_mfma_f32_16x16x128_f8f6f4 v[26:29], v[208:215], v[224:231], v[26:29]
	v_mfma_f32_16x16x128_f8f6f4 v[34:37], v[208:215], v[216:223], v[34:37]
	v_mfma_f32_16x16x128_f8f6f4 v[38:41], v[200:207], v[216:223], v[38:41]
	s_setprio 0
	s_barrier
	ds_read_b128 v[192:195], v189 offset:32768
	ds_read_b128 v[196:199], v189 offset:33792
	ds_read_b128 v[200:203], v189 offset:34816
	ds_read_b128 v[204:207], v189 offset:35840
	ds_read_b128 v[2:5], v189 offset:49152
	ds_read_b128 v[6:9], v189 offset:50176
	ds_read_b128 v[208:211], v189 offset:51200
	ds_read_b128 v[212:215], v189 offset:52224
	s_add_u32 s38, s38, 0x158000
	s_addc_u32 s39, s39, 0
	s_mov_b32 m0, s45
	v_lshl_add_u64 v[248:249], s[38:39], 0, v[154:155]
	ds_read_b128 v[216:219], v190 offset:32768
	ds_read_b128 v[220:223], v190 offset:33792
	ds_read_b128 v[224:227], v190 offset:34816
	ds_read_b128 v[228:231], v190 offset:35840
	ds_read_b128 v[232:235], v190 offset:36864
	ds_read_b128 v[236:239], v190 offset:37888
	ds_read_b128 v[240:243], v190 offset:38912
	ds_read_b128 v[244:247], v190 offset:39936
	global_load_lds_dwordx4 v[248:249], off
	v_lshl_add_u64 v[248:249], s[38:39], 0, v[158:159]
	s_mov_b32 m0, s46
	s_nop 0
	global_load_lds_dwordx4 v[248:249], off
	s_waitcnt vmcnt(8)
	s_waitcnt lgkmcnt(0)
	s_setprio 1
	s_barrier
	v_mfma_f32_16x16x128_f8f6f4 v[134:137], v[192:199], v[216:223], v[134:137]
	v_mfma_f32_16x16x128_f8f6f4 v[130:133], v[200:207], v[216:223], v[130:133]
	v_mfma_f32_16x16x128_f8f6f4 v[122:125], v[200:207], v[224:231], v[122:125]
	v_mfma_f32_16x16x128_f8f6f4 v[126:129], v[192:199], v[224:231], v[126:129]
	v_mfma_f32_16x16x128_f8f6f4 v[118:121], v[192:199], v[232:239], v[118:121]
	v_mfma_f32_16x16x128_f8f6f4 v[114:117], v[200:207], v[232:239], v[114:117]
	v_mfma_f32_16x16x128_f8f6f4 v[106:109], v[200:207], v[240:247], v[106:109]
	v_mfma_f32_16x16x128_f8f6f4 v[110:113], v[192:199], v[240:247], v[110:113]
	s_setprio 0
	s_setprio 1
	v_mfma_f32_16x16x128_f8f6f4 v[78:81], v[2:9], v[240:247], v[78:81]
	v_mfma_f32_16x16x128_f8f6f4 v[74:77], v[208:215], v[240:247], v[74:77]
	v_mfma_f32_16x16x128_f8f6f4 v[82:85], v[208:215], v[232:239], v[82:85]
	v_mfma_f32_16x16x128_f8f6f4 v[86:89], v[2:9], v[232:239], v[86:89]
	v_mfma_f32_16x16x128_f8f6f4 v[94:97], v[2:9], v[224:231], v[94:97]
	v_mfma_f32_16x16x128_f8f6f4 v[90:93], v[208:215], v[224:231], v[90:93]
	v_mfma_f32_16x16x128_f8f6f4 v[98:101], v[208:215], v[216:223], v[98:101]
	v_mfma_f32_16x16x128_f8f6f4 v[102:105], v[2:9], v[216:223], v[102:105]
	s_setprio 0
	s_barrier
	s_mov_b32 m0, s52
	v_lshl_add_u64 v[176:177], v[176:177], 0, s[14:15]
	s_add_u32 s26, s26, 0x158080
	ds_read_b128 v[216:219], v190 offset:49152
	ds_read_b128 v[220:223], v190 offset:50176
	ds_read_b128 v[224:227], v190 offset:51200
	ds_read_b128 v[228:231], v190 offset:52224
	ds_read_b128 v[232:235], v190 offset:53248
	ds_read_b128 v[236:239], v190 offset:54272
	ds_read_b128 v[240:243], v190 offset:55296
	ds_read_b128 v[244:247], v190 offset:56320
	global_load_lds_dwordx4 v[176:177], off
	v_lshl_add_u64 v[176:177], v[182:183], 0, s[14:15]
	s_mov_b32 m0, s53
	s_addc_u32 s27, s27, 0
	global_load_lds_dwordx4 v[176:177], off
	v_lshl_add_u64 v[176:177], s[26:27], 0, v[156:157]
	s_mov_b32 m0, s56
	s_nop 0
	global_load_lds_dwordx4 v[176:177], off
	v_lshl_add_u64 v[176:177], s[26:27], 0, v[160:161]
	s_mov_b32 m0, s57
	s_nop 0
	global_load_lds_dwordx4 v[176:177], off
	v_lshl_add_u64 v[176:177], v[184:185], 0, s[14:15]
	s_mov_b32 m0, s54
	s_nop 0
	global_load_lds_dwordx4 v[176:177], off
	v_lshl_add_u64 v[176:177], v[186:187], 0, s[14:15]
	s_mov_b32 m0, s55
	s_nop 0
	global_load_lds_dwordx4 v[176:177], off
	s_waitcnt vmcnt(8)
	s_waitcnt lgkmcnt(0)
	s_setprio 1
	s_barrier
	v_mfma_f32_16x16x128_f8f6f4 v[70:73], v[192:199], v[216:223], v[70:73]
	v_mfma_f32_16x16x128_f8f6f4 v[66:69], v[200:207], v[216:223], v[66:69]
	v_mfma_f32_16x16x128_f8f6f4 v[58:61], v[200:207], v[224:231], v[58:61]
	v_mfma_f32_16x16x128_f8f6f4 v[62:65], v[192:199], v[224:231], v[62:65]
	v_mfma_f32_16x16x128_f8f6f4 v[54:57], v[192:199], v[232:239], v[54:57]
	v_mfma_f32_16x16x128_f8f6f4 v[50:53], v[200:207], v[232:239], v[50:53]
	v_mfma_f32_16x16x128_f8f6f4 v[42:45], v[200:207], v[240:247], v[42:45]
	v_mfma_f32_16x16x128_f8f6f4 v[46:49], v[192:199], v[240:247], v[46:49]
	s_setprio 0
	s_setprio 1
	v_mfma_f32_16x16x128_f8f6f4 v[14:17], v[2:9], v[240:247], v[14:17]
	v_mfma_f32_16x16x128_f8f6f4 v[10:13], v[208:215], v[240:247], v[10:13]
	v_mfma_f32_16x16x128_f8f6f4 v[18:21], v[208:215], v[232:239], v[18:21]
	v_mfma_f32_16x16x128_f8f6f4 v[22:25], v[2:9], v[232:239], v[22:25]
	v_mfma_f32_16x16x128_f8f6f4 v[30:33], v[2:9], v[224:231], v[30:33]
	v_mfma_f32_16x16x128_f8f6f4 v[26:29], v[208:215], v[224:231], v[26:29]
	v_mfma_f32_16x16x128_f8f6f4 v[34:37], v[208:215], v[216:223], v[34:37]
	v_mfma_f32_16x16x128_f8f6f4 v[38:41], v[2:9], v[216:223], v[38:41]
	s_setprio 0
	s_barrier
	s_add_i32 s26, s84, 2
	s_add_u32 s36, s36, 0x100
	s_addc_u32 s37, s37, 0
	s_add_u32 s40, s40, 0x100
	s_addc_u32 s41, s41, 0
	s_cmp_ge_i32 s84, s82
	s_cbranch_scc1 .LBB0_1036
	s_mov_b32 s84, s26
	s_cmp_eq_u32 s82, s84
	s_cselect_b64 s[26:27], -1, 0
	s_cmp_lg_u32 s82, s84
	s_cbranch_scc0 .LBB0_1033
	s_branch .LBB0_1034
